# nt on further read-once streams: x rows in P0, final-phase rows and output stores, split-K partial loads, residual-epilogue base loads, passC staging loads
# baseline (speedup 1.0000x reference)
; __device__ __forceinline__ unsigned cvt_pk_bf16(float lo, float hi) { unsigned r; asm volatile("v_cvt_pk_bf16_f32 %0, %1, %2" : "=v"(r) : "v"(lo), "v"(hi)); return r; }
; __device__ __forceinline__ void row_bf16_ss(const float* xrow, bf16_t* orow, float* ss, int lane) {
;     const f32x4* xr = (const f32x4*)xrow + lane; f32x4 v[8]; float s = 0.f;
; #pragma unroll
;     for (int j = 0; j < 8; ++j) { v[j] = xr[64 * j]; s += (v[j].x * v[j].x + v[j].y * v[j].y) + (v[j].z * v[j].z + v[j].w * v[j].w); }
;     s = wave_sum(s); u32x2* o8 = (u32x2*)orow + lane;
; #pragma unroll
;     for (int j = 0; j < 8; ++j) { u32x2 w; w.x = cvt_pk_bf16(v[j].x, v[j].y); w.y = cvt_pk_bf16(v[j].z, v[j].w); o8[64 * j] = w; }
;     if (lane == 0) *ss = s;
; }
.LBB0_160:
	s_waitcnt lgkmcnt(0)
	global_load_dwordx4 v[16:19], v0, s[18:19] nt
	global_load_dwordx4 v[20:23], v0, s[18:19] offset:1024 nt
	global_load_dwordx4 v[24:27], v0, s[18:19] offset:2048 nt
	global_load_dwordx4 v[28:31], v0, s[18:19] offset:3072 nt
	v_lshl_add_u64 v[34:35], s[18:19], 0, v[0:1]
	v_add_co_u32_e32 v50, vcc, s24, v34
	s_lshl_b64 s[18:19], s[16:17], 12
	s_nop 0
	v_addc_co_u32_e32 v51, vcc, 0, v35, vcc
	global_load_dwordx4 v[34:37], v[50:51], off nt
	global_load_dwordx4 v[38:41], v[50:51], off offset:1024 nt
	global_load_dwordx4 v[42:45], v[50:51], off offset:2048 nt
	global_load_dwordx4 v[46:49], v[50:51], off offset:3072 nt
	v_cmp_lt_i32_e32 vcc, v9, v8
	s_waitcnt vmcnt(6)
	v_mul_f32_e32 v56, v21, v21
	v_cndmask_b32_e32 v15, v7, v9, vcc
	v_cmp_lt_i32_e32 vcc, v10, v8
	v_mul_f32_e32 v57, v23, v23
	s_waitcnt vmcnt(5)
	v_mul_f32_e32 v58, v25, v25
	v_cndmask_b32_e32 v32, v7, v10, vcc
	v_cmp_lt_i32_e32 vcc, v11, v8
	v_mul_f32_e32 v59, v27, v27
	v_fmac_f32_e32 v56, v20, v20
	v_cndmask_b32_e32 v50, v7, v11, vcc
	v_cmp_lt_i32_e32 vcc, v12, v8
	v_lshlrev_b32_e32 v54, 2, v50
	v_mul_f32_e32 v50, v17, v17
	v_cndmask_b32_e32 v51, v7, v12, vcc
	v_lshlrev_b32_e32 v55, 2, v51
	v_mul_f32_e32 v51, v19, v19
	v_fmac_f32_e32 v50, v16, v16
	v_fmac_f32_e32 v51, v18, v18
	v_fmac_f32_e32 v57, v22, v22
	s_waitcnt vmcnt(4)
	v_mul_f32_e32 v60, v29, v29
	v_mul_f32_e32 v61, v31, v31
	v_fmac_f32_e32 v58, v24, v24
	v_fmac_f32_e32 v59, v26, v26
	v_add_f32_e32 v50, v50, v51
	v_add_f32_e32 v51, v56, v57
	v_fmac_f32_e32 v60, v28, v28
	v_fmac_f32_e32 v61, v30, v30
	v_add_f32_e32 v56, v58, v59
	s_waitcnt vmcnt(3)
	v_mul_f32_e32 v58, v35, v35
	v_mul_f32_e32 v59, v37, v37
	v_add_f32_e32 v50, v50, v51
	v_add_f32_e32 v57, v60, v61
	s_waitcnt vmcnt(2)
	v_mul_f32_e32 v60, v39, v39
	v_mul_f32_e32 v61, v41, v41
	v_fmac_f32_e32 v58, v34, v34
	v_fmac_f32_e32 v59, v36, v36
	v_add_f32_e32 v50, v50, v56
	s_waitcnt vmcnt(1)
	v_mul_f32_e32 v62, v43, v43
	v_mul_f32_e32 v63, v45, v45
	v_fmac_f32_e32 v60, v38, v38
	v_fmac_f32_e32 v61, v40, v40
	v_add_f32_e32 v51, v58, v59
	v_add_f32_e32 v50, v50, v57
	s_waitcnt vmcnt(0)
	v_mul_f32_e32 v64, v47, v47
	v_mul_f32_e32 v65, v49, v49
	v_fmac_f32_e32 v62, v42, v42
	v_fmac_f32_e32 v63, v44, v44
	v_add_f32_e32 v56, v60, v61
	v_add_f32_e32 v50, v50, v51
	v_fmac_f32_e32 v64, v46, v46
	v_fmac_f32_e32 v65, v48, v48
	v_add_f32_e32 v58, v62, v63
	v_add_f32_e32 v50, v50, v56
	v_add_f32_e32 v59, v64, v65
	v_add_f32_e32 v50, v50, v58
	v_lshlrev_b32_e32 v15, 2, v15
	v_add_f32_e32 v56, v50, v59
	ds_bpermute_b32 v15, v15, v56
	v_lshlrev_b32_e32 v32, 2, v32
	v_cvt_pk_bf16_f32 v16, v16, v17
	v_cvt_pk_bf16_f32 v17, v18, v19
	v_cmp_lt_i32_e32 vcc, v13, v8
	s_waitcnt lgkmcnt(0)
	v_add_f32_e32 v15, v56, v15
	ds_bpermute_b32 v18, v32, v15
	v_cndmask_b32_e32 v52, v7, v13, vcc
	v_lshlrev_b32_e32 v52, 2, v52
	v_lshl_add_u64 v[50:51], v[4:5], 0, s[18:19]
	global_store_dwordx2 v[50:51], v[16:17], off
	s_waitcnt lgkmcnt(0)
	v_add_f32_e32 v15, v15, v18
	ds_bpermute_b32 v18, v54, v15
	v_cvt_pk_bf16_f32 v16, v20, v21
	v_cvt_pk_bf16_f32 v17, v22, v23
	global_store_dwordx2 v[50:51], v[16:17], off offset:512
	v_cvt_pk_bf16_f32 v16, v24, v25
	s_waitcnt lgkmcnt(0)
	v_add_f32_e32 v15, v15, v18
	ds_bpermute_b32 v18, v55, v15
	v_cvt_pk_bf16_f32 v17, v26, v27
	global_store_dwordx2 v[50:51], v[16:17], off offset:1024
	v_cvt_pk_bf16_f32 v16, v28, v29
	v_cmp_lt_i32_e32 vcc, v14, v8
	s_waitcnt lgkmcnt(0)
	v_add_f32_e32 v15, v15, v18
	ds_bpermute_b32 v19, v52, v15
	v_cvt_pk_bf16_f32 v17, v30, v31
	global_store_dwordx2 v[50:51], v[16:17], off offset:1536
	v_cvt_pk_bf16_f32 v16, v34, v35
	v_cndmask_b32_e32 v53, v7, v14, vcc
	v_cvt_pk_bf16_f32 v17, v36, v37
	global_store_dwordx2 v[50:51], v[16:17], off offset:2048
	v_cvt_pk_bf16_f32 v16, v38, v39
	v_lshlrev_b32_e32 v53, 2, v53
	v_cvt_pk_bf16_f32 v17, v40, v41
	global_store_dwordx2 v[50:51], v[16:17], off offset:2560
	s_waitcnt lgkmcnt(0)
	v_add_f32_e32 v16, v15, v19
	ds_bpermute_b32 v17, v53, v16
	v_cvt_pk_bf16_f32 v18, v42, v43
	v_cvt_pk_bf16_f32 v19, v44, v45
	global_store_dwordx2 v[50:51], v[18:19], off offset:3072
	v_cvt_pk_bf16_f32 v18, v46, v47
	v_cvt_pk_bf16_f32 v19, v48, v49
	global_store_dwordx2 v[50:51], v[18:19], off offset:3584
	s_and_saveexec_b64 s[18:19], s[6:7]
	s_cbranch_execz .LBB0_162
	s_waitcnt lgkmcnt(0)
	v_add_f32_e32 v15, v16, v17
	s_or_b64 s[14:15], s[14:15], exec

; #define LAS __attribute__((address_space(3)))
; __device__ __forceinline__ void gla_passC(LAS unsigned char* lds, int uidx, const bf16_t* PR, const bf16_t* SUB, const bf16_t* QT, const bf16_t* AM, const float* gn  ,
;                                           bf16_t* Y, int tid, int wid, int lane) {
;     ...
;     u32x4 ogr[4];
;     { const bf16_t* gp0 = PR + (size_t)(tok0 + (tid >> 3)) * PRW + 3072 + h * DV + (tid & 7) * 32;
; #pragma unroll
;       for (int j = 0; j < 4; ++j) ogr[j] = *(const u32x4*)(gp0 + 8 * j); }
;     { const bf16_t* sp = SUB + ((size_t)bh * NCH + c) * (DK * DV);
; #pragma unroll
;       for (int i = 0; i < 8; ++i) { const int id = tid + 512 * i, k = id >> 5, cc = id & 31; *(LAS u32x4*)(Sn + k * 272 + cc * 8) = *(const u32x4*)(sp + k * DV + cc * 8); } }
; #pragma unroll
;     for (int i = 0; i < 2; ++i) { const int id = tid + 512 * i, row = id >> 4, cc = id & 15; *(LAS u32x4*)(Qs + row * 136 + cc * 8) = *(const u32x4*)(QT + (size_t)(tok0 + row) * QKD + h * DK + cc * 8); }
;     { const int row = tid >> 3, cc = tid & 7; *(LAS u32x4*)(As + row * 72 + cc * 8) = *(const u32x4*)(AM + (size_t)uidx * 4096 + row * 64 + cc * 8); }
;     stage_v(Vn, PR, tok0, h, tid);
;     __syncthreads();
.LBB0_487:
	s_ashr_i32 s10, s6, 7
	s_bfe_u32 s25, s6, 0x50002
	s_lshl_b32 s22, s10, 11
	s_lshl_b32 s23, s25, 6
	s_and_b32 s7, s6, 3
	s_or_b32 s24, s23, s22
	s_lshl_b32 s10, s10, 2
	s_or_b32 s26, s10, s7
	v_add_u32_e32 v74, s24, v78
	v_ashrrev_i32_e32 v75, 31, v74
	s_ashr_i32 s27, s26, 31
	v_lshlrev_b64 v[0:1], 13, v[74:75]
	s_lshl_b32 s10, s7, 8
	s_lshl_b32 s22, s7, 9
	s_lshl_b64 s[26:27], s[26:27], 21
	v_lshl_add_u64 v[0:1], s[4:5], 0, v[0:1]
	s_mov_b32 s23, s11
	s_add_u32 s26, s8, s26
	v_lshl_add_u64 v[0:1], v[0:1], 0, s[22:23]
	s_addc_u32 s27, s9, s27
	s_lshl_b32 s25, s25, 16
	v_lshl_add_u64 v[0:1], v[0:1], 0, v[168:169]
	s_mov_b64 s[28:29], 0x1800
	s_add_u32 s26, s26, s25
	v_lshl_add_u64 v[8:9], v[0:1], 0, s[28:29]
	v_add_co_u32_e32 v0, vcc, s15, v0
	s_addc_u32 s27, s27, 0
	v_mov_b32_e32 v71, v169
	v_addc_co_u32_e32 v1, vcc, 0, v1, vcc
	v_lshl_add_u64 v[12:13], s[26:27], 0, v[70:71]
	global_load_dwordx4 v[36:39], v[0:1], off offset:2048
	s_nop 0
	global_load_dwordx4 v[0:3], v[8:9], off offset:48
	global_load_dwordx4 v[4:7], v[8:9], off offset:32
	global_load_dwordx4 v[20:23], v[8:9], off offset:16
	v_lshl_add_u64 v[8:9], v[48:49], 1, v[12:13]
	global_load_dwordx4 v[128:131], v[8:9], off nt
	v_lshlrev_b64 v[74:75], 12, v[74:75]
	v_lshl_add_u64 v[74:75], s[2:3], 0, v[74:75]
	v_lshl_add_u64 v[74:75], v[74:75], 0, s[22:23]
	s_add_i32 s6, s6, s82
	v_lshl_add_u64 v[8:9], v[50:51], 1, v[12:13]
	global_load_dwordx4 v[132:135], v[8:9], off nt
	v_lshl_add_u64 v[8:9], v[52:53], 1, v[12:13]
	global_load_dwordx4 v[136:139], v[8:9], off nt
	v_lshl_add_u64 v[8:9], v[54:55], 1, v[12:13]
	global_load_dwordx4 v[140:143], v[8:9], off nt
	v_lshl_add_u64 v[8:9], v[56:57], 1, v[12:13]
	global_load_dwordx4 v[144:147], v[8:9], off nt
	v_lshl_add_u64 v[8:9], v[58:59], 1, v[12:13]
	global_load_dwordx4 v[148:151], v[8:9], off nt
	v_lshl_add_u64 v[8:9], v[60:61], 1, v[12:13]
	global_load_dwordx4 v[152:155], v[8:9], off nt
	v_lshl_add_u64 v[8:9], v[62:63], 1, v[12:13]
	global_load_dwordx4 v[156:159], v[8:9], off nt
	v_lshl_add_u64 v[12:13], v[64:65], 0, s[10:11]
	s_lshl_b32 s10, s7, 10
	s_mov_b32 s7, 0x18c84000
	s_cmpk_gt_i32 s6, 0x1ff
	v_add_u32_e32 v8, s24, v83
	v_ashrrev_i32_e32 v9, 31, v8
	v_lshlrev_b64 v[8:9], 10, v[8:9]
	v_lshl_add_u64 v[8:9], v[12:13], 0, v[8:9]
	global_load_dwordx4 v[160:163], v[8:9], off nt
	v_add_u32_e32 v8, s24, v84
	v_ashrrev_i32_e32 v9, 31, v8
	v_lshlrev_b64 v[8:9], 10, v[8:9]
	v_lshl_add_u64 v[8:9], v[12:13], 0, v[8:9]
	global_load_dwordx4 v[164:167], v[8:9], off nt
	global_load_dwordx4 v[178:181], v[68:69], off nt
	v_lshl_add_u64 v[68:69], v[68:69], 0, s[34:35]
	v_add_u32_e32 v8, s24, v79
	v_ashrrev_i32_e32 v9, 31, v8
	v_lshlrev_b64 v[8:9], 13, v[8:9]
	v_lshl_add_u64 v[8:9], s[4:5], 0, v[8:9]
	v_lshl_add_u64 v[8:9], v[8:9], 0, s[22:23]
	v_lshl_add_u64 v[8:9], v[8:9], 0, v[70:71]
	v_add_co_u32_e32 v8, vcc, s15, v8
	s_nop 1
	v_addc_co_u32_e32 v9, vcc, 0, v9, vcc
	global_load_dwordx4 v[182:185], v[8:9], off nt
	v_add_u32_e32 v8, s24, v80
	v_ashrrev_i32_e32 v9, 31, v8
	v_lshlrev_b64 v[8:9], 13, v[8:9]
	v_lshl_add_u64 v[8:9], s[4:5], 0, v[8:9]
	v_lshl_add_u64 v[8:9], v[8:9], 0, s[22:23]
	v_lshl_add_u64 v[8:9], v[8:9], 0, v[70:71]
	v_add_co_u32_e32 v8, vcc, s15, v8
	s_nop 1
	v_addc_co_u32_e32 v9, vcc, 0, v9, vcc
	global_load_dwordx4 v[186:189], v[8:9], off nt
	v_add_u32_e32 v8, s24, v81
	v_ashrrev_i32_e32 v9, 31, v8
	v_lshlrev_b64 v[8:9], 13, v[8:9]
	v_lshl_add_u64 v[8:9], s[4:5], 0, v[8:9]
	v_lshl_add_u64 v[8:9], v[8:9], 0, s[22:23]
	v_lshl_add_u64 v[8:9], v[8:9], 0, v[70:71]
	v_add_co_u32_e32 v8, vcc, s15, v8
	s_nop 1
	v_addc_co_u32_e32 v9, vcc, 0, v9, vcc
	global_load_dwordx4 v[190:193], v[8:9], off nt
	v_add_u32_e32 v8, s24, v82
	v_ashrrev_i32_e32 v9, 31, v8
	v_lshlrev_b64 v[8:9], 13, v[8:9]
	v_lshl_add_u64 v[8:9], s[4:5], 0, v[8:9]
	v_lshl_add_u64 v[8:9], v[8:9], 0, s[22:23]
	v_lshl_add_u64 v[8:9], v[8:9], 0, v[70:71]
	v_add_co_u32_e32 v8, vcc, s15, v8
	s_mov_b64 s[22:23], 0x18c84800
	s_nop 0
	v_addc_co_u32_e32 v9, vcc, 0, v9, vcc
	global_load_dwordx4 v[194:197], v[8:9], off nt
	s_waitcnt vmcnt(14)
	ds_write_b128 v92, v[128:131] offset:61440
	s_waitcnt vmcnt(13)
	ds_write_b128 v93, v[132:135] offset:61440
	s_waitcnt vmcnt(12)
	ds_write_b128 v94, v[136:139] offset:61440
	s_waitcnt vmcnt(11)
	ds_write_b128 v95, v[140:143] offset:61440
	s_waitcnt vmcnt(10)
	ds_write_b128 v96, v[144:147] offset:61440
	s_waitcnt vmcnt(9)
	ds_write_b128 v97, v[148:151] offset:61440
	s_waitcnt vmcnt(8)
	ds_write_b128 v98, v[152:155] offset:61440
	s_waitcnt vmcnt(7)
	ds_write_b128 v99, v[156:159] offset:61440
	s_waitcnt vmcnt(6)
	ds_write_b128 v100, v[160:163]
	s_waitcnt vmcnt(5)
	ds_write_b128 v101, v[164:167]
	s_waitcnt vmcnt(4)
	ds_write_b128 v85, v[178:181] offset:17408
	s_waitcnt vmcnt(3)
	ds_write_b128 v92, v[182:185] offset:26624
	s_waitcnt vmcnt(2)
	ds_write_b128 v93, v[186:189] offset:26624
	s_waitcnt vmcnt(1)
	ds_write_b128 v94, v[190:193] offset:26624
	s_waitcnt vmcnt(0)
	ds_write_b128 v95, v[194:197] offset:26624
	s_waitcnt lgkmcnt(0)
	s_barrier
; #define LAS __attribute__((address_space(3)))
; #define MFMA16(x, y, c) __builtin_amdgcn_mfma_f32_16x16x32_bf16((x), (y), (c), 0, 0, 0)
; __device__ __forceinline__ void gla_passC(LAS unsigned char* lds, int uidx, const bf16_t* PR, const bf16_t* SUB, const bf16_t* QT, const bf16_t* AM, const float* gn  ,
;                                           bf16_t* Y, int tid, int wid, int lane) {
;     ...
;     f32x4 acc[2][4];
; #pragma unroll
;     for (int a = 0; a < 2; ++a)
; #pragma unroll
;         for (int it = 0; it < 4; ++it) acc[a][it] = (f32x4){0.f, 0.f, 0.f, 0.f};
; #pragma unroll
;     for (int ks = 0; ks < 4; ++ks) { bf16x8 x[2];
; #pragma unroll
;         for (int a = 0; a < 2; ++a) x[a] = tr_frag<272>(Sn, 2 * wid + a, ks, lane);
; #pragma unroll
;         for (int it = 0; it < 4; ++it) { const bf16x8 y = *(const LAS bf16x8*)(Qs + (16 * it + r) * 136 + 32 * ks + 8 * q);
; #pragma unroll
;             for (int a = 0; a < 2; ++a) acc[a][it] = MFMA16(x[a], y, acc[a][it]); } }
	ds_read_u16 v8, v86 offset:61440
	ds_read_u16 v12, v86 offset:61984
	ds_read_u16 v9, v86 offset:62528
	ds_read_u16 v13, v86 offset:63072
	ds_read_u16 v10, v86 offset:63616
	ds_read_u16 v14, v86 offset:64160
	ds_read_u16 v11, v86 offset:64704
	ds_read_u16 v15, v86 offset:65248
	ds_read_u16 v24, v86 offset:61472
	ds_read_u16 v28, v86 offset:62016
	ds_read_u16 v25, v86 offset:62560
	ds_read_u16 v29, v86 offset:63104
	ds_read_u16 v26, v86 offset:63648
	ds_read_u16 v30, v86 offset:64192
	ds_read_u16 v27, v86 offset:64736
	ds_read_u16 v31, v86 offset:65280
	s_waitcnt lgkmcnt(8)
	v_perm_b32 v11, v15, v11, s13
	v_perm_b32 v10, v14, v10, s13
	v_perm_b32 v9, v13, v9, s13
	v_perm_b32 v8, v12, v8, s13
	ds_read_b128 v[12:15], v102
	s_waitcnt lgkmcnt(1)
	v_perm_b32 v27, v31, v27, s13
	v_perm_b32 v26, v30, v26, s13
	v_perm_b32 v25, v29, v25, s13
	v_perm_b32 v24, v28, v24, s13
	ds_read_b128 v[28:31], v102 offset:4352
	ds_read_b128 v[40:43], v102 offset:8704
	ds_read_b128 v[110:113], v102 offset:13056
	s_waitcnt lgkmcnt(3)
	v_mfma_f32_16x16x32_bf16 v[16:19], v[8:11], v[12:15], 0
	v_mfma_f32_16x16x32_bf16 v[12:15], v[24:27], v[12:15], 0
	s_waitcnt lgkmcnt(2)
	v_mfma_f32_16x16x32_bf16 v[32:35], v[8:11], v[28:31], 0
	v_mfma_f32_16x16x32_bf16 v[28:31], v[24:27], v[28:31], 0
	s_waitcnt lgkmcnt(1)
	v_mfma_f32_16x16x32_bf16 v[44:47], v[8:11], v[40:43], 0
	v_mfma_f32_16x16x32_bf16 v[40:43], v[24:27], v[40:43], 0
	s_waitcnt lgkmcnt(0)
	v_mfma_f32_16x16x32_bf16 v[8:11], v[8:11], v[110:113], 0
	v_mfma_f32_16x16x32_bf16 v[24:27], v[24:27], v[110:113], 0
	ds_read_u16 v71, v103 offset:61984
	ds_read_u16 v72, v103 offset:62528
	ds_read_u16 v73, v103 offset:63072
	ds_read_u16 v76, v103 offset:63616
	ds_read_u16 v77, v103 offset:64160
	ds_read_u16 v109, v103 offset:64704
	ds_read_u16 v110, v103 offset:65248
	ds_read_u16 v114, v103 offset:61440
	ds_read_u16 v118, v103 offset:61472
	ds_read_u16 v122, v103 offset:62016
	ds_read_u16 v119, v103 offset:62560
	ds_read_u16 v123, v103 offset:63104
	ds_read_u16 v120, v103 offset:63648
	ds_read_u16 v124, v103 offset:64192
	ds_read_u16 v121, v103 offset:64736
	ds_read_u16 v125, v103 offset:65280
	s_waitcnt lgkmcnt(9)
	v_perm_b32 v113, v110, v109, s13
	v_perm_b32 v112, v77, v76, s13
	v_perm_b32 v111, v73, v72, s13
	s_waitcnt lgkmcnt(8)
	v_perm_b32 v110, v71, v114, s13
	ds_read_b128 v[114:117], v102 offset:64
	s_waitcnt lgkmcnt(1)
	v_perm_b32 v121, v125, v121, s13
	v_perm_b32 v120, v124, v120, s13
	v_perm_b32 v119, v123, v119, s13
	v_perm_b32 v118, v122, v118, s13
	s_waitcnt lgkmcnt(0)
	v_mfma_f32_16x16x32_bf16 v[16:19], v[110:113], v[114:117], v[16:19]
	v_mfma_f32_16x16x32_bf16 v[12:15], v[118:121], v[114:117], v[12:15]
	ds_read_b128 v[114:117], v102 offset:4416
	s_waitcnt lgkmcnt(0)
	v_mfma_f32_16x16x32_bf16 v[32:35], v[110:113], v[114:117], v[32:35]
	v_mfma_f32_16x16x32_bf16 v[28:31], v[118:121], v[114:117], v[28:31]
	ds_read_b128 v[114:117], v102 offset:8768
	s_waitcnt lgkmcnt(0)
	v_mfma_f32_16x16x32_bf16 v[44:47], v[110:113], v[114:117], v[44:47]
	v_mfma_f32_16x16x32_bf16 v[40:43], v[118:121], v[114:117], v[40:43]
	ds_read_b128 v[114:117], v102 offset:13120
	s_waitcnt lgkmcnt(0)
	v_mfma_f32_16x16x32_bf16 v[8:11], v[110:113], v[114:117], v[8:11]
	v_mfma_f32_16x16x32_bf16 v[24:27], v[118:121], v[114:117], v[24:27]
	ds_read_u16 v71, v87 offset:35360
	ds_read_u16 v72, v87 offset:35904
	ds_read_u16 v73, v87 offset:36448
	ds_read_u16 v76, v87 offset:36992
	ds_read_u16 v77, v87 offset:37536
	ds_read_u16 v109, v87 offset:38080
	ds_read_u16 v110, v87 offset:38624
	ds_read_u16 v114, v87 offset:34816
	ds_read_u16 v118, v87 offset:34848
	ds_read_u16 v122, v87 offset:35392
	ds_read_u16 v119, v87 offset:35936
	ds_read_u16 v123, v87 offset:36480
	ds_read_u16 v120, v87 offset:37024
	ds_read_u16 v124, v87 offset:37568
	ds_read_u16 v121, v87 offset:38112
	ds_read_u16 v125, v87 offset:38656
	s_waitcnt lgkmcnt(9)
	v_perm_b32 v113, v110, v109, s13
	v_perm_b32 v112, v77, v76, s13
	v_perm_b32 v111, v73, v72, s13
	s_waitcnt lgkmcnt(8)
	v_perm_b32 v110, v71, v114, s13
	ds_read_b128 v[114:117], v102 offset:128
	s_waitcnt lgkmcnt(1)
	v_perm_b32 v121, v125, v121, s13
	v_perm_b32 v120, v124, v120, s13
	v_perm_b32 v119, v123, v119, s13
	v_perm_b32 v118, v122, v118, s13
	s_waitcnt lgkmcnt(0)
	v_mfma_f32_16x16x32_bf16 v[16:19], v[110:113], v[114:117], v[16:19]
	v_mfma_f32_16x16x32_bf16 v[12:15], v[118:121], v[114:117], v[12:15]
	ds_read_b128 v[114:117], v102 offset:4480
	s_waitcnt lgkmcnt(0)
	v_mfma_f32_16x16x32_bf16 v[32:35], v[110:113], v[114:117], v[32:35]
	v_mfma_f32_16x16x32_bf16 v[28:31], v[118:121], v[114:117], v[28:31]
	ds_read_b128 v[114:117], v102 offset:8832
	s_waitcnt lgkmcnt(0)
	v_mfma_f32_16x16x32_bf16 v[44:47], v[110:113], v[114:117], v[44:47]
	v_mfma_f32_16x16x32_bf16 v[40:43], v[118:121], v[114:117], v[40:43]
	ds_read_b128 v[114:117], v102 offset:13184
	s_waitcnt lgkmcnt(0)
	v_mfma_f32_16x16x32_bf16 v[8:11], v[110:113], v[114:117], v[8:11]
	v_mfma_f32_16x16x32_bf16 v[24:27], v[118:121], v[114:117], v[24:27]
	ds_read_u16 v71, v87 offset:52224
	ds_read_u16 v72, v87 offset:52768
	ds_read_u16 v73, v87 offset:53312
	ds_read_u16 v76, v87 offset:53856
	ds_read_u16 v77, v87 offset:54400
	ds_read_u16 v109, v87 offset:54944
	ds_read_u16 v110, v87 offset:55488
	ds_read_u16 v111, v87 offset:56032
	ds_read_u16 v118, v87 offset:52256
	ds_read_u16 v122, v87 offset:52800
	ds_read_u16 v119, v87 offset:53344
	ds_read_u16 v123, v87 offset:53888
	ds_read_u16 v120, v87 offset:54432
	ds_read_u16 v124, v87 offset:54976
	ds_read_u16 v121, v87 offset:55520
	ds_read_u16 v125, v87 offset:56064
	s_waitcnt lgkmcnt(8)
; #define LAS __attribute__((address_space(3)))
; #define MFMA16(x, y, c) __builtin_amdgcn_mfma_f32_16x16x32_bf16((x), (y), (c), 0, 0, 0)
; __device__ __forceinline__ void gla_passC(LAS unsigned char* lds, int uidx, const bf16_t* PR, const bf16_t* SUB, const bf16_t* QT, const bf16_t* AM, const float* gn  ,
;                                           bf16_t* Y, int tid, int wid, int lane) {
;     ...
;     for (int ks = 0; ks < 4; ++ks) { bf16x8 x[2];
; #pragma unroll
;         for (int a = 0; a < 2; ++a) x[a] = tr_frag<272>(Sn, 2 * wid + a, ks, lane);
; #pragma unroll
;         for (int it = 0; it < 4; ++it) { const bf16x8 y = *(const LAS bf16x8*)(Qs + (16 * it + r) * 136 + 32 * ks + 8 * q);
; #pragma unroll
;             for (int a = 0; a < 2; ++a) acc[a][it] = MFMA16(x[a], y, acc[a][it]); } }
; #pragma unroll
;     for (int ks = 0; ks < 2; ++ks) { bf16x8 x[2];
; #pragma unroll
;         for (int a = 0; a < 2; ++a) x[a] = tr_frag<272>(Vn, 2 * wid + a, ks, lane);
; #pragma unroll
;         for (int it = 0; it < 4; ++it) { const bf16x8 y = *(const LAS bf16x8*)(As + (16 * it + r) * 72 + 32 * ks + 8 * q);
; #pragma unroll
;             for (int a = 0; a < 2; ++a) acc[a][it] = MFMA16(x[a], y, acc[a][it]); } }
;     __syncthreads();
; #pragma unroll
;     for (int a = 0; a < 2; ++a)
; #pragma unroll
;         for (int it = 0; it < 4; ++it) *(LAS f32x4*)(Of + (16 * it + r) * 260 + 32 * wid + 16 * a + 4 * q) = acc[a][it];
;     __syncthreads();
	v_perm_b32 v113, v111, v110, s13
	v_perm_b32 v112, v109, v77, s13
	v_perm_b32 v111, v76, v73, s13
	v_perm_b32 v110, v72, v71, s13
	ds_read_b128 v[114:117], v102 offset:192
	s_waitcnt lgkmcnt(1)
	v_perm_b32 v121, v125, v121, s13
	v_perm_b32 v120, v124, v120, s13
	v_perm_b32 v119, v123, v119, s13
	v_perm_b32 v118, v122, v118, s13
	s_waitcnt lgkmcnt(0)
	v_mfma_f32_16x16x32_bf16 v[16:19], v[110:113], v[114:117], v[16:19]
	v_mfma_f32_16x16x32_bf16 v[12:15], v[118:121], v[114:117], v[12:15]
	ds_read_b128 v[114:117], v102 offset:4544
	s_waitcnt lgkmcnt(0)
	v_mfma_f32_16x16x32_bf16 v[32:35], v[110:113], v[114:117], v[32:35]
	v_mfma_f32_16x16x32_bf16 v[28:31], v[118:121], v[114:117], v[28:31]
	ds_read_b128 v[114:117], v102 offset:8896
	s_waitcnt lgkmcnt(0)
	v_mfma_f32_16x16x32_bf16 v[44:47], v[110:113], v[114:117], v[44:47]
	v_mfma_f32_16x16x32_bf16 v[40:43], v[118:121], v[114:117], v[40:43]
	ds_read_b128 v[114:117], v102 offset:13248
	s_waitcnt lgkmcnt(0)
	v_mfma_f32_16x16x32_bf16 v[8:11], v[110:113], v[114:117], v[8:11]
	v_mfma_f32_16x16x32_bf16 v[24:27], v[118:121], v[114:117], v[24:27]
	ds_read_u16 v71, v86 offset:27168
	ds_read_u16 v72, v86 offset:27712
	ds_read_u16 v73, v86 offset:28256
	ds_read_u16 v76, v86 offset:28800
	ds_read_u16 v77, v86 offset:29344
	ds_read_u16 v109, v86 offset:29888
	ds_read_u16 v110, v86 offset:30432
	ds_read_u16 v114, v86 offset:26624
	ds_read_u16 v118, v86 offset:26656
	ds_read_u16 v122, v86 offset:27200
	ds_read_u16 v119, v86 offset:27744
	ds_read_u16 v123, v86 offset:28288
	ds_read_u16 v120, v86 offset:28832
	ds_read_u16 v124, v86 offset:29376
	ds_read_u16 v121, v86 offset:29920
	ds_read_u16 v125, v86 offset:30464
	s_waitcnt lgkmcnt(9)
	v_perm_b32 v113, v110, v109, s13
	v_perm_b32 v112, v77, v76, s13
	v_perm_b32 v111, v73, v72, s13
	s_waitcnt lgkmcnt(8)
	v_perm_b32 v110, v71, v114, s13
	ds_read_b128 v[114:117], v104 offset:17408
	s_waitcnt lgkmcnt(1)
	v_perm_b32 v121, v125, v121, s13
	v_perm_b32 v120, v124, v120, s13
	v_perm_b32 v119, v123, v119, s13
	v_perm_b32 v118, v122, v118, s13
	s_waitcnt lgkmcnt(0)
	v_mfma_f32_16x16x32_bf16 v[16:19], v[110:113], v[114:117], v[16:19]
	v_mfma_f32_16x16x32_bf16 v[12:15], v[118:121], v[114:117], v[12:15]
	ds_read_b128 v[114:117], v104 offset:19712
	s_waitcnt lgkmcnt(0)
	v_mfma_f32_16x16x32_bf16 v[32:35], v[110:113], v[114:117], v[32:35]
	v_mfma_f32_16x16x32_bf16 v[28:31], v[118:121], v[114:117], v[28:31]
	ds_read_b128 v[114:117], v104 offset:22016
	s_waitcnt lgkmcnt(0)
	v_mfma_f32_16x16x32_bf16 v[44:47], v[110:113], v[114:117], v[44:47]
	v_mfma_f32_16x16x32_bf16 v[40:43], v[118:121], v[114:117], v[40:43]
	ds_read_b128 v[114:117], v104 offset:24320
	s_waitcnt lgkmcnt(0)
	v_mfma_f32_16x16x32_bf16 v[8:11], v[110:113], v[114:117], v[8:11]
	v_mfma_f32_16x16x32_bf16 v[24:27], v[118:121], v[114:117], v[24:27]
	ds_read_u16 v71, v86 offset:44032
	ds_read_u16 v72, v86 offset:44576
	ds_read_u16 v73, v86 offset:45120
	ds_read_u16 v76, v86 offset:45664
	ds_read_u16 v77, v86 offset:46208
	ds_read_u16 v109, v86 offset:46752
	ds_read_u16 v110, v86 offset:47296
	ds_read_u16 v111, v86 offset:47840
	ds_read_u16 v118, v86 offset:44064
	ds_read_u16 v122, v86 offset:44608
	ds_read_u16 v119, v86 offset:45152
	ds_read_u16 v123, v86 offset:45696
	ds_read_u16 v120, v86 offset:46240
	ds_read_u16 v124, v86 offset:46784
	ds_read_u16 v121, v86 offset:47328
	ds_read_u16 v125, v86 offset:47872
	s_waitcnt lgkmcnt(8)
	v_perm_b32 v113, v111, v110, s13
	v_perm_b32 v112, v109, v77, s13
	v_perm_b32 v111, v76, v73, s13
	v_perm_b32 v110, v72, v71, s13
	ds_read_b128 v[114:117], v104 offset:17472
	s_waitcnt lgkmcnt(1)
	v_perm_b32 v121, v125, v121, s13
	v_perm_b32 v120, v124, v120, s13
	v_perm_b32 v119, v123, v119, s13
	v_perm_b32 v118, v122, v118, s13
	s_waitcnt lgkmcnt(0)
	v_mfma_f32_16x16x32_bf16 v[16:19], v[110:113], v[114:117], v[16:19]
	v_mfma_f32_16x16x32_bf16 v[12:15], v[118:121], v[114:117], v[12:15]
	ds_read_b128 v[114:117], v104 offset:19776
	s_waitcnt lgkmcnt(0)
	v_mfma_f32_16x16x32_bf16 v[32:35], v[110:113], v[114:117], v[32:35]
	v_mfma_f32_16x16x32_bf16 v[28:31], v[118:121], v[114:117], v[28:31]
	ds_read_b128 v[114:117], v104 offset:22080
	s_waitcnt lgkmcnt(0)
	v_mfma_f32_16x16x32_bf16 v[44:47], v[110:113], v[114:117], v[44:47]
	v_mfma_f32_16x16x32_bf16 v[40:43], v[118:121], v[114:117], v[40:43]
	ds_read_b128 v[114:117], v104 offset:24384
	s_waitcnt lgkmcnt(0)
	s_barrier
	v_mfma_f32_16x16x32_bf16 v[8:11], v[110:113], v[114:117], v[8:11]
	v_mfma_f32_16x16x32_bf16 v[24:27], v[118:121], v[114:117], v[24:27]
	ds_write_b128 v105, v[16:19] offset:61440
	ds_write_b128 v106, v[32:35] offset:61440
	ds_write_b128 v107, v[44:47] offset:61440
	s_nop 3
	ds_write_b128 v108, v[8:11] offset:61440
	ds_write_b128 v105, v[12:15] offset:61504
	ds_write_b128 v106, v[28:31] offset:61504
	ds_write_b128 v107, v[40:43] offset:61504
	ds_write_b128 v108, v[24:27] offset:61504
	s_waitcnt lgkmcnt(0)
	s_barrier
; __device__ __forceinline__ unsigned cvt_pk_bf16(float lo, float hi) { unsigned r; asm volatile("v_cvt_pk_bf16_f32 %0, %1, %2" : "=v"(r) : "v"(lo), "v"(hi)); return r; }
; #define LAS __attribute__((address_space(3)))
; __device__ __forceinline__ float bf_lo(unsigned w) { return __uint_as_float(w << 16); }
; __device__ __forceinline__ float bf_hi(unsigned w) { return __uint_as_float(w & 0xffff0000u); }
; __device__ __forceinline__ float silu_f(float x) { return x * __builtin_amdgcn_rcpf(1.f + __expf(-x)); }
; __device__ __forceinline__ void gla_passC(LAS unsigned char* lds, int uidx, const bf16_t* PR, const bf16_t* SUB, const bf16_t* QT, const bf16_t* AM, const float* gn  ,
;                                           bf16_t* Y, int tid, int wid, int lane) {
;     ...
;     { const int i = tid >> 3, seg = tid & 7; f32x4 o[8]; float ss = 0.f;
; #pragma unroll
;       for (int j = 0; j < 8; ++j) { o[j] = *(const LAS f32x4*)(Of + i * 260 + seg * 32 + 4 * j); ss += (o[j].x * o[j].x + o[j].y * o[j].y) + (o[j].z * o[j].z + o[j].w * o[j].w); }
;       ss += __shfl_xor(ss, 1); ss += __shfl_xor(ss, 2); ss += __shfl_xor(ss, 4);
;       const float rstd = rsqrtf(ss * (1.f / DV) + EPS);
;       const bf16_t* gp = PR + (size_t)(tok0 + i) * PRW + 3072 + h * DV + seg * 32; const float* gnp = gn + h * DV + seg * 32; bf16_t* yp = Y + (size_t)(tok0 + i) * DM + 1024 + h * DV + seg * 32;
; #pragma unroll
;       for (int j = 0; j < 4; ++j) { const u32x4 g = ogr[j]; const f32x4 n0 = *(const f32x4*)(gnp + 8 * j), n1 = *(const f32x4*)(gnp + 8 * j + 4); const f32x4 a0 = o[2 * j], a1 = o[2 * j + 1]; u32x4 w;
;           w.x = cvt_pk_bf16(a0.x * rstd * n0.x * silu_f(bf_lo(g.x)), a0.y * rstd * n0.y * silu_f(bf_hi(g.x)));
;           w.y = cvt_pk_bf16(a0.z * rstd * n0.z * silu_f(bf_lo(g.y)), a0.w * rstd * n0.w * silu_f(bf_hi(g.y)));
;           w.z = cvt_pk_bf16(a1.x * rstd * n1.x * silu_f(bf_lo(g.z)), a1.y * rstd * n1.y * silu_f(bf_hi(g.z)));
;           w.w = cvt_pk_bf16(a1.z * rstd * n1.z * silu_f(bf_lo(g.w)), a1.w * rstd * n1.w * silu_f(bf_hi(g.w)));
;           *(u32x4*)(yp + 8 * j) = w; } }
	ds_read_b128 v[44:47], v88 offset:61440
	ds_read_b128 v[40:43], v88 offset:61456
	ds_read_b128 v[32:35], v88 offset:61472
	ds_read_b128 v[28:31], v88 offset:61488
	ds_read_b128 v[24:27], v88 offset:61504
	ds_read_b128 v[16:19], v88 offset:61520
	s_waitcnt lgkmcnt(5)
	v_mov_b32_e32 v10, v45
	s_waitcnt lgkmcnt(4)
	v_mov_b32_e32 v11, v41
	v_mov_b32_e32 v8, v44
	v_mov_b32_e32 v9, v40
	v_pk_mul_f32 v[10:11], v[10:11], v[10:11]
	v_mov_b32_e32 v12, v47
	v_mov_b32_e32 v13, v43
	v_pk_fma_f32 v[8:9], v[8:9], v[8:9], v[10:11]
	v_mov_b32_e32 v10, v46
	v_mov_b32_e32 v11, v42
	v_pk_mul_f32 v[12:13], v[12:13], v[12:13]
	v_lshlrev_b32_e32 v118, 16, v36
	v_pk_fma_f32 v[10:11], v[10:11], v[10:11], v[12:13]
	s_waitcnt lgkmcnt(3)
	v_pk_mul_f32 v[12:13], v[32:33], v[32:33]
	v_pk_add_f32 v[8:9], v[8:9], v[10:11]
	v_pk_mul_f32 v[10:11], v[34:35], v[34:35]
	v_pk_add_f32 v[8:9], v[8:9], v[8:9] op_sel:[0,1] op_sel_hi:[1,0]
	v_pk_mov_b32 v[14:15], v[12:13], v[10:11] op_sel:[1,0]
	v_mov_b32_e32 v13, v11
	v_pk_add_f32 v[10:11], v[14:15], v[12:13]
	s_waitcnt lgkmcnt(1)
	v_mul_f32_e32 v12, v24, v24
	v_mul_f32_e32 v13, v25, v25
	v_pk_add_f32 v[10:11], v[10:11], v[10:11] op_sel:[0,1] op_sel_hi:[1,0]
	v_mov_b32_e32 v9, v12
	v_mov_b32_e32 v11, v13
	v_pk_add_f32 v[8:9], v[8:9], v[10:11]
	v_mul_f32_e32 v10, v29, v29
	v_mul_f32_e32 v12, v31, v31
	v_mul_f32_e32 v14, v26, v26
	v_mul_f32_e32 v15, v27, v27
	v_pk_fma_f32 v[10:11], v[28:29], v[28:29], v[10:11] op_sel_hi:[1,1,0]
	v_pk_fma_f32 v[12:13], v[30:31], v[30:31], v[12:13] op_sel_hi:[1,1,0]
	v_mov_b32_e32 v11, v14
	v_mov_b32_e32 v13, v15
	v_pk_add_f32 v[10:11], v[10:11], v[12:13]
	s_nop 0
	v_pk_add_f32 v[72:73], v[8:9], v[10:11]
	s_waitcnt lgkmcnt(0)
	v_pk_mul_f32 v[8:9], v[18:19], v[18:19]
	v_pk_mul_f32 v[10:11], v[16:17], v[16:17]
	v_pk_add_f32 v[72:73], v[72:73], v[72:73] op_sel:[0,1] op_sel_hi:[1,0]
	v_pk_mov_b32 v[12:13], v[10:11], v[8:9] op_sel:[1,0]
	v_mov_b32_e32 v11, v9
	v_pk_add_f32 v[76:77], v[12:13], v[10:11]
	ds_read_b128 v[12:15], v88 offset:61536
	ds_read_b128 v[8:11], v88 offset:61552
	v_pk_add_f32 v[76:77], v[76:77], v[76:77] op_sel:[0,1] op_sel_hi:[1,0]
	s_waitcnt lgkmcnt(0)
	v_mul_f32_e32 v71, v8, v8
	v_mul_f32_e32 v109, v9, v9
	v_mov_b32_e32 v73, v71
	v_mov_b32_e32 v77, v109
	v_pk_add_f32 v[72:73], v[72:73], v[76:77]
	v_mul_f32_e32 v76, v13, v13
	v_mul_f32_e32 v110, v10, v10
	v_pk_fma_f32 v[76:77], v[12:13], v[12:13], v[76:77] op_sel_hi:[1,1,0]
	v_mul_f32_e32 v112, v11, v11
	v_mov_b32_e32 v77, v110
	v_mul_f32_e32 v110, v15, v15
	v_pk_fma_f32 v[110:111], v[14:15], v[14:15], v[110:111] op_sel_hi:[1,1,0]
	s_nop 0
	v_mov_b32_e32 v111, v112
	v_pk_add_f32 v[76:77], v[76:77], v[110:111]
	s_nop 0
	v_pk_add_f32 v[72:73], v[72:73], v[76:77]
	v_lshl_add_u64 v[76:77], v[74:75], 0, v[168:169]
	v_add_f32_e32 v71, v72, v73
	ds_bpermute_b32 v72, v89, v71
	v_lshl_add_u64 v[74:75], v[76:77], 0, s[22:23]
	s_waitcnt lgkmcnt(0)
	v_add_f32_e32 v71, v71, v72
	ds_bpermute_b32 v72, v90, v71
	s_waitcnt lgkmcnt(0)
	v_add_f32_e32 v71, v71, v72
	ds_bpermute_b32 v72, v91, v71
	s_waitcnt lgkmcnt(0)
	v_add_f32_e32 v71, v71, v72
	v_fmamk_f32 v71, v71, 0x3b800000, v212
	v_cmp_gt_f32_e32 vcc, s14, v71
	v_mul_f32_e32 v72, 0x4b800000, v71
	s_nop 0
	v_cndmask_b32_e32 v71, v71, v72, vcc
	v_rsq_f32_e32 v71, v71
	s_nop 0
	v_mul_f32_e32 v72, 0x45800000, v71
	v_cndmask_b32_e32 v71, v71, v72, vcc
	v_lshl_add_u64 v[72:73], v[66:67], 0, s[10:11]
	global_load_dwordx4 v[110:113], v[72:73], off offset:16
	global_load_dwordx4 v[114:117], v[72:73], off
	v_mul_f32_e32 v119, v44, v71
	v_mul_f32_e32 v44, 0xbfb8aa3b, v118
	v_exp_f32_e32 v44, v44
	v_mul_f32_e32 v45, v45, v71
	v_mul_f32_e32 v41, v41, v71
	v_mul_f32_e32 v33, v33, v71
	v_add_f32_e32 v44, 1.0, v44
	v_rcp_f32_e32 v120, v44
	v_and_b32_e32 v44, 0xffff0000, v36
	v_mul_f32_e32 v36, 0xbfb8aa3b, v44
	v_exp_f32_e32 v36, v36
	v_mul_f32_e32 v29, v29, v71
	v_mul_f32_e32 v25, v25, v71
	v_mul_f32_e32 v17, v17, v71
	v_add_f32_e32 v36, 1.0, v36
	v_mul_f32_e32 v13, v13, v71
	v_mul_f32_e32 v9, v9, v71
	s_waitcnt vmcnt(0)
	v_mov_b32_e32 v121, v114
	v_rcp_f32_e32 v114, v36
	v_pk_mul_f32 v[118:119], v[120:121], v[118:119]
	v_pk_mul_f32 v[44:45], v[114:115], v[44:45]
	s_nop 0
	v_mul_f32_e32 v36, v44, v45
	v_lshlrev_b32_e32 v44, 16, v37
	v_mul_f32_e32 v45, v46, v71
	v_mul_f32_e32 v46, 0xbfb8aa3b, v44
	v_exp_f32_e32 v46, v46
	v_mov_b32_e32 v115, v116
	v_mul_f32_e32 v109, v118, v119
	v_cvt_pk_bf16_f32 v36, v109, v36
	v_add_f32_e32 v46, 1.0, v46
	v_rcp_f32_e32 v114, v46
	s_nop 0
	v_pk_mul_f32 v[44:45], v[114:115], v[44:45]
	s_nop 0
	v_mul_f32_e32 v46, v44, v45
	v_and_b32_e32 v44, 0xffff0000, v37
	v_mul_f32_e32 v37, 0xbfb8aa3b, v44
	v_exp_f32_e32 v37, v37
	v_mul_f32_e32 v45, v47, v71
	v_mov_b32_e32 v47, v110
	v_add_f32_e32 v37, 1.0, v37
	v_rcp_f32_e32 v116, v37
	s_nop 0
	v_pk_mul_f32 v[44:45], v[116:117], v[44:45]
	s_nop 0
	v_mul_f32_e32 v37, v44, v45
	v_lshlrev_b32_e32 v44, 16, v38
	v_mul_f32_e32 v45, v40, v71
	v_mul_f32_e32 v40, 0xbfb8aa3b, v44
	v_exp_f32_e32 v40, v40
	v_cvt_pk_bf16_f32 v37, v46, v37
	s_nop 0
	v_add_f32_e32 v40, 1.0, v40
	v_rcp_f32_e32 v46, v40
	v_and_b32_e32 v40, 0xffff0000, v38
	v_mul_f32_e32 v38, 0xbfb8aa3b, v40
	v_exp_f32_e32 v38, v38
	v_pk_mul_f32 v[44:45], v[46:47], v[44:45]
	v_add_f32_e32 v38, 1.0, v38
	v_rcp_f32_e32 v110, v38
	v_mul_f32_e32 v44, v44, v45
	v_mov_b32_e32 v45, v112
	v_pk_mul_f32 v[40:41], v[110:111], v[40:41]
	s_nop 0
	v_mul_f32_e32 v38, v40, v41
	v_lshlrev_b32_e32 v40, 16, v39
	v_mul_f32_e32 v41, v42, v71
	v_mul_f32_e32 v42, 0xbfb8aa3b, v40
	v_exp_f32_e32 v42, v42
	v_cvt_pk_bf16_f32 v38, v44, v38
	s_nop 0
	v_add_f32_e32 v42, 1.0, v42
	v_rcp_f32_e32 v44, v42
	s_nop 0
	v_pk_mul_f32 v[40:41], v[44:45], v[40:41]
	s_nop 0
	v_mul_f32_e32 v42, v40, v41
	v_and_b32_e32 v40, 0xffff0000, v39
	v_mul_f32_e32 v39, 0xbfb8aa3b, v40
	v_exp_f32_e32 v39, v39
	v_mul_f32_e32 v41, v43, v71
	v_lshlrev_b32_e32 v44, 16, v20
	v_mul_f32_e32 v45, v32, v71
	v_add_f32_e32 v39, 1.0, v39
	v_rcp_f32_e32 v112, v39
	v_mul_f32_e32 v32, 0xbfb8aa3b, v44
	v_exp_f32_e32 v32, v32
	v_pk_mul_f32 v[40:41], v[112:113], v[40:41]
	s_nop 0
	v_mul_f32_e32 v39, v40, v41
	v_add_co_u32_e32 v40, vcc, s7, v76
	v_cvt_pk_bf16_f32 v39, v42, v39
	v_add_f32_e32 v32, 1.0, v32
	s_nop 0
	v_addc_co_u32_e32 v41, vcc, 0, v77, vcc
	global_store_dwordx4 v[40:41], v[36:39], off offset:2048
	global_load_dwordx4 v[36:39], v[72:73], off offset:48
	s_nop 0
	global_load_dwordx4 v[40:43], v[72:73], off offset:32
	v_rcp_f32_e32 v46, v32
	v_and_b32_e32 v32, 0xffff0000, v20
	v_mul_f32_e32 v20, 0xbfb8aa3b, v32
	v_exp_f32_e32 v20, v20
	s_waitcnt vmcnt(0)
; __device__ __forceinline__ unsigned cvt_pk_bf16(float lo, float hi) { unsigned r; asm volatile("v_cvt_pk_bf16_f32 %0, %1, %2" : "=v"(r) : "v"(lo), "v"(hi)); return r; }
; __device__ __forceinline__ float bf_lo(unsigned w) { return __uint_as_float(w << 16); }
; __device__ __forceinline__ float bf_hi(unsigned w) { return __uint_as_float(w & 0xffff0000u); }
; __device__ __forceinline__ float silu_f(float x) { return x * __builtin_amdgcn_rcpf(1.f + __expf(-x)); }
; __device__ __forceinline__ void gla_passC(LAS unsigned char* lds, int uidx, const bf16_t* PR, const bf16_t* SUB, const bf16_t* QT, const bf16_t* AM, const float* gn  ,
;                                           bf16_t* Y, int tid, int wid, int lane) {
;     ...
;       const bf16_t* gp = PR + (size_t)(tok0 + i) * PRW + 3072 + h * DV + seg * 32; const float* gnp = gn + h * DV + seg * 32; bf16_t* yp = Y + (size_t)(tok0 + i) * DM + 1024 + h * DV + seg * 32;
; #pragma unroll
;       for (int j = 0; j < 4; ++j) { const u32x4 g = ogr[j]; const f32x4 n0 = *(const f32x4*)(gnp + 8 * j), n1 = *(const f32x4*)(gnp + 8 * j + 4); const f32x4 a0 = o[2 * j], a1 = o[2 * j + 1]; u32x4 w;
;           w.x = cvt_pk_bf16(a0.x * rstd * n0.x * silu_f(bf_lo(g.x)), a0.y * rstd * n0.y * silu_f(bf_hi(g.x)));
;           w.y = cvt_pk_bf16(a0.z * rstd * n0.z * silu_f(bf_lo(g.y)), a0.w * rstd * n0.w * silu_f(bf_hi(g.y)));
;           w.z = cvt_pk_bf16(a1.x * rstd * n1.x * silu_f(bf_lo(g.z)), a1.y * rstd * n1.y * silu_f(bf_hi(g.z)));
;           w.w = cvt_pk_bf16(a1.z * rstd * n1.z * silu_f(bf_lo(g.w)), a1.w * rstd * n1.w * silu_f(bf_hi(g.w)));
;           *(u32x4*)(yp + 8 * j) = w; } }
;     __syncthreads();
	v_mov_b32_e32 v47, v40
	v_add_f32_e32 v20, 1.0, v20
	v_rcp_f32_e32 v40, v20
	v_pk_mul_f32 v[44:45], v[46:47], v[44:45]
	v_pk_mul_f32 v[32:33], v[40:41], v[32:33]
	s_nop 0
	v_mul_f32_e32 v20, v32, v33
	v_lshlrev_b32_e32 v32, 16, v21
	v_mul_f32_e32 v33, v34, v71
	v_mul_f32_e32 v34, 0xbfb8aa3b, v32
	v_exp_f32_e32 v34, v34
	v_mov_b32_e32 v41, v42
	v_mul_f32_e32 v44, v44, v45
	v_cvt_pk_bf16_f32 v20, v44, v20
	v_add_f32_e32 v34, 1.0, v34
	v_rcp_f32_e32 v40, v34
	s_nop 0
	v_pk_mul_f32 v[32:33], v[40:41], v[32:33]
	s_nop 0
	v_mul_f32_e32 v34, v32, v33
	v_and_b32_e32 v32, 0xffff0000, v21
	v_mul_f32_e32 v21, 0xbfb8aa3b, v32
	v_exp_f32_e32 v21, v21
	v_mul_f32_e32 v33, v35, v71
	v_mov_b32_e32 v35, v36
	v_add_f32_e32 v21, 1.0, v21
	v_rcp_f32_e32 v42, v21
	s_nop 0
	v_pk_mul_f32 v[32:33], v[42:43], v[32:33]
	s_nop 0
	v_mul_f32_e32 v21, v32, v33
	v_lshlrev_b32_e32 v32, 16, v22
	v_mul_f32_e32 v33, v28, v71
	v_mul_f32_e32 v28, 0xbfb8aa3b, v32
	v_exp_f32_e32 v28, v28
	v_cvt_pk_bf16_f32 v21, v34, v21
	s_nop 0
	v_add_f32_e32 v28, 1.0, v28
	v_rcp_f32_e32 v34, v28
	v_and_b32_e32 v28, 0xffff0000, v22
	v_mul_f32_e32 v22, 0xbfb8aa3b, v28
	v_exp_f32_e32 v22, v22
	v_pk_mul_f32 v[32:33], v[34:35], v[32:33]
	v_lshlrev_b32_e32 v34, 16, v4
	v_mul_f32_e32 v32, v32, v33
	v_add_f32_e32 v22, 1.0, v22
	v_rcp_f32_e32 v36, v22
	v_mov_b32_e32 v33, v38
	v_pk_mul_f32 v[28:29], v[36:37], v[28:29]
	s_nop 0
	v_mul_f32_e32 v22, v28, v29
	v_lshlrev_b32_e32 v28, 16, v23
	v_mul_f32_e32 v29, v30, v71
	v_mul_f32_e32 v30, 0xbfb8aa3b, v28
	v_exp_f32_e32 v30, v30
	v_cvt_pk_bf16_f32 v22, v32, v22
	s_nop 0
	v_add_f32_e32 v30, 1.0, v30
	v_rcp_f32_e32 v32, v30
	s_nop 0
	v_pk_mul_f32 v[28:29], v[32:33], v[28:29]
	s_nop 0
	v_mul_f32_e32 v30, v28, v29
	v_and_b32_e32 v28, 0xffff0000, v23
	v_mul_f32_e32 v23, 0xbfb8aa3b, v28
	v_exp_f32_e32 v23, v23
	v_mul_f32_e32 v29, v31, v71
	v_mul_f32_e32 v33, v24, v71
	v_mul_f32_e32 v24, 0xbfb8aa3b, v34
	v_add_f32_e32 v23, 1.0, v23
	v_rcp_f32_e32 v38, v23
	v_exp_f32_e32 v24, v24
	v_pk_mul_f32 v[28:29], v[38:39], v[28:29]
	s_nop 0
	v_mul_f32_e32 v23, v28, v29
	v_cvt_pk_bf16_f32 v23, v30, v23
	global_store_dwordx4 v[74:75], v[20:23], off offset:16
	global_load_dwordx4 v[20:23], v[72:73], off offset:80
	s_nop 0
	global_load_dwordx4 v[28:31], v[72:73], off offset:64
	v_add_f32_e32 v24, 1.0, v24
	v_rcp_f32_e32 v32, v24
	s_waitcnt vmcnt(0)
	v_mov_b32_e32 v35, v28
	v_and_b32_e32 v28, 0xffff0000, v4
	v_mul_f32_e32 v4, 0xbfb8aa3b, v28
	v_exp_f32_e32 v4, v4
	v_pk_mul_f32 v[32:33], v[32:33], v[34:35]
	v_add_f32_e32 v4, 1.0, v4
	v_rcp_f32_e32 v24, v4
	v_mul_f32_e32 v32, v32, v33
	v_pk_mul_f32 v[24:25], v[24:25], v[28:29]
	v_lshlrev_b32_e32 v28, 16, v5
	v_mul_f32_e32 v4, v24, v25
	v_mul_f32_e32 v24, 0xbfb8aa3b, v28
	v_exp_f32_e32 v24, v24
	v_mov_b32_e32 v29, v30
	v_and_b32_e32 v30, 0xffff0000, v5
	v_mul_f32_e32 v5, 0xbfb8aa3b, v30
	v_add_f32_e32 v24, 1.0, v24
	v_rcp_f32_e32 v24, v24
	v_exp_f32_e32 v5, v5
	v_mul_f32_e32 v25, v26, v71
	v_cvt_pk_bf16_f32 v4, v32, v4
	v_pk_mul_f32 v[24:25], v[24:25], v[28:29]
	v_add_f32_e32 v5, 1.0, v5
	v_mul_f32_e32 v26, v24, v25
	v_rcp_f32_e32 v24, v5
	v_mul_f32_e32 v25, v27, v71
	v_mov_b32_e32 v27, v20
	v_and_b32_e32 v20, 0xffff0000, v6
	v_pk_mul_f32 v[24:25], v[24:25], v[30:31]
	s_nop 0
	v_mul_f32_e32 v5, v24, v25
	v_cvt_pk_bf16_f32 v5, v26, v5
	v_lshlrev_b32_e32 v26, 16, v6
	v_mul_f32_e32 v25, v16, v71
	v_mul_f32_e32 v16, 0xbfb8aa3b, v26
	v_mul_f32_e32 v6, 0xbfb8aa3b, v20
	v_exp_f32_e32 v16, v16
	v_exp_f32_e32 v6, v6
	v_add_f32_e32 v16, 1.0, v16
	v_add_f32_e32 v6, 1.0, v6
	v_rcp_f32_e32 v24, v16
	v_rcp_f32_e32 v16, v6
	v_pk_mul_f32 v[24:25], v[24:25], v[26:27]
	v_pk_mul_f32 v[16:17], v[16:17], v[20:21]
	v_lshlrev_b32_e32 v20, 16, v7
	v_mul_f32_e32 v6, v16, v17
	v_mul_f32_e32 v16, 0xbfb8aa3b, v20
	v_exp_f32_e32 v16, v16
	v_mov_b32_e32 v21, v22
	v_and_b32_e32 v22, 0xffff0000, v7
	v_mul_f32_e32 v7, 0xbfb8aa3b, v22
	v_add_f32_e32 v16, 1.0, v16
	v_rcp_f32_e32 v16, v16
	v_exp_f32_e32 v7, v7
	v_mul_f32_e32 v17, v18, v71
	v_mul_f32_e32 v24, v24, v25
	v_pk_mul_f32 v[16:17], v[16:17], v[20:21]
	v_add_f32_e32 v7, 1.0, v7
	v_mul_f32_e32 v18, v16, v17
	v_rcp_f32_e32 v16, v7
	v_mul_f32_e32 v17, v19, v71
	v_cvt_pk_bf16_f32 v6, v24, v6
	v_mul_f32_e32 v21, v12, v71
	v_pk_mul_f32 v[16:17], v[16:17], v[22:23]
	v_lshlrev_b32_e32 v22, 16, v0
	v_mul_f32_e32 v7, v16, v17
	v_cvt_pk_bf16_f32 v7, v18, v7
	global_store_dwordx4 v[74:75], v[4:7], off offset:32
	global_load_dwordx4 v[4:7], v[72:73], off offset:112
	s_nop 0
	global_load_dwordx4 v[16:19], v[72:73], off offset:96
	v_mul_f32_e32 v12, 0xbfb8aa3b, v22
	v_exp_f32_e32 v12, v12
	s_waitcnt vmcnt(0)
	v_mov_b32_e32 v23, v16
	v_and_b32_e32 v16, 0xffff0000, v0
	v_mul_f32_e32 v0, 0xbfb8aa3b, v16
	v_exp_f32_e32 v0, v0
	v_add_f32_e32 v12, 1.0, v12
	v_rcp_f32_e32 v20, v12
	v_add_f32_e32 v0, 1.0, v0
	v_rcp_f32_e32 v12, v0
	v_pk_mul_f32 v[20:21], v[20:21], v[22:23]
	v_pk_mul_f32 v[12:13], v[12:13], v[16:17]
	v_lshlrev_b32_e32 v16, 16, v1
	v_mul_f32_e32 v0, v12, v13
	v_mul_f32_e32 v12, 0xbfb8aa3b, v16
	v_exp_f32_e32 v12, v12
	v_mov_b32_e32 v17, v18
	v_and_b32_e32 v18, 0xffff0000, v1
	v_mul_f32_e32 v1, 0xbfb8aa3b, v18
	v_add_f32_e32 v12, 1.0, v12
	v_rcp_f32_e32 v12, v12
	v_exp_f32_e32 v1, v1
	v_mul_f32_e32 v13, v14, v71
	v_mul_f32_e32 v20, v20, v21
	v_pk_mul_f32 v[12:13], v[12:13], v[16:17]
	v_add_f32_e32 v1, 1.0, v1
	v_mul_f32_e32 v14, v12, v13
	v_rcp_f32_e32 v12, v1
	v_mul_f32_e32 v13, v15, v71
	v_cvt_pk_bf16_f32 v0, v20, v0
	v_mov_b32_e32 v15, v4
	v_pk_mul_f32 v[12:13], v[12:13], v[18:19]
	v_and_b32_e32 v4, 0xffff0000, v2
	v_mul_f32_e32 v1, v12, v13
	v_cvt_pk_bf16_f32 v1, v14, v1
	v_lshlrev_b32_e32 v14, 16, v2
	v_mul_f32_e32 v13, v8, v71
	v_mul_f32_e32 v8, 0xbfb8aa3b, v14
	v_mul_f32_e32 v2, 0xbfb8aa3b, v4
	v_exp_f32_e32 v8, v8
	v_exp_f32_e32 v2, v2
	v_add_f32_e32 v8, 1.0, v8
	v_add_f32_e32 v2, 1.0, v2
	v_rcp_f32_e32 v12, v8
	v_rcp_f32_e32 v8, v2
	v_pk_mul_f32 v[12:13], v[12:13], v[14:15]
	v_pk_mul_f32 v[4:5], v[8:9], v[4:5]
	v_lshlrev_b32_e32 v8, 16, v3
	v_mul_f32_e32 v2, v4, v5
	v_mul_f32_e32 v4, 0xbfb8aa3b, v8
	v_exp_f32_e32 v4, v4
	v_mov_b32_e32 v9, v6
	v_and_b32_e32 v6, 0xffff0000, v3
	v_mul_f32_e32 v3, 0xbfb8aa3b, v6
	v_add_f32_e32 v4, 1.0, v4
	v_rcp_f32_e32 v4, v4
	v_exp_f32_e32 v3, v3
	v_mul_f32_e32 v5, v10, v71
	v_mul_f32_e32 v12, v12, v13
	v_pk_mul_f32 v[4:5], v[4:5], v[8:9]
	v_add_f32_e32 v3, 1.0, v3
	v_mul_f32_e32 v8, v4, v5
	v_rcp_f32_e32 v4, v3
	v_mul_f32_e32 v5, v11, v71
	v_cvt_pk_bf16_f32 v2, v12, v2
	v_pk_mul_f32 v[4:5], v[4:5], v[6:7]
	s_nop 0
	v_mul_f32_e32 v3, v4, v5
	v_cvt_pk_bf16_f32 v3, v8, v3
	global_store_dwordx4 v[74:75], v[0:3], off offset:48
	s_barrier
	s_cbranch_scc0 .LBB0_487

; __device__ __forceinline__ unsigned cvt_pk_bf16(float lo, float hi) { unsigned r; asm volatile("v_cvt_pk_bf16_f32 %0, %1, %2" : "=v"(r) : "v"(lo), "v"(hi)); return r; }
; #define EPI_ST(p, v) __builtin_nontemporal_store((v), (p))
; __device__ __forceinline__ float bf_lo(unsigned w) { return __uint_as_float(w << 16); }
; __device__ __forceinline__ float bf_hi(unsigned w) { return __uint_as_float(w & 0xffff0000u); }
;     __device__ __forceinline__ void operator()(const f32x4 (&acc)[2][2][4][2], const pg8::Unit& u, int wr, int wc, int fr, int fq) const {
;     ...
; #pragma unroll
;         for (int ai = 0; ai < 2; ++ai)
; #pragma unroll
;             for (int m = 0; m < 4; ++m) { const int row = row0 + ai * 128 + m * 16;
;                 { bf16_t* xb = XB + (size_t)row * DM + col0; float ss = 0.f;
; #pragma unroll
;                     for (int bj = 0; bj < 2; ++bj) { f32x4 b0, b1;
;                         if (baseP) { const float* bp = baseP + (size_t)row * DM + col0 + bj * 128; b0 = *(const f32x4*)bp; b1 = *(const f32x4*)(bp + 4); }
;                         else { const u32x4 bw = *(const u32x4*)(xb + bj * 128); b0 = (f32x4){bf_lo(bw.x), bf_hi(bw.x), bf_lo(bw.y), bf_hi(bw.y)}; b1 = (f32x4){bf_lo(bw.z), bf_hi(bw.z), bf_lo(bw.w), bf_hi(bw.w)}; }
;                         const f32x4 v0 = b0 + acc[ai][bj][m][0], v1 = b1 + acc[ai][bj][m][1];
;                         ss += ((v0.x * v0.x + v0.y * v0.y) + (v0.z * v0.z + v0.w * v0.w)) + ((v1.x * v1.x + v1.y * v1.y) + (v1.z * v1.z + v1.w * v1.w));
;                         u32x4 w; w.x = cvt_pk_bf16(v0.x, v0.y); w.y = cvt_pk_bf16(v0.z, v0.w); w.z = cvt_pk_bf16(v1.x, v1.y); w.w = cvt_pk_bf16(v1.z, v1.w); EPI_ST((u32x4*)(xb + bj * 128), w); }
;                     if (SS) { ss += __shfl_xor(ss, 16); ss += __shfl_xor(ss, 32); if (fq == 0) SS[(size_t)row * 32 + u.pn * 4 + wc] = ss; } }
;                 asm volatile("" ::: "memory"); }
.LBB0_563:
	s_mov_b32 s5, s58
	v_mov_b32_e32 v160, v163
	s_mov_b32 s56, s69
	v_mov_b32_e32 v144, v162
	s_lshl_b32 s54, s5, 6
	s_lshl_b32 s5, s22, 8
	s_lshl_b32 s6, s56, 5
	s_add_i32 s6, s6, s5
	v_lshl_add_u32 v142, v160, 3, s6
	v_readlane_b32 s78, v244, 5
	s_cmp_gt_i32 s4, -1
	v_ashrrev_i32_e32 v143, 31, v142
	s_mov_b64 s[6:7], -1
	v_readlane_b32 s79, v244, 6
	s_cbranch_scc1 .LBB0_566
	s_lshl_b32 s5, s40, 8
	s_add_i32 s5, s54, s5
	v_add_u32_e32 v146, s5, v144
	v_lshlrev_b32_e32 v247, 12, v146
	v_lshl_add_u32 v247, v142, 1, v247
	v_lshlrev_b32_e32 v255, 7, v146
	v_xor_b32_e32 v166, 16, v211
	v_xor_b32_e32 v167, 32, v211
	v_lshlrev_b32_e32 v166, 2, v166
	v_lshlrev_b32_e32 v167, 2, v167
	s_lshl_b32 s5, s22, 4
	s_lshl_b32 s30, s56, 2
	s_add_i32 s5, s5, s30
	s_add_u32 s100, s28, s5
	s_addc_u32 s101, s29, 0
	s_and_b64 vcc, exec, s[38:39]
	s_cbranch_vccz .Lres1_bf16
	v_lshlrev_b32_e32 v248, 1, v247
	global_load_dwordx4 v[128:131], v248, s[2:3] nt
	global_load_dwordx4 v[132:135], v248, s[2:3] offset:16 nt
	global_load_dwordx4 v[142:145], v248, s[2:3] offset:512 nt
	global_load_dwordx4 v[146:149], v248, s[2:3] offset:528 nt
	s_add_u32 s98, s2, 0x20000
	s_addc_u32 s99, s3, 0
	global_load_dwordx4 v[150:153], v248, s[98:99] nt
	global_load_dwordx4 v[154:157], v248, s[98:99] offset:16 nt
	global_load_dwordx4 v[158:161], v248, s[98:99] offset:512 nt
	global_load_dwordx4 v[178:181], v248, s[98:99] offset:528 nt
	s_add_u32 s98, s2, 0x40000
	s_addc_u32 s99, s3, 0
	global_load_dwordx4 v[182:185], v248, s[98:99] nt
	global_load_dwordx4 v[186:189], v248, s[98:99] offset:16 nt
	global_load_dwordx4 v[190:193], v248, s[98:99] offset:512 nt
	global_load_dwordx4 v[194:197], v248, s[98:99] offset:528 nt
	s_add_u32 s98, s2, 0x60000
	s_addc_u32 s99, s3, 0
	global_load_dwordx4 v[198:201], v248, s[98:99] nt
	global_load_dwordx4 v[202:205], v248, s[98:99] offset:16 nt
	global_load_dwordx4 v[206:209], v248, s[98:99] offset:512 nt
	global_load_dwordx4 v[226:229], v248, s[98:99] offset:528 nt
	s_waitcnt vmcnt(12)
	v_pk_add_f32 v[68:69], v[68:69], v[128:129]
	v_pk_add_f32 v[70:71], v[70:71], v[130:131]
	v_pk_add_f32 v[64:65], v[64:65], v[132:133]
	v_pk_add_f32 v[66:67], v[66:67], v[134:135]
	v_pk_add_f32 v[48:49], v[48:49], v[142:143]
	v_pk_add_f32 v[50:51], v[50:51], v[144:145]
	v_pk_add_f32 v[44:45], v[44:45], v[146:147]
	v_pk_add_f32 v[46:47], v[46:47], v[148:149]
	v_mul_f32_e32 v250, v69, v69
	v_mul_f32_e32 v252, v71, v71
	v_fmac_f32_e32 v250, v68, v68
	v_fmac_f32_e32 v252, v70, v70
	v_mul_f32_e32 v253, v65, v65
	v_mul_f32_e32 v254, v67, v67
	v_add_f32_e32 v250, v250, v252
	v_fmac_f32_e32 v253, v64, v64
	v_fmac_f32_e32 v254, v66, v66
	v_add_f32_e32 v253, v253, v254
	v_add_f32_e32 v250, v250, v253
	v_mul_f32_e32 v251, v49, v49
	v_mul_f32_e32 v252, v51, v51
	v_fmac_f32_e32 v251, v48, v48
	v_fmac_f32_e32 v252, v50, v50
	v_mul_f32_e32 v253, v45, v45
	v_mul_f32_e32 v254, v47, v47
	v_add_f32_e32 v251, v251, v252
	v_fmac_f32_e32 v253, v44, v44
	v_fmac_f32_e32 v254, v46, v46
	v_add_f32_e32 v253, v253, v254
	v_add_f32_e32 v251, v251, v253
	v_cvt_pk_bf16_f32 v128, v68, v69
	v_cvt_pk_bf16_f32 v129, v70, v71
	v_cvt_pk_bf16_f32 v130, v64, v65
	v_cvt_pk_bf16_f32 v131, v66, v67
	v_cvt_pk_bf16_f32 v142, v48, v49
	v_cvt_pk_bf16_f32 v143, v50, v51
	v_cvt_pk_bf16_f32 v144, v44, v45
	v_cvt_pk_bf16_f32 v145, v46, v47
	v_add_f32_e32 v132, v250, v251
	global_store_dwordx4 v247, v[128:131], s[26:27]
	global_store_dwordx4 v247, v[142:145], s[26:27] offset:256
	s_add_u32 s98, s2, 0x100000
	s_addc_u32 s99, s3, 0
	global_load_dwordx4 v[68:71], v248, s[98:99] nt
	global_load_dwordx4 v[64:67], v248, s[98:99] offset:16 nt
	global_load_dwordx4 v[48:51], v248, s[98:99] offset:512 nt
	global_load_dwordx4 v[44:47], v248, s[98:99] offset:528 nt
	s_waitcnt vmcnt(14)
	v_pk_add_f32 v[60:61], v[60:61], v[150:151]
	v_pk_add_f32 v[62:63], v[62:63], v[152:153]
	v_pk_add_f32 v[56:57], v[56:57], v[154:155]
	v_pk_add_f32 v[58:59], v[58:59], v[156:157]
	v_pk_add_f32 v[28:29], v[28:29], v[158:159]
	v_pk_add_f32 v[30:31], v[30:31], v[160:161]
	v_pk_add_f32 v[24:25], v[24:25], v[178:179]
	v_pk_add_f32 v[26:27], v[26:27], v[180:181]
	v_mul_f32_e32 v250, v61, v61
	v_mul_f32_e32 v252, v63, v63
	v_fmac_f32_e32 v250, v60, v60
	v_fmac_f32_e32 v252, v62, v62
	v_mul_f32_e32 v253, v57, v57
	v_mul_f32_e32 v254, v59, v59
	v_add_f32_e32 v250, v250, v252
	v_fmac_f32_e32 v253, v56, v56
	v_fmac_f32_e32 v254, v58, v58
	v_add_f32_e32 v253, v253, v254
	v_add_f32_e32 v250, v250, v253
	v_mul_f32_e32 v251, v29, v29
	v_mul_f32_e32 v252, v31, v31
	v_fmac_f32_e32 v251, v28, v28
	v_fmac_f32_e32 v252, v30, v30
	v_mul_f32_e32 v253, v25, v25
	v_mul_f32_e32 v254, v27, v27
	v_add_f32_e32 v251, v251, v252
	v_fmac_f32_e32 v253, v24, v24
	v_fmac_f32_e32 v254, v26, v26
	v_add_f32_e32 v253, v253, v254
	v_add_f32_e32 v251, v251, v253
	v_cvt_pk_bf16_f32 v150, v60, v61
	v_cvt_pk_bf16_f32 v151, v62, v63
	v_cvt_pk_bf16_f32 v152, v56, v57
	v_cvt_pk_bf16_f32 v153, v58, v59
	v_cvt_pk_bf16_f32 v158, v28, v29
	v_cvt_pk_bf16_f32 v159, v30, v31
	v_cvt_pk_bf16_f32 v160, v24, v25
	v_cvt_pk_bf16_f32 v161, v26, v27
	v_add_f32_e32 v154, v250, v251
	s_add_u32 s98, s26, 0x10000
	s_addc_u32 s99, s27, 0
	global_store_dwordx4 v247, v[150:153], s[98:99]
	global_store_dwordx4 v247, v[158:161], s[98:99] offset:256
	s_add_u32 s98, s2, 0x120000
	s_addc_u32 s99, s3, 0
	global_load_dwordx4 v[60:63], v248, s[98:99] nt
	global_load_dwordx4 v[56:59], v248, s[98:99] offset:16 nt
	global_load_dwordx4 v[28:31], v248, s[98:99] offset:512 nt
	global_load_dwordx4 v[24:27], v248, s[98:99] offset:528 nt
	s_waitcnt vmcnt(16)
; __device__ __forceinline__ unsigned cvt_pk_bf16(float lo, float hi) { unsigned r; asm volatile("v_cvt_pk_bf16_f32 %0, %1, %2" : "=v"(r) : "v"(lo), "v"(hi)); return r; }
; #define EPI_ST(p, v) __builtin_nontemporal_store((v), (p))
; __device__ __forceinline__ float bf_lo(unsigned w) { return __uint_as_float(w << 16); }
; __device__ __forceinline__ float bf_hi(unsigned w) { return __uint_as_float(w & 0xffff0000u); }
;     __device__ __forceinline__ void operator()(const f32x4 (&acc)[2][2][4][2], const pg8::Unit& u, int wr, int wc, int fr, int fq) const {
;     ...
;                     for (int bj = 0; bj < 2; ++bj) { f32x4 b0, b1;
;                         if (baseP) { const float* bp = baseP + (size_t)row * DM + col0 + bj * 128; b0 = *(const f32x4*)bp; b1 = *(const f32x4*)(bp + 4); }
;                         else { const u32x4 bw = *(const u32x4*)(xb + bj * 128); b0 = (f32x4){bf_lo(bw.x), bf_hi(bw.x), bf_lo(bw.y), bf_hi(bw.y)}; b1 = (f32x4){bf_lo(bw.z), bf_hi(bw.z), bf_lo(bw.w), bf_hi(bw.w)}; }
;                         const f32x4 v0 = b0 + acc[ai][bj][m][0], v1 = b1 + acc[ai][bj][m][1];
;                         ss += ((v0.x * v0.x + v0.y * v0.y) + (v0.z * v0.z + v0.w * v0.w)) + ((v1.x * v1.x + v1.y * v1.y) + (v1.z * v1.z + v1.w * v1.w));
;                         u32x4 w; w.x = cvt_pk_bf16(v0.x, v0.y); w.y = cvt_pk_bf16(v0.z, v0.w); w.z = cvt_pk_bf16(v1.x, v1.y); w.w = cvt_pk_bf16(v1.z, v1.w); EPI_ST((u32x4*)(xb + bj * 128), w); }
	v_pk_add_f32 v[40:41], v[40:41], v[182:183]
	v_pk_add_f32 v[42:43], v[42:43], v[184:185]
	v_pk_add_f32 v[32:33], v[32:33], v[186:187]
	v_pk_add_f32 v[34:35], v[34:35], v[188:189]
	v_pk_add_f32 v[12:13], v[12:13], v[190:191]
	v_pk_add_f32 v[14:15], v[14:15], v[192:193]
	v_pk_add_f32 v[8:9], v[8:9], v[194:195]
	v_pk_add_f32 v[10:11], v[10:11], v[196:197]
	v_mul_f32_e32 v250, v41, v41
	v_mul_f32_e32 v252, v43, v43
	v_fmac_f32_e32 v250, v40, v40
	v_fmac_f32_e32 v252, v42, v42
	v_mul_f32_e32 v253, v33, v33
	v_mul_f32_e32 v254, v35, v35
	v_add_f32_e32 v250, v250, v252
	v_fmac_f32_e32 v253, v32, v32
	v_fmac_f32_e32 v254, v34, v34
	v_add_f32_e32 v253, v253, v254
	v_add_f32_e32 v250, v250, v253
	v_mul_f32_e32 v251, v13, v13
	v_mul_f32_e32 v252, v15, v15
	v_fmac_f32_e32 v251, v12, v12
	v_fmac_f32_e32 v252, v14, v14
	v_mul_f32_e32 v253, v9, v9
	v_mul_f32_e32 v254, v11, v11
	v_add_f32_e32 v251, v251, v252
	v_fmac_f32_e32 v253, v8, v8
	v_fmac_f32_e32 v254, v10, v10
	v_add_f32_e32 v253, v253, v254
	v_add_f32_e32 v251, v251, v253
	v_cvt_pk_bf16_f32 v182, v40, v41
	v_cvt_pk_bf16_f32 v183, v42, v43
	v_cvt_pk_bf16_f32 v184, v32, v33
	v_cvt_pk_bf16_f32 v185, v34, v35
	v_cvt_pk_bf16_f32 v190, v12, v13
	v_cvt_pk_bf16_f32 v191, v14, v15
	v_cvt_pk_bf16_f32 v192, v8, v9
	v_cvt_pk_bf16_f32 v193, v10, v11
	v_add_f32_e32 v186, v250, v251
	s_add_u32 s98, s26, 0x20000
	s_addc_u32 s99, s27, 0
	global_store_dwordx4 v247, v[182:185], s[98:99]
	global_store_dwordx4 v247, v[190:193], s[98:99] offset:256
	s_add_u32 s98, s2, 0x140000
	s_addc_u32 s99, s3, 0
	global_load_dwordx4 v[40:43], v248, s[98:99] nt
	global_load_dwordx4 v[32:35], v248, s[98:99] offset:16 nt
	global_load_dwordx4 v[12:15], v248, s[98:99] offset:512 nt
	global_load_dwordx4 v[8:11], v248, s[98:99] offset:528 nt
	s_waitcnt vmcnt(18)
	v_pk_add_f32 v[20:21], v[20:21], v[198:199]
	v_pk_add_f32 v[22:23], v[22:23], v[200:201]
	v_pk_add_f32 v[16:17], v[16:17], v[202:203]
	v_pk_add_f32 v[18:19], v[18:19], v[204:205]
	v_pk_add_f32 v[4:5], v[4:5], v[206:207]
	v_pk_add_f32 v[6:7], v[6:7], v[208:209]
	v_pk_add_f32 v[0:1], v[0:1], v[226:227]
	v_pk_add_f32 v[2:3], v[2:3], v[228:229]
	v_mul_f32_e32 v250, v21, v21
	v_mul_f32_e32 v252, v23, v23
	v_fmac_f32_e32 v250, v20, v20
	v_fmac_f32_e32 v252, v22, v22
	v_mul_f32_e32 v253, v17, v17
	v_mul_f32_e32 v254, v19, v19
	v_add_f32_e32 v250, v250, v252
	v_fmac_f32_e32 v253, v16, v16
	v_fmac_f32_e32 v254, v18, v18
	v_add_f32_e32 v253, v253, v254
	v_add_f32_e32 v250, v250, v253
	v_mul_f32_e32 v251, v5, v5
	v_mul_f32_e32 v252, v7, v7
	v_fmac_f32_e32 v251, v4, v4
	v_fmac_f32_e32 v252, v6, v6
	v_mul_f32_e32 v253, v1, v1
	v_mul_f32_e32 v254, v3, v3
	v_add_f32_e32 v251, v251, v252
	v_fmac_f32_e32 v253, v0, v0
	v_fmac_f32_e32 v254, v2, v2
	v_add_f32_e32 v253, v253, v254
	v_add_f32_e32 v251, v251, v253
	v_cvt_pk_bf16_f32 v198, v20, v21
	v_cvt_pk_bf16_f32 v199, v22, v23
	v_cvt_pk_bf16_f32 v200, v16, v17
	v_cvt_pk_bf16_f32 v201, v18, v19
	v_cvt_pk_bf16_f32 v206, v4, v5
	v_cvt_pk_bf16_f32 v207, v6, v7
	v_cvt_pk_bf16_f32 v208, v0, v1
	v_cvt_pk_bf16_f32 v209, v2, v3
	v_add_f32_e32 v202, v250, v251
	s_add_u32 s98, s26, 0x30000
	s_addc_u32 s99, s27, 0
	global_store_dwordx4 v247, v[198:201], s[98:99]
	global_store_dwordx4 v247, v[206:209], s[98:99] offset:256
	s_add_u32 s98, s2, 0x160000
	s_addc_u32 s99, s3, 0
	global_load_dwordx4 v[20:23], v248, s[98:99] nt
	global_load_dwordx4 v[16:19], v248, s[98:99] offset:16 nt
	global_load_dwordx4 v[4:7], v248, s[98:99] offset:512 nt
	global_load_dwordx4 v[0:3], v248, s[98:99] offset:528 nt
	s_waitcnt vmcnt(18)
	v_pk_add_f32 v[124:125], v[124:125], v[68:69]
	v_pk_add_f32 v[126:127], v[126:127], v[70:71]
	v_pk_add_f32 v[120:121], v[120:121], v[64:65]
	v_pk_add_f32 v[122:123], v[122:123], v[66:67]
	v_pk_add_f32 v[116:117], v[116:117], v[48:49]
	v_pk_add_f32 v[118:119], v[118:119], v[50:51]
	v_pk_add_f32 v[112:113], v[112:113], v[44:45]
	v_pk_add_f32 v[114:115], v[114:115], v[46:47]
	v_mul_f32_e32 v250, v125, v125
	v_mul_f32_e32 v252, v127, v127
	v_fmac_f32_e32 v250, v124, v124
	v_fmac_f32_e32 v252, v126, v126
	v_mul_f32_e32 v253, v121, v121
	v_mul_f32_e32 v254, v123, v123
	v_add_f32_e32 v250, v250, v252
	v_fmac_f32_e32 v253, v120, v120
	v_fmac_f32_e32 v254, v122, v122
	v_add_f32_e32 v253, v253, v254
	v_add_f32_e32 v250, v250, v253
	v_mul_f32_e32 v251, v117, v117
	v_mul_f32_e32 v252, v119, v119
	v_fmac_f32_e32 v251, v116, v116
	v_fmac_f32_e32 v252, v118, v118
	v_mul_f32_e32 v253, v113, v113
	v_mul_f32_e32 v254, v115, v115
	v_add_f32_e32 v251, v251, v252
	v_fmac_f32_e32 v253, v112, v112
	v_fmac_f32_e32 v254, v114, v114
	v_add_f32_e32 v253, v253, v254
	v_add_f32_e32 v251, v251, v253
	v_cvt_pk_bf16_f32 v68, v124, v125
	v_cvt_pk_bf16_f32 v69, v126, v127
	v_cvt_pk_bf16_f32 v70, v120, v121
	v_cvt_pk_bf16_f32 v71, v122, v123
	v_cvt_pk_bf16_f32 v48, v116, v117
	v_cvt_pk_bf16_f32 v49, v118, v119
	v_cvt_pk_bf16_f32 v50, v112, v113
	v_cvt_pk_bf16_f32 v51, v114, v115
	v_add_f32_e32 v64, v250, v251
	s_add_u32 s98, s26, 0x80000
	s_addc_u32 s99, s27, 0
	global_store_dwordx4 v247, v[68:71], s[98:99]
	global_store_dwordx4 v247, v[48:51], s[98:99] offset:256
	s_waitcnt vmcnt(14)
; __device__ __forceinline__ unsigned cvt_pk_bf16(float lo, float hi) { unsigned r; asm volatile("v_cvt_pk_bf16_f32 %0, %1, %2" : "=v"(r) : "v"(lo), "v"(hi)); return r; }
; #define EPI_ST(p, v) __builtin_nontemporal_store((v), (p))
; __device__ __forceinline__ float bf_lo(unsigned w) { return __uint_as_float(w << 16); }
; __device__ __forceinline__ float bf_hi(unsigned w) { return __uint_as_float(w & 0xffff0000u); }
;     __device__ __forceinline__ void operator()(const f32x4 (&acc)[2][2][4][2], const pg8::Unit& u, int wr, int wc, int fr, int fq) const {
;     ...
;                         if (baseP) { const float* bp = baseP + (size_t)row * DM + col0 + bj * 128; b0 = *(const f32x4*)bp; b1 = *(const f32x4*)(bp + 4); }
;                         else { const u32x4 bw = *(const u32x4*)(xb + bj * 128); b0 = (f32x4){bf_lo(bw.x), bf_hi(bw.x), bf_lo(bw.y), bf_hi(bw.y)}; b1 = (f32x4){bf_lo(bw.z), bf_hi(bw.z), bf_lo(bw.w), bf_hi(bw.w)}; }
;                         const f32x4 v0 = b0 + acc[ai][bj][m][0], v1 = b1 + acc[ai][bj][m][1];
;                         ss += ((v0.x * v0.x + v0.y * v0.y) + (v0.z * v0.z + v0.w * v0.w)) + ((v1.x * v1.x + v1.y * v1.y) + (v1.z * v1.z + v1.w * v1.w));
;                         u32x4 w; w.x = cvt_pk_bf16(v0.x, v0.y); w.y = cvt_pk_bf16(v0.z, v0.w); w.z = cvt_pk_bf16(v1.x, v1.y); w.w = cvt_pk_bf16(v1.z, v1.w); EPI_ST((u32x4*)(xb + bj * 128), w); }
;                     if (SS) { ss += __shfl_xor(ss, 16); ss += __shfl_xor(ss, 32); if (fq == 0) SS[(size_t)row * 32 + u.pn * 4 + wc] = ss; } }
	v_pk_add_f32 v[108:109], v[108:109], v[60:61]
	v_pk_add_f32 v[110:111], v[110:111], v[62:63]
	v_pk_add_f32 v[104:105], v[104:105], v[56:57]
	v_pk_add_f32 v[106:107], v[106:107], v[58:59]
	v_pk_add_f32 v[100:101], v[100:101], v[28:29]
	v_pk_add_f32 v[102:103], v[102:103], v[30:31]
	v_pk_add_f32 v[96:97], v[96:97], v[24:25]
	v_pk_add_f32 v[98:99], v[98:99], v[26:27]
	v_mul_f32_e32 v250, v109, v109
	v_mul_f32_e32 v252, v111, v111
	v_fmac_f32_e32 v250, v108, v108
	v_fmac_f32_e32 v252, v110, v110
	v_mul_f32_e32 v253, v105, v105
	v_mul_f32_e32 v254, v107, v107
	v_add_f32_e32 v250, v250, v252
	v_fmac_f32_e32 v253, v104, v104
	v_fmac_f32_e32 v254, v106, v106
	v_add_f32_e32 v253, v253, v254
	v_add_f32_e32 v250, v250, v253
	v_mul_f32_e32 v251, v101, v101
	v_mul_f32_e32 v252, v103, v103
	v_fmac_f32_e32 v251, v100, v100
	v_fmac_f32_e32 v252, v102, v102
	v_mul_f32_e32 v253, v97, v97
	v_mul_f32_e32 v254, v99, v99
	v_add_f32_e32 v251, v251, v252
	v_fmac_f32_e32 v253, v96, v96
	v_fmac_f32_e32 v254, v98, v98
	v_add_f32_e32 v253, v253, v254
	v_add_f32_e32 v251, v251, v253
	v_cvt_pk_bf16_f32 v60, v108, v109
	v_cvt_pk_bf16_f32 v61, v110, v111
	v_cvt_pk_bf16_f32 v62, v104, v105
	v_cvt_pk_bf16_f32 v63, v106, v107
	v_cvt_pk_bf16_f32 v28, v100, v101
	v_cvt_pk_bf16_f32 v29, v102, v103
	v_cvt_pk_bf16_f32 v30, v96, v97
	v_cvt_pk_bf16_f32 v31, v98, v99
	v_add_f32_e32 v56, v250, v251
	s_add_u32 s98, s26, 0x90000
	s_addc_u32 s99, s27, 0
	global_store_dwordx4 v247, v[60:63], s[98:99]
	global_store_dwordx4 v247, v[28:31], s[98:99] offset:256
	s_waitcnt vmcnt(10)
	v_pk_add_f32 v[92:93], v[92:93], v[40:41]
	v_pk_add_f32 v[94:95], v[94:95], v[42:43]
	v_pk_add_f32 v[88:89], v[88:89], v[32:33]
	v_pk_add_f32 v[90:91], v[90:91], v[34:35]
	v_pk_add_f32 v[84:85], v[84:85], v[12:13]
	v_pk_add_f32 v[86:87], v[86:87], v[14:15]
	v_pk_add_f32 v[80:81], v[80:81], v[8:9]
	v_pk_add_f32 v[82:83], v[82:83], v[10:11]
	v_mul_f32_e32 v250, v93, v93
	v_mul_f32_e32 v252, v95, v95
	v_fmac_f32_e32 v250, v92, v92
	v_fmac_f32_e32 v252, v94, v94
	v_mul_f32_e32 v253, v89, v89
	v_mul_f32_e32 v254, v91, v91
	v_add_f32_e32 v250, v250, v252
	v_fmac_f32_e32 v253, v88, v88
	v_fmac_f32_e32 v254, v90, v90
	v_add_f32_e32 v253, v253, v254
	v_add_f32_e32 v250, v250, v253
	v_mul_f32_e32 v251, v85, v85
	v_mul_f32_e32 v252, v87, v87
	v_fmac_f32_e32 v251, v84, v84
	v_fmac_f32_e32 v252, v86, v86
	v_mul_f32_e32 v253, v81, v81
	v_mul_f32_e32 v254, v83, v83
	v_add_f32_e32 v251, v251, v252
	v_fmac_f32_e32 v253, v80, v80
	v_fmac_f32_e32 v254, v82, v82
	v_add_f32_e32 v253, v253, v254
	v_add_f32_e32 v251, v251, v253
	v_cvt_pk_bf16_f32 v40, v92, v93
	v_cvt_pk_bf16_f32 v41, v94, v95
	v_cvt_pk_bf16_f32 v42, v88, v89
	v_cvt_pk_bf16_f32 v43, v90, v91
	v_cvt_pk_bf16_f32 v12, v84, v85
	v_cvt_pk_bf16_f32 v13, v86, v87
	v_cvt_pk_bf16_f32 v14, v80, v81
	v_cvt_pk_bf16_f32 v15, v82, v83
	v_add_f32_e32 v32, v250, v251
	s_add_u32 s98, s26, 0xa0000
	s_addc_u32 s99, s27, 0
	global_store_dwordx4 v247, v[40:43], s[98:99]
	global_store_dwordx4 v247, v[12:15], s[98:99] offset:256
	s_waitcnt vmcnt(6)
	v_pk_add_f32 v[76:77], v[76:77], v[20:21]
	v_pk_add_f32 v[78:79], v[78:79], v[22:23]
	v_pk_add_f32 v[72:73], v[72:73], v[16:17]
	v_pk_add_f32 v[74:75], v[74:75], v[18:19]
	v_pk_add_f32 v[52:53], v[52:53], v[4:5]
	v_pk_add_f32 v[54:55], v[54:55], v[6:7]
	v_pk_add_f32 v[36:37], v[36:37], v[0:1]
	v_pk_add_f32 v[38:39], v[38:39], v[2:3]
	v_mul_f32_e32 v250, v77, v77
	v_mul_f32_e32 v252, v79, v79
	v_fmac_f32_e32 v250, v76, v76
	v_fmac_f32_e32 v252, v78, v78
	v_mul_f32_e32 v253, v73, v73
	v_mul_f32_e32 v254, v75, v75
	v_add_f32_e32 v250, v250, v252
	v_fmac_f32_e32 v253, v72, v72
	v_fmac_f32_e32 v254, v74, v74
	v_add_f32_e32 v253, v253, v254
	v_add_f32_e32 v250, v250, v253
	v_mul_f32_e32 v251, v53, v53
	v_mul_f32_e32 v252, v55, v55
	v_fmac_f32_e32 v251, v52, v52
	v_fmac_f32_e32 v252, v54, v54
	v_mul_f32_e32 v253, v37, v37
	v_mul_f32_e32 v254, v39, v39
	v_add_f32_e32 v251, v251, v252
	v_fmac_f32_e32 v253, v36, v36
	v_fmac_f32_e32 v254, v38, v38
	v_add_f32_e32 v253, v253, v254
	v_add_f32_e32 v251, v251, v253
	v_cvt_pk_bf16_f32 v20, v76, v77
	v_cvt_pk_bf16_f32 v21, v78, v79
	v_cvt_pk_bf16_f32 v22, v72, v73
	v_cvt_pk_bf16_f32 v23, v74, v75
	v_cvt_pk_bf16_f32 v4, v52, v53
	v_cvt_pk_bf16_f32 v5, v54, v55
	v_cvt_pk_bf16_f32 v6, v36, v37
	v_cvt_pk_bf16_f32 v7, v38, v39
	v_add_f32_e32 v16, v250, v251
	s_add_u32 s98, s26, 0xb0000
	s_addc_u32 s99, s27, 0
	global_store_dwordx4 v247, v[20:23], s[98:99]
	global_store_dwordx4 v247, v[4:7], s[98:99] offset:256
	ds_bpermute_b32 v133, v166, v132
	ds_bpermute_b32 v155, v166, v154
	ds_bpermute_b32 v187, v166, v186
	ds_bpermute_b32 v203, v166, v202
	ds_bpermute_b32 v65, v166, v64
	ds_bpermute_b32 v57, v166, v56
	ds_bpermute_b32 v33, v166, v32
	ds_bpermute_b32 v17, v166, v16
	v_cmp_eq_u32_e64 s[42:43], 0, v163
	s_waitcnt lgkmcnt(0)
	v_add_f32_e32 v132, v132, v133
	v_add_f32_e32 v154, v154, v155
	v_add_f32_e32 v186, v186, v187
	v_add_f32_e32 v202, v202, v203
	v_add_f32_e32 v64, v64, v65
	v_add_f32_e32 v56, v56, v57
	v_add_f32_e32 v32, v32, v33
	v_add_f32_e32 v16, v16, v17
	ds_bpermute_b32 v133, v167, v132
	ds_bpermute_b32 v155, v167, v154
	ds_bpermute_b32 v187, v167, v186
	ds_bpermute_b32 v203, v167, v202
	ds_bpermute_b32 v65, v167, v64
	ds_bpermute_b32 v57, v167, v56
	ds_bpermute_b32 v33, v167, v32
	ds_bpermute_b32 v17, v167, v16
	s_waitcnt lgkmcnt(0)
	v_add_f32_e32 v132, v132, v133
	v_add_f32_e32 v154, v154, v155
	v_add_f32_e32 v186, v186, v187
	v_add_f32_e32 v202, v202, v203
	v_add_f32_e32 v64, v64, v65
	v_add_f32_e32 v56, v56, v57
	v_add_f32_e32 v32, v32, v33
	v_add_f32_e32 v16, v16, v17
	s_and_saveexec_b64 s[6:7], s[42:43]
	global_store_dword v255, v132, s[100:101]
	s_add_u32 s98, s100, 0x800
	s_addc_u32 s99, s101, 0
	global_store_dword v255, v154, s[98:99]
	s_add_u32 s98, s100, 0x1000
	s_addc_u32 s99, s101, 0
	global_store_dword v255, v186, s[98:99]
	s_add_u32 s98, s100, 0x1800
	s_addc_u32 s99, s101, 0
	global_store_dword v255, v202, s[98:99]
	s_add_u32 s98, s100, 0x4000
	s_addc_u32 s99, s101, 0
	global_store_dword v255, v64, s[98:99]
	s_add_u32 s98, s100, 0x4800
	s_addc_u32 s99, s101, 0
	global_store_dword v255, v56, s[98:99]
	s_add_u32 s98, s100, 0x5000
	s_addc_u32 s99, s101, 0
	global_store_dword v255, v32, s[98:99]
	s_add_u32 s98, s100, 0x5800
	s_addc_u32 s99, s101, 0
	global_store_dword v255, v16, s[98:99]
	s_or_b64 exec, exec, s[6:7]
	s_branch .Lres1_done
; __device__ __forceinline__ unsigned cvt_pk_bf16(float lo, float hi) { unsigned r; asm volatile("v_cvt_pk_bf16_f32 %0, %1, %2" : "=v"(r) : "v"(lo), "v"(hi)); return r; }
; #define EPI_ST(p, v) __builtin_nontemporal_store((v), (p))
; __device__ __forceinline__ float bf_lo(unsigned w) { return __uint_as_float(w << 16); }
; __device__ __forceinline__ float bf_hi(unsigned w) { return __uint_as_float(w & 0xffff0000u); }
;     __device__ __forceinline__ void operator()(const f32x4 (&acc)[2][2][4][2], const pg8::Unit& u, int wr, int wc, int fr, int fq) const {
;     ...
;                 { bf16_t* xb = XB + (size_t)row * DM + col0; float ss = 0.f;
; #pragma unroll
;                     for (int bj = 0; bj < 2; ++bj) { f32x4 b0, b1;
;                         if (baseP) { const float* bp = baseP + (size_t)row * DM + col0 + bj * 128; b0 = *(const f32x4*)bp; b1 = *(const f32x4*)(bp + 4); }
;                         else { const u32x4 bw = *(const u32x4*)(xb + bj * 128); b0 = (f32x4){bf_lo(bw.x), bf_hi(bw.x), bf_lo(bw.y), bf_hi(bw.y)}; b1 = (f32x4){bf_lo(bw.z), bf_hi(bw.z), bf_lo(bw.w), bf_hi(bw.w)}; }
;                         const f32x4 v0 = b0 + acc[ai][bj][m][0], v1 = b1 + acc[ai][bj][m][1];
;                         ss += ((v0.x * v0.x + v0.y * v0.y) + (v0.z * v0.z + v0.w * v0.w)) + ((v1.x * v1.x + v1.y * v1.y) + (v1.z * v1.z + v1.w * v1.w));
;                         u32x4 w; w.x = cvt_pk_bf16(v0.x, v0.y); w.y = cvt_pk_bf16(v0.z, v0.w); w.z = cvt_pk_bf16(v1.x, v1.y); w.w = cvt_pk_bf16(v1.z, v1.w); EPI_ST((u32x4*)(xb + bj * 128), w); }
.Lres1_bf16:
	global_load_dwordx4 v[128:131], v247, s[26:27] nt
	global_load_dwordx4 v[132:135], v247, s[26:27] offset:256 nt
	s_add_u32 s98, s26, 0x10000
	s_addc_u32 s99, s27, 0
	global_load_dwordx4 v[142:145], v247, s[98:99] nt
	global_load_dwordx4 v[146:149], v247, s[98:99] offset:256 nt
	s_add_u32 s98, s26, 0x20000
	s_addc_u32 s99, s27, 0
	global_load_dwordx4 v[150:153], v247, s[98:99] nt
	global_load_dwordx4 v[154:157], v247, s[98:99] offset:256 nt
	s_add_u32 s98, s26, 0x30000
	s_addc_u32 s99, s27, 0
	global_load_dwordx4 v[158:161], v247, s[98:99] nt
	global_load_dwordx4 v[178:181], v247, s[98:99] offset:256 nt
	s_add_u32 s98, s26, 0x80000
	s_addc_u32 s99, s27, 0
	global_load_dwordx4 v[182:185], v247, s[98:99] nt
	global_load_dwordx4 v[186:189], v247, s[98:99] offset:256 nt
	s_add_u32 s98, s26, 0x90000
	s_addc_u32 s99, s27, 0
	global_load_dwordx4 v[190:193], v247, s[98:99] nt
	global_load_dwordx4 v[194:197], v247, s[98:99] offset:256 nt
	s_add_u32 s98, s26, 0xa0000
	s_addc_u32 s99, s27, 0
	global_load_dwordx4 v[198:201], v247, s[98:99] nt
	global_load_dwordx4 v[202:205], v247, s[98:99] offset:256 nt
	s_add_u32 s98, s26, 0xb0000
	s_addc_u32 s99, s27, 0
	global_load_dwordx4 v[206:209], v247, s[98:99] nt
	global_load_dwordx4 v[226:229], v247, s[98:99] offset:256 nt
	s_waitcnt vmcnt(14)
	v_lshlrev_b32_e32 v248, 16, v128
	v_and_b32_e32 v249, 0xffff0000, v128
	v_lshlrev_b32_e32 v250, 16, v129
	v_and_b32_e32 v251, 0xffff0000, v129
	v_pk_add_f32 v[68:69], v[68:69], v[248:249]
	v_pk_add_f32 v[70:71], v[70:71], v[250:251]
	v_lshlrev_b32_e32 v248, 16, v130
	v_and_b32_e32 v249, 0xffff0000, v130
	v_lshlrev_b32_e32 v250, 16, v131
	v_and_b32_e32 v251, 0xffff0000, v131
	v_pk_add_f32 v[64:65], v[64:65], v[248:249]
	v_pk_add_f32 v[66:67], v[66:67], v[250:251]
	v_lshlrev_b32_e32 v248, 16, v132
	v_and_b32_e32 v249, 0xffff0000, v132
	v_lshlrev_b32_e32 v250, 16, v133
	v_and_b32_e32 v251, 0xffff0000, v133
	v_pk_add_f32 v[48:49], v[48:49], v[248:249]
	v_pk_add_f32 v[50:51], v[50:51], v[250:251]
	v_lshlrev_b32_e32 v248, 16, v134
	v_and_b32_e32 v249, 0xffff0000, v134
	v_lshlrev_b32_e32 v250, 16, v135
	v_and_b32_e32 v251, 0xffff0000, v135
	v_pk_add_f32 v[44:45], v[44:45], v[248:249]
	v_pk_add_f32 v[46:47], v[46:47], v[250:251]
	v_mul_f32_e32 v250, v69, v69
	v_mul_f32_e32 v252, v71, v71
	v_fmac_f32_e32 v250, v68, v68
	v_fmac_f32_e32 v252, v70, v70
	v_mul_f32_e32 v253, v65, v65
	v_mul_f32_e32 v254, v67, v67
	v_add_f32_e32 v250, v250, v252
	v_fmac_f32_e32 v253, v64, v64
	v_fmac_f32_e32 v254, v66, v66
	v_add_f32_e32 v253, v253, v254
	v_add_f32_e32 v250, v250, v253
	v_mul_f32_e32 v251, v49, v49
	v_mul_f32_e32 v252, v51, v51
	v_fmac_f32_e32 v251, v48, v48
	v_fmac_f32_e32 v252, v50, v50
	v_mul_f32_e32 v253, v45, v45
	v_mul_f32_e32 v254, v47, v47
	v_add_f32_e32 v251, v251, v252
	v_fmac_f32_e32 v253, v44, v44
	v_fmac_f32_e32 v254, v46, v46
	v_add_f32_e32 v253, v253, v254
	v_add_f32_e32 v251, v251, v253
	v_cvt_pk_bf16_f32 v128, v68, v69
	v_cvt_pk_bf16_f32 v129, v70, v71
	v_cvt_pk_bf16_f32 v130, v64, v65
	v_cvt_pk_bf16_f32 v131, v66, v67
	v_cvt_pk_bf16_f32 v132, v48, v49
	v_cvt_pk_bf16_f32 v133, v50, v51
	v_cvt_pk_bf16_f32 v134, v44, v45
	v_cvt_pk_bf16_f32 v135, v46, v47
	v_add_f32_e32 v68, v250, v251
	global_store_dwordx4 v247, v[128:131], s[26:27]
	global_store_dwordx4 v247, v[132:135], s[26:27] offset:256
	s_waitcnt vmcnt(14)
	v_lshlrev_b32_e32 v248, 16, v142
	v_and_b32_e32 v249, 0xffff0000, v142
	v_lshlrev_b32_e32 v250, 16, v143
	v_and_b32_e32 v251, 0xffff0000, v143
	v_pk_add_f32 v[60:61], v[60:61], v[248:249]
	v_pk_add_f32 v[62:63], v[62:63], v[250:251]
	v_lshlrev_b32_e32 v248, 16, v144
	v_and_b32_e32 v249, 0xffff0000, v144
	v_lshlrev_b32_e32 v250, 16, v145
	v_and_b32_e32 v251, 0xffff0000, v145
	v_pk_add_f32 v[56:57], v[56:57], v[248:249]
	v_pk_add_f32 v[58:59], v[58:59], v[250:251]
	v_lshlrev_b32_e32 v248, 16, v146
	v_and_b32_e32 v249, 0xffff0000, v146
	v_lshlrev_b32_e32 v250, 16, v147
	v_and_b32_e32 v251, 0xffff0000, v147
	v_pk_add_f32 v[28:29], v[28:29], v[248:249]
	v_pk_add_f32 v[30:31], v[30:31], v[250:251]
	v_lshlrev_b32_e32 v248, 16, v148
	v_and_b32_e32 v249, 0xffff0000, v148
	v_lshlrev_b32_e32 v250, 16, v149
	v_and_b32_e32 v251, 0xffff0000, v149
	v_pk_add_f32 v[24:25], v[24:25], v[248:249]
	v_pk_add_f32 v[26:27], v[26:27], v[250:251]
	v_mul_f32_e32 v250, v61, v61
	v_mul_f32_e32 v252, v63, v63
	v_fmac_f32_e32 v250, v60, v60
	v_fmac_f32_e32 v252, v62, v62
	v_mul_f32_e32 v253, v57, v57
	v_mul_f32_e32 v254, v59, v59
	v_add_f32_e32 v250, v250, v252
	v_fmac_f32_e32 v253, v56, v56
	v_fmac_f32_e32 v254, v58, v58
	v_add_f32_e32 v253, v253, v254
	v_add_f32_e32 v250, v250, v253
	v_mul_f32_e32 v251, v29, v29
	v_mul_f32_e32 v252, v31, v31
	v_fmac_f32_e32 v251, v28, v28
	v_fmac_f32_e32 v252, v30, v30
	v_mul_f32_e32 v253, v25, v25
	v_mul_f32_e32 v254, v27, v27
	v_add_f32_e32 v251, v251, v252
	v_fmac_f32_e32 v253, v24, v24
	v_fmac_f32_e32 v254, v26, v26
	v_add_f32_e32 v253, v253, v254
	v_add_f32_e32 v251, v251, v253
	v_cvt_pk_bf16_f32 v142, v60, v61
	v_cvt_pk_bf16_f32 v143, v62, v63
	v_cvt_pk_bf16_f32 v144, v56, v57
	v_cvt_pk_bf16_f32 v145, v58, v59
	v_cvt_pk_bf16_f32 v146, v28, v29
	v_cvt_pk_bf16_f32 v147, v30, v31
	v_cvt_pk_bf16_f32 v148, v24, v25
	v_cvt_pk_bf16_f32 v149, v26, v27
	v_add_f32_e32 v60, v250, v251
	s_add_u32 s98, s26, 0x10000
	s_addc_u32 s99, s27, 0
	global_store_dwordx4 v247, v[142:145], s[98:99]
	global_store_dwordx4 v247, v[146:149], s[98:99] offset:256
	s_waitcnt vmcnt(14)
; __device__ __forceinline__ unsigned cvt_pk_bf16(float lo, float hi) { unsigned r; asm volatile("v_cvt_pk_bf16_f32 %0, %1, %2" : "=v"(r) : "v"(lo), "v"(hi)); return r; }
; #define EPI_ST(p, v) __builtin_nontemporal_store((v), (p))
; __device__ __forceinline__ float bf_lo(unsigned w) { return __uint_as_float(w << 16); }
; __device__ __forceinline__ float bf_hi(unsigned w) { return __uint_as_float(w & 0xffff0000u); }
;     __device__ __forceinline__ void operator()(const f32x4 (&acc)[2][2][4][2], const pg8::Unit& u, int wr, int wc, int fr, int fq) const {
;     ...
;                     for (int bj = 0; bj < 2; ++bj) { f32x4 b0, b1;
;                         if (baseP) { const float* bp = baseP + (size_t)row * DM + col0 + bj * 128; b0 = *(const f32x4*)bp; b1 = *(const f32x4*)(bp + 4); }
;                         else { const u32x4 bw = *(const u32x4*)(xb + bj * 128); b0 = (f32x4){bf_lo(bw.x), bf_hi(bw.x), bf_lo(bw.y), bf_hi(bw.y)}; b1 = (f32x4){bf_lo(bw.z), bf_hi(bw.z), bf_lo(bw.w), bf_hi(bw.w)}; }
;                         const f32x4 v0 = b0 + acc[ai][bj][m][0], v1 = b1 + acc[ai][bj][m][1];
;                         ss += ((v0.x * v0.x + v0.y * v0.y) + (v0.z * v0.z + v0.w * v0.w)) + ((v1.x * v1.x + v1.y * v1.y) + (v1.z * v1.z + v1.w * v1.w));
;                         u32x4 w; w.x = cvt_pk_bf16(v0.x, v0.y); w.y = cvt_pk_bf16(v0.z, v0.w); w.z = cvt_pk_bf16(v1.x, v1.y); w.w = cvt_pk_bf16(v1.z, v1.w); EPI_ST((u32x4*)(xb + bj * 128), w); }
	v_lshlrev_b32_e32 v248, 16, v150
	v_and_b32_e32 v249, 0xffff0000, v150
	v_lshlrev_b32_e32 v250, 16, v151
	v_and_b32_e32 v251, 0xffff0000, v151
	v_pk_add_f32 v[40:41], v[40:41], v[248:249]
	v_pk_add_f32 v[42:43], v[42:43], v[250:251]
	v_lshlrev_b32_e32 v248, 16, v152
	v_and_b32_e32 v249, 0xffff0000, v152
	v_lshlrev_b32_e32 v250, 16, v153
	v_and_b32_e32 v251, 0xffff0000, v153
	v_pk_add_f32 v[32:33], v[32:33], v[248:249]
	v_pk_add_f32 v[34:35], v[34:35], v[250:251]
	v_lshlrev_b32_e32 v248, 16, v154
	v_and_b32_e32 v249, 0xffff0000, v154
	v_lshlrev_b32_e32 v250, 16, v155
	v_and_b32_e32 v251, 0xffff0000, v155
	v_pk_add_f32 v[12:13], v[12:13], v[248:249]
	v_pk_add_f32 v[14:15], v[14:15], v[250:251]
	v_lshlrev_b32_e32 v248, 16, v156
	v_and_b32_e32 v249, 0xffff0000, v156
	v_lshlrev_b32_e32 v250, 16, v157
	v_and_b32_e32 v251, 0xffff0000, v157
	v_pk_add_f32 v[8:9], v[8:9], v[248:249]
	v_pk_add_f32 v[10:11], v[10:11], v[250:251]
	v_mul_f32_e32 v250, v41, v41
	v_mul_f32_e32 v252, v43, v43
	v_fmac_f32_e32 v250, v40, v40
	v_fmac_f32_e32 v252, v42, v42
	v_mul_f32_e32 v253, v33, v33
	v_mul_f32_e32 v254, v35, v35
	v_add_f32_e32 v250, v250, v252
	v_fmac_f32_e32 v253, v32, v32
	v_fmac_f32_e32 v254, v34, v34
	v_add_f32_e32 v253, v253, v254
	v_add_f32_e32 v250, v250, v253
	v_mul_f32_e32 v251, v13, v13
	v_mul_f32_e32 v252, v15, v15
	v_fmac_f32_e32 v251, v12, v12
	v_fmac_f32_e32 v252, v14, v14
	v_mul_f32_e32 v253, v9, v9
	v_mul_f32_e32 v254, v11, v11
	v_add_f32_e32 v251, v251, v252
	v_fmac_f32_e32 v253, v8, v8
	v_fmac_f32_e32 v254, v10, v10
	v_add_f32_e32 v253, v253, v254
	v_add_f32_e32 v251, v251, v253
	v_cvt_pk_bf16_f32 v150, v40, v41
	v_cvt_pk_bf16_f32 v151, v42, v43
	v_cvt_pk_bf16_f32 v152, v32, v33
	v_cvt_pk_bf16_f32 v153, v34, v35
	v_cvt_pk_bf16_f32 v154, v12, v13
	v_cvt_pk_bf16_f32 v155, v14, v15
	v_cvt_pk_bf16_f32 v156, v8, v9
	v_cvt_pk_bf16_f32 v157, v10, v11
	v_add_f32_e32 v40, v250, v251
	s_add_u32 s98, s26, 0x20000
	s_addc_u32 s99, s27, 0
	global_store_dwordx4 v247, v[150:153], s[98:99]
	global_store_dwordx4 v247, v[154:157], s[98:99] offset:256
	s_waitcnt vmcnt(14)
	v_lshlrev_b32_e32 v248, 16, v158
	v_and_b32_e32 v249, 0xffff0000, v158
	v_lshlrev_b32_e32 v250, 16, v159
	v_and_b32_e32 v251, 0xffff0000, v159
	v_pk_add_f32 v[20:21], v[20:21], v[248:249]
	v_pk_add_f32 v[22:23], v[22:23], v[250:251]
	v_lshlrev_b32_e32 v248, 16, v160
	v_and_b32_e32 v249, 0xffff0000, v160
	v_lshlrev_b32_e32 v250, 16, v161
	v_and_b32_e32 v251, 0xffff0000, v161
	v_pk_add_f32 v[16:17], v[16:17], v[248:249]
	v_pk_add_f32 v[18:19], v[18:19], v[250:251]
	v_lshlrev_b32_e32 v248, 16, v178
	v_and_b32_e32 v249, 0xffff0000, v178
	v_lshlrev_b32_e32 v250, 16, v179
	v_and_b32_e32 v251, 0xffff0000, v179
	v_pk_add_f32 v[4:5], v[4:5], v[248:249]
	v_pk_add_f32 v[6:7], v[6:7], v[250:251]
	v_lshlrev_b32_e32 v248, 16, v180
	v_and_b32_e32 v249, 0xffff0000, v180
	v_lshlrev_b32_e32 v250, 16, v181
	v_and_b32_e32 v251, 0xffff0000, v181
	v_pk_add_f32 v[0:1], v[0:1], v[248:249]
	v_pk_add_f32 v[2:3], v[2:3], v[250:251]
	v_mul_f32_e32 v250, v21, v21
	v_mul_f32_e32 v252, v23, v23
	v_fmac_f32_e32 v250, v20, v20
	v_fmac_f32_e32 v252, v22, v22
	v_mul_f32_e32 v253, v17, v17
	v_mul_f32_e32 v254, v19, v19
	v_add_f32_e32 v250, v250, v252
	v_fmac_f32_e32 v253, v16, v16
	v_fmac_f32_e32 v254, v18, v18
	v_add_f32_e32 v253, v253, v254
	v_add_f32_e32 v250, v250, v253
	v_mul_f32_e32 v251, v5, v5
	v_mul_f32_e32 v252, v7, v7
	v_fmac_f32_e32 v251, v4, v4
	v_fmac_f32_e32 v252, v6, v6
	v_mul_f32_e32 v253, v1, v1
	v_mul_f32_e32 v254, v3, v3
	v_add_f32_e32 v251, v251, v252
	v_fmac_f32_e32 v253, v0, v0
	v_fmac_f32_e32 v254, v2, v2
	v_add_f32_e32 v253, v253, v254
	v_add_f32_e32 v251, v251, v253
	v_cvt_pk_bf16_f32 v158, v20, v21
	v_cvt_pk_bf16_f32 v159, v22, v23
	v_cvt_pk_bf16_f32 v160, v16, v17
	v_cvt_pk_bf16_f32 v161, v18, v19
	v_cvt_pk_bf16_f32 v178, v4, v5
	v_cvt_pk_bf16_f32 v179, v6, v7
	v_cvt_pk_bf16_f32 v180, v0, v1
	v_cvt_pk_bf16_f32 v181, v2, v3
	v_add_f32_e32 v20, v250, v251
	s_add_u32 s98, s26, 0x30000
	s_addc_u32 s99, s27, 0
	global_store_dwordx4 v247, v[158:161], s[98:99]
	global_store_dwordx4 v247, v[178:181], s[98:99] offset:256
	s_waitcnt vmcnt(14)
	v_lshlrev_b32_e32 v248, 16, v182
	v_and_b32_e32 v249, 0xffff0000, v182
	v_lshlrev_b32_e32 v250, 16, v183
	v_and_b32_e32 v251, 0xffff0000, v183
	v_pk_add_f32 v[124:125], v[124:125], v[248:249]
	v_pk_add_f32 v[126:127], v[126:127], v[250:251]
	v_lshlrev_b32_e32 v248, 16, v184
	v_and_b32_e32 v249, 0xffff0000, v184
	v_lshlrev_b32_e32 v250, 16, v185
	v_and_b32_e32 v251, 0xffff0000, v185
	v_pk_add_f32 v[120:121], v[120:121], v[248:249]
	v_pk_add_f32 v[122:123], v[122:123], v[250:251]
	v_lshlrev_b32_e32 v248, 16, v186
	v_and_b32_e32 v249, 0xffff0000, v186
	v_lshlrev_b32_e32 v250, 16, v187
	v_and_b32_e32 v251, 0xffff0000, v187
	v_pk_add_f32 v[116:117], v[116:117], v[248:249]
	v_pk_add_f32 v[118:119], v[118:119], v[250:251]
	v_lshlrev_b32_e32 v248, 16, v188
	v_and_b32_e32 v249, 0xffff0000, v188
	v_lshlrev_b32_e32 v250, 16, v189
	v_and_b32_e32 v251, 0xffff0000, v189
	v_pk_add_f32 v[112:113], v[112:113], v[248:249]
	v_pk_add_f32 v[114:115], v[114:115], v[250:251]
	v_mul_f32_e32 v250, v125, v125
	v_mul_f32_e32 v252, v127, v127
	v_fmac_f32_e32 v250, v124, v124
	v_fmac_f32_e32 v252, v126, v126
	v_mul_f32_e32 v253, v121, v121
	v_mul_f32_e32 v254, v123, v123
	v_add_f32_e32 v250, v250, v252
	v_fmac_f32_e32 v253, v120, v120
	v_fmac_f32_e32 v254, v122, v122
	v_add_f32_e32 v253, v253, v254
	v_add_f32_e32 v250, v250, v253
	v_mul_f32_e32 v251, v117, v117
	v_mul_f32_e32 v252, v119, v119
	v_fmac_f32_e32 v251, v116, v116
	v_fmac_f32_e32 v252, v118, v118
	v_mul_f32_e32 v253, v113, v113
	v_mul_f32_e32 v254, v115, v115
	v_add_f32_e32 v251, v251, v252
	v_fmac_f32_e32 v253, v112, v112
	v_fmac_f32_e32 v254, v114, v114
	v_add_f32_e32 v253, v253, v254
	v_add_f32_e32 v251, v251, v253
	v_cvt_pk_bf16_f32 v182, v124, v125
	v_cvt_pk_bf16_f32 v183, v126, v127
	v_cvt_pk_bf16_f32 v184, v120, v121
	v_cvt_pk_bf16_f32 v185, v122, v123
	v_cvt_pk_bf16_f32 v186, v116, v117
	v_cvt_pk_bf16_f32 v187, v118, v119
	v_cvt_pk_bf16_f32 v188, v112, v113
	v_cvt_pk_bf16_f32 v189, v114, v115
	v_add_f32_e32 v124, v250, v251
	s_add_u32 s98, s26, 0x80000
	s_addc_u32 s99, s27, 0
	global_store_dwordx4 v247, v[182:185], s[98:99]
	global_store_dwordx4 v247, v[186:189], s[98:99] offset:256
	s_waitcnt vmcnt(14)
; __device__ __forceinline__ unsigned cvt_pk_bf16(float lo, float hi) { unsigned r; asm volatile("v_cvt_pk_bf16_f32 %0, %1, %2" : "=v"(r) : "v"(lo), "v"(hi)); return r; }
; #define EPI_ST(p, v) __builtin_nontemporal_store((v), (p))
; __device__ __forceinline__ float bf_lo(unsigned w) { return __uint_as_float(w << 16); }
; __device__ __forceinline__ float bf_hi(unsigned w) { return __uint_as_float(w & 0xffff0000u); }
;     __device__ __forceinline__ void operator()(const f32x4 (&acc)[2][2][4][2], const pg8::Unit& u, int wr, int wc, int fr, int fq) const {
;     ...
;                     for (int bj = 0; bj < 2; ++bj) { f32x4 b0, b1;
;                         if (baseP) { const float* bp = baseP + (size_t)row * DM + col0 + bj * 128; b0 = *(const f32x4*)bp; b1 = *(const f32x4*)(bp + 4); }
;                         else { const u32x4 bw = *(const u32x4*)(xb + bj * 128); b0 = (f32x4){bf_lo(bw.x), bf_hi(bw.x), bf_lo(bw.y), bf_hi(bw.y)}; b1 = (f32x4){bf_lo(bw.z), bf_hi(bw.z), bf_lo(bw.w), bf_hi(bw.w)}; }
;                         const f32x4 v0 = b0 + acc[ai][bj][m][0], v1 = b1 + acc[ai][bj][m][1];
;                         ss += ((v0.x * v0.x + v0.y * v0.y) + (v0.z * v0.z + v0.w * v0.w)) + ((v1.x * v1.x + v1.y * v1.y) + (v1.z * v1.z + v1.w * v1.w));
;                         u32x4 w; w.x = cvt_pk_bf16(v0.x, v0.y); w.y = cvt_pk_bf16(v0.z, v0.w); w.z = cvt_pk_bf16(v1.x, v1.y); w.w = cvt_pk_bf16(v1.z, v1.w); EPI_ST((u32x4*)(xb + bj * 128), w); }
	v_lshlrev_b32_e32 v248, 16, v190
	v_and_b32_e32 v249, 0xffff0000, v190
	v_lshlrev_b32_e32 v250, 16, v191
	v_and_b32_e32 v251, 0xffff0000, v191
	v_pk_add_f32 v[108:109], v[108:109], v[248:249]
	v_pk_add_f32 v[110:111], v[110:111], v[250:251]
	v_lshlrev_b32_e32 v248, 16, v192
	v_and_b32_e32 v249, 0xffff0000, v192
	v_lshlrev_b32_e32 v250, 16, v193
	v_and_b32_e32 v251, 0xffff0000, v193
	v_pk_add_f32 v[104:105], v[104:105], v[248:249]
	v_pk_add_f32 v[106:107], v[106:107], v[250:251]
	v_lshlrev_b32_e32 v248, 16, v194
	v_and_b32_e32 v249, 0xffff0000, v194
	v_lshlrev_b32_e32 v250, 16, v195
	v_and_b32_e32 v251, 0xffff0000, v195
	v_pk_add_f32 v[100:101], v[100:101], v[248:249]
	v_pk_add_f32 v[102:103], v[102:103], v[250:251]
	v_lshlrev_b32_e32 v248, 16, v196
	v_and_b32_e32 v249, 0xffff0000, v196
	v_lshlrev_b32_e32 v250, 16, v197
	v_and_b32_e32 v251, 0xffff0000, v197
	v_pk_add_f32 v[96:97], v[96:97], v[248:249]
	v_pk_add_f32 v[98:99], v[98:99], v[250:251]
	v_mul_f32_e32 v250, v109, v109
	v_mul_f32_e32 v252, v111, v111
	v_fmac_f32_e32 v250, v108, v108
	v_fmac_f32_e32 v252, v110, v110
	v_mul_f32_e32 v253, v105, v105
	v_mul_f32_e32 v254, v107, v107
	v_add_f32_e32 v250, v250, v252
	v_fmac_f32_e32 v253, v104, v104
	v_fmac_f32_e32 v254, v106, v106
	v_add_f32_e32 v253, v253, v254
	v_add_f32_e32 v250, v250, v253
	v_mul_f32_e32 v251, v101, v101
	v_mul_f32_e32 v252, v103, v103
	v_fmac_f32_e32 v251, v100, v100
	v_fmac_f32_e32 v252, v102, v102
	v_mul_f32_e32 v253, v97, v97
	v_mul_f32_e32 v254, v99, v99
	v_add_f32_e32 v251, v251, v252
	v_fmac_f32_e32 v253, v96, v96
	v_fmac_f32_e32 v254, v98, v98
	v_add_f32_e32 v253, v253, v254
	v_add_f32_e32 v251, v251, v253
	v_cvt_pk_bf16_f32 v190, v108, v109
	v_cvt_pk_bf16_f32 v191, v110, v111
	v_cvt_pk_bf16_f32 v192, v104, v105
	v_cvt_pk_bf16_f32 v193, v106, v107
	v_cvt_pk_bf16_f32 v194, v100, v101
	v_cvt_pk_bf16_f32 v195, v102, v103
	v_cvt_pk_bf16_f32 v196, v96, v97
	v_cvt_pk_bf16_f32 v197, v98, v99
	v_add_f32_e32 v108, v250, v251
	s_add_u32 s98, s26, 0x90000
	s_addc_u32 s99, s27, 0
	global_store_dwordx4 v247, v[190:193], s[98:99]
	global_store_dwordx4 v247, v[194:197], s[98:99] offset:256
	s_waitcnt vmcnt(14)
	v_lshlrev_b32_e32 v248, 16, v198
	v_and_b32_e32 v249, 0xffff0000, v198
	v_lshlrev_b32_e32 v250, 16, v199
	v_and_b32_e32 v251, 0xffff0000, v199
	v_pk_add_f32 v[92:93], v[92:93], v[248:249]
	v_pk_add_f32 v[94:95], v[94:95], v[250:251]
	v_lshlrev_b32_e32 v248, 16, v200
	v_and_b32_e32 v249, 0xffff0000, v200
	v_lshlrev_b32_e32 v250, 16, v201
	v_and_b32_e32 v251, 0xffff0000, v201
	v_pk_add_f32 v[88:89], v[88:89], v[248:249]
	v_pk_add_f32 v[90:91], v[90:91], v[250:251]
	v_lshlrev_b32_e32 v248, 16, v202
	v_and_b32_e32 v249, 0xffff0000, v202
	v_lshlrev_b32_e32 v250, 16, v203
	v_and_b32_e32 v251, 0xffff0000, v203
	v_pk_add_f32 v[84:85], v[84:85], v[248:249]
	v_pk_add_f32 v[86:87], v[86:87], v[250:251]
	v_lshlrev_b32_e32 v248, 16, v204
	v_and_b32_e32 v249, 0xffff0000, v204
	v_lshlrev_b32_e32 v250, 16, v205
	v_and_b32_e32 v251, 0xffff0000, v205
	v_pk_add_f32 v[80:81], v[80:81], v[248:249]
	v_pk_add_f32 v[82:83], v[82:83], v[250:251]
	v_mul_f32_e32 v250, v93, v93
	v_mul_f32_e32 v252, v95, v95
	v_fmac_f32_e32 v250, v92, v92
	v_fmac_f32_e32 v252, v94, v94
	v_mul_f32_e32 v253, v89, v89
	v_mul_f32_e32 v254, v91, v91
	v_add_f32_e32 v250, v250, v252
	v_fmac_f32_e32 v253, v88, v88
	v_fmac_f32_e32 v254, v90, v90
	v_add_f32_e32 v253, v253, v254
	v_add_f32_e32 v250, v250, v253
	v_mul_f32_e32 v251, v85, v85
	v_mul_f32_e32 v252, v87, v87
	v_fmac_f32_e32 v251, v84, v84
	v_fmac_f32_e32 v252, v86, v86
	v_mul_f32_e32 v253, v81, v81
	v_mul_f32_e32 v254, v83, v83
	v_add_f32_e32 v251, v251, v252
	v_fmac_f32_e32 v253, v80, v80
	v_fmac_f32_e32 v254, v82, v82
	v_add_f32_e32 v253, v253, v254
	v_add_f32_e32 v251, v251, v253
	v_cvt_pk_bf16_f32 v198, v92, v93
	v_cvt_pk_bf16_f32 v199, v94, v95
	v_cvt_pk_bf16_f32 v200, v88, v89
	v_cvt_pk_bf16_f32 v201, v90, v91
	v_cvt_pk_bf16_f32 v202, v84, v85
	v_cvt_pk_bf16_f32 v203, v86, v87
	v_cvt_pk_bf16_f32 v204, v80, v81
	v_cvt_pk_bf16_f32 v205, v82, v83
	v_add_f32_e32 v92, v250, v251
	s_add_u32 s98, s26, 0xa0000
	s_addc_u32 s99, s27, 0
	global_store_dwordx4 v247, v[198:201], s[98:99]
	global_store_dwordx4 v247, v[202:205], s[98:99] offset:256
	s_waitcnt vmcnt(14)
; __device__ __forceinline__ unsigned cvt_pk_bf16(float lo, float hi) { unsigned r; asm volatile("v_cvt_pk_bf16_f32 %0, %1, %2" : "=v"(r) : "v"(lo), "v"(hi)); return r; }
; #define EPI_ST(p, v) __builtin_nontemporal_store((v), (p))
; __device__ __forceinline__ float bf_lo(unsigned w) { return __uint_as_float(w << 16); }
; __device__ __forceinline__ float bf_hi(unsigned w) { return __uint_as_float(w & 0xffff0000u); }
;     __device__ __forceinline__ void operator()(const f32x4 (&acc)[2][2][4][2], const pg8::Unit& u, int wr, int wc, int fr, int fq) const {
;     ...
;                     for (int bj = 0; bj < 2; ++bj) { f32x4 b0, b1;
;                         if (baseP) { const float* bp = baseP + (size_t)row * DM + col0 + bj * 128; b0 = *(const f32x4*)bp; b1 = *(const f32x4*)(bp + 4); }
;                         else { const u32x4 bw = *(const u32x4*)(xb + bj * 128); b0 = (f32x4){bf_lo(bw.x), bf_hi(bw.x), bf_lo(bw.y), bf_hi(bw.y)}; b1 = (f32x4){bf_lo(bw.z), bf_hi(bw.z), bf_lo(bw.w), bf_hi(bw.w)}; }
;                         const f32x4 v0 = b0 + acc[ai][bj][m][0], v1 = b1 + acc[ai][bj][m][1];
;                         ss += ((v0.x * v0.x + v0.y * v0.y) + (v0.z * v0.z + v0.w * v0.w)) + ((v1.x * v1.x + v1.y * v1.y) + (v1.z * v1.z + v1.w * v1.w));
;                         u32x4 w; w.x = cvt_pk_bf16(v0.x, v0.y); w.y = cvt_pk_bf16(v0.z, v0.w); w.z = cvt_pk_bf16(v1.x, v1.y); w.w = cvt_pk_bf16(v1.z, v1.w); EPI_ST((u32x4*)(xb + bj * 128), w); }
;                     if (SS) { ss += __shfl_xor(ss, 16); ss += __shfl_xor(ss, 32); if (fq == 0) SS[(size_t)row * 32 + u.pn * 4 + wc] = ss; } }
	v_lshlrev_b32_e32 v248, 16, v206
	v_and_b32_e32 v249, 0xffff0000, v206
	v_lshlrev_b32_e32 v250, 16, v207
	v_and_b32_e32 v251, 0xffff0000, v207
	v_pk_add_f32 v[76:77], v[76:77], v[248:249]
	v_pk_add_f32 v[78:79], v[78:79], v[250:251]
	v_lshlrev_b32_e32 v248, 16, v208
	v_and_b32_e32 v249, 0xffff0000, v208
	v_lshlrev_b32_e32 v250, 16, v209
	v_and_b32_e32 v251, 0xffff0000, v209
	v_pk_add_f32 v[72:73], v[72:73], v[248:249]
	v_pk_add_f32 v[74:75], v[74:75], v[250:251]
	v_lshlrev_b32_e32 v248, 16, v226
	v_and_b32_e32 v249, 0xffff0000, v226
	v_lshlrev_b32_e32 v250, 16, v227
	v_and_b32_e32 v251, 0xffff0000, v227
	v_pk_add_f32 v[52:53], v[52:53], v[248:249]
	v_pk_add_f32 v[54:55], v[54:55], v[250:251]
	v_lshlrev_b32_e32 v248, 16, v228
	v_and_b32_e32 v249, 0xffff0000, v228
	v_lshlrev_b32_e32 v250, 16, v229
	v_and_b32_e32 v251, 0xffff0000, v229
	v_pk_add_f32 v[36:37], v[36:37], v[248:249]
	v_pk_add_f32 v[38:39], v[38:39], v[250:251]
	v_mul_f32_e32 v250, v77, v77
	v_mul_f32_e32 v252, v79, v79
	v_fmac_f32_e32 v250, v76, v76
	v_fmac_f32_e32 v252, v78, v78
	v_mul_f32_e32 v253, v73, v73
	v_mul_f32_e32 v254, v75, v75
	v_add_f32_e32 v250, v250, v252
	v_fmac_f32_e32 v253, v72, v72
	v_fmac_f32_e32 v254, v74, v74
	v_add_f32_e32 v253, v253, v254
	v_add_f32_e32 v250, v250, v253
	v_mul_f32_e32 v251, v53, v53
	v_mul_f32_e32 v252, v55, v55
	v_fmac_f32_e32 v251, v52, v52
	v_fmac_f32_e32 v252, v54, v54
	v_mul_f32_e32 v253, v37, v37
	v_mul_f32_e32 v254, v39, v39
	v_add_f32_e32 v251, v251, v252
	v_fmac_f32_e32 v253, v36, v36
	v_fmac_f32_e32 v254, v38, v38
	v_add_f32_e32 v253, v253, v254
	v_add_f32_e32 v251, v251, v253
	v_cvt_pk_bf16_f32 v206, v76, v77
	v_cvt_pk_bf16_f32 v207, v78, v79
	v_cvt_pk_bf16_f32 v208, v72, v73
	v_cvt_pk_bf16_f32 v209, v74, v75
	v_cvt_pk_bf16_f32 v226, v52, v53
	v_cvt_pk_bf16_f32 v227, v54, v55
	v_cvt_pk_bf16_f32 v228, v36, v37
	v_cvt_pk_bf16_f32 v229, v38, v39
	v_add_f32_e32 v76, v250, v251
	s_add_u32 s98, s26, 0xb0000
	s_addc_u32 s99, s27, 0
	global_store_dwordx4 v247, v[206:209], s[98:99]
	global_store_dwordx4 v247, v[226:229], s[98:99] offset:256
	ds_bpermute_b32 v69, v166, v68
	ds_bpermute_b32 v61, v166, v60
	ds_bpermute_b32 v41, v166, v40
	ds_bpermute_b32 v21, v166, v20
	ds_bpermute_b32 v125, v166, v124
	ds_bpermute_b32 v109, v166, v108
	ds_bpermute_b32 v93, v166, v92
	ds_bpermute_b32 v77, v166, v76
	v_cmp_eq_u32_e64 s[42:43], 0, v163
	s_waitcnt lgkmcnt(0)
	v_add_f32_e32 v68, v68, v69
	v_add_f32_e32 v60, v60, v61
	v_add_f32_e32 v40, v40, v41
	v_add_f32_e32 v20, v20, v21
	v_add_f32_e32 v124, v124, v125
	v_add_f32_e32 v108, v108, v109
	v_add_f32_e32 v92, v92, v93
	v_add_f32_e32 v76, v76, v77
	ds_bpermute_b32 v69, v167, v68
	ds_bpermute_b32 v61, v167, v60
	ds_bpermute_b32 v41, v167, v40
	ds_bpermute_b32 v21, v167, v20
	ds_bpermute_b32 v125, v167, v124
	ds_bpermute_b32 v109, v167, v108
	ds_bpermute_b32 v93, v167, v92
	ds_bpermute_b32 v77, v167, v76
	s_waitcnt lgkmcnt(0)
	v_add_f32_e32 v68, v68, v69
	v_add_f32_e32 v60, v60, v61
	v_add_f32_e32 v40, v40, v41
	v_add_f32_e32 v20, v20, v21
	v_add_f32_e32 v124, v124, v125
	v_add_f32_e32 v108, v108, v109
	v_add_f32_e32 v92, v92, v93
	v_add_f32_e32 v76, v76, v77
	s_and_saveexec_b64 s[6:7], s[42:43]
	global_store_dword v255, v68, s[100:101]
	s_add_u32 s98, s100, 0x800
	s_addc_u32 s99, s101, 0
	global_store_dword v255, v60, s[98:99]
	s_add_u32 s98, s100, 0x1000
	s_addc_u32 s99, s101, 0
	global_store_dword v255, v40, s[98:99]
	s_add_u32 s98, s100, 0x1800
	s_addc_u32 s99, s101, 0
	global_store_dword v255, v20, s[98:99]
	s_add_u32 s98, s100, 0x4000
	s_addc_u32 s99, s101, 0
	global_store_dword v255, v124, s[98:99]
	s_add_u32 s98, s100, 0x4800
	s_addc_u32 s99, s101, 0
	global_store_dword v255, v108, s[98:99]
	s_add_u32 s98, s100, 0x5000
	s_addc_u32 s99, s101, 0
	global_store_dword v255, v92, s[98:99]
	s_add_u32 s98, s100, 0x5800
	s_addc_u32 s99, s101, 0
	global_store_dword v255, v76, s[98:99]
	s_or_b64 exec, exec, s[6:7]

; __device__ __forceinline__ unsigned cvt_pk_bf16(float lo, float hi) { unsigned r; asm volatile("v_cvt_pk_bf16_f32 %0, %1, %2" : "=v"(r) : "v"(lo), "v"(hi)); return r; }
; __device__ __forceinline__ void row_bf16_ss(const float* xrow, bf16_t* orow, float* ss, int lane) {
;     const f32x4* xr = (const f32x4*)xrow + lane; f32x4 v[8]; float s = 0.f;
; #pragma unroll
;     for (int j = 0; j < 8; ++j) { v[j] = xr[64 * j]; s += (v[j].x * v[j].x + v[j].y * v[j].y) + (v[j].z * v[j].z + v[j].w * v[j].w); }
;     s = wave_sum(s); u32x2* o8 = (u32x2*)orow + lane;
; #pragma unroll
;     for (int j = 0; j < 8; ++j) { u32x2 w; w.x = cvt_pk_bf16(v[j].x, v[j].y); w.y = cvt_pk_bf16(v[j].z, v[j].w); o8[64 * j] = w; }
;     if (lane == 0) *ss = s;
; }
; __device__ __forceinline__ void sample_assemble(const float* base, const float* XSP, int nsp, int s, float* xr, int lane) {
;     const f32x4* br = (const f32x4*)base + lane; f32x4* o = (f32x4*)xr + lane;
; #pragma unroll
;     for (int j = 0; j < 8; ++j) { f32x4 v = br[64 * j];
;         for (int sp = 0; sp < nsp; ++sp) v += *((const f32x4*)(XSP + ((size_t)sp * NS + s) * DM) + lane + 64 * j);
;         o[64 * j] = v; }
; }
.LBB0_721:
	v_readfirstlane_b32 s98, v34
	v_readfirstlane_b32 s99, v35
	v_readfirstlane_b32 s100, v32
	v_readfirstlane_b32 s101, v33
	s_add_u32 s98, s98, s6
	s_addc_u32 s99, s99, s7
	s_add_u32 s100, s100, s30
	s_addc_u32 s101, s101, s31
	v_add_u32_e32 v0, 0x1000, v168
	global_load_dwordx4 v[82:85], v168, s[28:29] nt
	global_load_dwordx4 v[86:89], v168, s[98:99] nt
	s_add_u32 s6, s98, 0x100000
	s_addc_u32 s7, s99, 0
	global_load_dwordx4 v[90:93], v168, s[6:7] nt
	s_add_u32 s6, s98, 0x200000
	s_addc_u32 s7, s99, 0
	global_load_dwordx4 v[94:97], v168, s[6:7] nt
	s_add_u32 s6, s98, 0x300000
	s_addc_u32 s7, s99, 0
	global_load_dwordx4 v[98:101], v168, s[6:7] nt
	s_add_u32 s6, s98, 0x400000
	s_addc_u32 s7, s99, 0
	global_load_dwordx4 v[102:105], v168, s[6:7] nt
	s_add_u32 s6, s98, 0x500000
	s_addc_u32 s7, s99, 0
	global_load_dwordx4 v[128:131], v168, s[6:7] nt
	s_add_u32 s6, s98, 0x600000
	s_addc_u32 s7, s99, 0
	global_load_dwordx4 v[132:135], v168, s[6:7] nt
	s_add_u32 s6, s98, 0x700000
	s_addc_u32 s7, s99, 0
	global_load_dwordx4 v[136:139], v168, s[6:7] nt
	global_load_dwordx4 v[140:143], v168, s[28:29] offset:1024 nt
	global_load_dwordx4 v[144:147], v168, s[98:99] offset:1024 nt
	s_add_u32 s6, s98, 0x100000
	s_addc_u32 s7, s99, 0
	global_load_dwordx4 v[148:151], v168, s[6:7] offset:1024 nt
	s_add_u32 s6, s98, 0x200000
	s_addc_u32 s7, s99, 0
	global_load_dwordx4 v[152:155], v168, s[6:7] offset:1024 nt
	s_add_u32 s6, s98, 0x300000
	s_addc_u32 s7, s99, 0
	global_load_dwordx4 v[156:159], v168, s[6:7] offset:1024 nt
	s_add_u32 s6, s98, 0x400000
	s_addc_u32 s7, s99, 0
	global_load_dwordx4 v[160:163], v168, s[6:7] offset:1024 nt
	s_add_u32 s6, s98, 0x500000
	s_addc_u32 s7, s99, 0
	global_load_dwordx4 v[164:167], v168, s[6:7] offset:1024 nt
	s_add_u32 s6, s98, 0x600000
	s_addc_u32 s7, s99, 0
	global_load_dwordx4 v[178:181], v168, s[6:7] offset:1024 nt
	s_add_u32 s6, s98, 0x700000
	s_addc_u32 s7, s99, 0
	global_load_dwordx4 v[182:185], v168, s[6:7] offset:1024 nt
	global_load_dwordx4 v[186:189], v168, s[28:29] offset:2048 nt
	global_load_dwordx4 v[190:193], v168, s[98:99] offset:2048 nt
	s_add_u32 s6, s98, 0x100000
	s_addc_u32 s7, s99, 0
	global_load_dwordx4 v[194:197], v168, s[6:7] offset:2048 nt
	s_add_u32 s6, s98, 0x200000
	s_addc_u32 s7, s99, 0
	global_load_dwordx4 v[198:201], v168, s[6:7] offset:2048 nt
	s_add_u32 s6, s98, 0x300000
	s_addc_u32 s7, s99, 0
	global_load_dwordx4 v[202:205], v168, s[6:7] offset:2048 nt
	s_add_u32 s6, s98, 0x400000
	s_addc_u32 s7, s99, 0
	global_load_dwordx4 v[206:209], v168, s[6:7] offset:2048 nt
	s_add_u32 s6, s98, 0x500000
	s_addc_u32 s7, s99, 0
	global_load_dwordx4 v[226:229], v168, s[6:7] offset:2048 nt
	s_add_u32 s6, s98, 0x600000
	s_addc_u32 s7, s99, 0
	global_load_dwordx4 v[230:233], v168, s[6:7] offset:2048 nt
	s_add_u32 s6, s98, 0x700000
	s_addc_u32 s7, s99, 0
	global_load_dwordx4 v[234:237], v168, s[6:7] offset:2048 nt
	s_waitcnt vmcnt(18)
	v_pk_add_f32 v[2:3], v[82:83], v[86:87]
	v_pk_add_f32 v[4:5], v[84:85], v[88:89]
	v_pk_add_f32 v[2:3], v[2:3], v[90:91]
	v_pk_add_f32 v[4:5], v[4:5], v[92:93]
	v_pk_add_f32 v[2:3], v[2:3], v[94:95]
	v_pk_add_f32 v[4:5], v[4:5], v[96:97]
	v_pk_add_f32 v[2:3], v[2:3], v[98:99]
	v_pk_add_f32 v[4:5], v[4:5], v[100:101]
	v_pk_add_f32 v[2:3], v[2:3], v[102:103]
	v_pk_add_f32 v[4:5], v[4:5], v[104:105]
	v_pk_add_f32 v[2:3], v[2:3], v[128:129]
	v_pk_add_f32 v[4:5], v[4:5], v[130:131]
	v_pk_add_f32 v[2:3], v[2:3], v[132:133]
	v_pk_add_f32 v[4:5], v[4:5], v[134:135]
	v_pk_add_f32 v[2:3], v[2:3], v[136:137]
	v_pk_add_f32 v[4:5], v[4:5], v[138:139]
	global_store_dwordx4 v168, v[2:5], s[100:101]
	global_load_dwordx4 v[82:85], v168, s[28:29] offset:3072 nt
	global_load_dwordx4 v[86:89], v168, s[98:99] offset:3072 nt
	s_add_u32 s6, s98, 0x100000
	s_addc_u32 s7, s99, 0
	global_load_dwordx4 v[90:93], v168, s[6:7] offset:3072 nt
	s_add_u32 s6, s98, 0x200000
	s_addc_u32 s7, s99, 0
	global_load_dwordx4 v[94:97], v168, s[6:7] offset:3072 nt
	s_add_u32 s6, s98, 0x300000
	s_addc_u32 s7, s99, 0
	global_load_dwordx4 v[98:101], v168, s[6:7] offset:3072 nt
	s_add_u32 s6, s98, 0x400000
	s_addc_u32 s7, s99, 0
	global_load_dwordx4 v[102:105], v168, s[6:7] offset:3072 nt
	s_add_u32 s6, s98, 0x500000
	s_addc_u32 s7, s99, 0
	global_load_dwordx4 v[128:131], v168, s[6:7] offset:3072 nt
	s_add_u32 s6, s98, 0x600000
	s_addc_u32 s7, s99, 0
	global_load_dwordx4 v[132:135], v168, s[6:7] offset:3072 nt
	s_add_u32 s6, s98, 0x700000
	s_addc_u32 s7, s99, 0
	global_load_dwordx4 v[136:139], v168, s[6:7] offset:3072 nt
	s_waitcnt vmcnt(19)
	v_pk_add_f32 v[6:7], v[140:141], v[144:145]
	v_pk_add_f32 v[8:9], v[142:143], v[146:147]
	v_pk_add_f32 v[6:7], v[6:7], v[148:149]
	v_pk_add_f32 v[8:9], v[8:9], v[150:151]
	v_pk_add_f32 v[6:7], v[6:7], v[152:153]
	v_pk_add_f32 v[8:9], v[8:9], v[154:155]
	v_pk_add_f32 v[6:7], v[6:7], v[156:157]
	v_pk_add_f32 v[8:9], v[8:9], v[158:159]
	v_pk_add_f32 v[6:7], v[6:7], v[160:161]
	v_pk_add_f32 v[8:9], v[8:9], v[162:163]
	v_pk_add_f32 v[6:7], v[6:7], v[164:165]
	v_pk_add_f32 v[8:9], v[8:9], v[166:167]
	v_pk_add_f32 v[6:7], v[6:7], v[178:179]
	v_pk_add_f32 v[8:9], v[8:9], v[180:181]
	v_pk_add_f32 v[6:7], v[6:7], v[182:183]
	v_pk_add_f32 v[8:9], v[8:9], v[184:185]
	global_store_dwordx4 v168, v[6:9], s[100:101] offset:1024
	global_load_dwordx4 v[140:143], v0, s[28:29] nt
	global_load_dwordx4 v[144:147], v0, s[98:99] nt
	s_add_u32 s6, s98, 0x100000
	s_addc_u32 s7, s99, 0
	global_load_dwordx4 v[148:151], v0, s[6:7] nt
	s_add_u32 s6, s98, 0x200000
	s_addc_u32 s7, s99, 0
	global_load_dwordx4 v[152:155], v0, s[6:7] nt
	s_add_u32 s6, s98, 0x300000
	s_addc_u32 s7, s99, 0
	global_load_dwordx4 v[156:159], v0, s[6:7] nt
	s_add_u32 s6, s98, 0x400000
	s_addc_u32 s7, s99, 0
	global_load_dwordx4 v[160:163], v0, s[6:7] nt
	s_add_u32 s6, s98, 0x500000
	s_addc_u32 s7, s99, 0
	global_load_dwordx4 v[164:167], v0, s[6:7] nt
	s_add_u32 s6, s98, 0x600000
	s_addc_u32 s7, s99, 0
	global_load_dwordx4 v[178:181], v0, s[6:7] nt
	s_add_u32 s6, s98, 0x700000
	s_addc_u32 s7, s99, 0
	global_load_dwordx4 v[182:185], v0, s[6:7] nt
	s_waitcnt vmcnt(20)
; __device__ __forceinline__ void sample_assemble(const float* base, const float* XSP, int nsp, int s, float* xr, int lane) {
;     const f32x4* br = (const f32x4*)base + lane; f32x4* o = (f32x4*)xr + lane;
; #pragma unroll
;     for (int j = 0; j < 8; ++j) { f32x4 v = br[64 * j];
;         for (int sp = 0; sp < nsp; ++sp) v += *((const f32x4*)(XSP + ((size_t)sp * NS + s) * DM) + lane + 64 * j);
;         o[64 * j] = v; }
; }
	v_pk_add_f32 v[10:11], v[186:187], v[190:191]
	v_pk_add_f32 v[12:13], v[188:189], v[192:193]
	v_pk_add_f32 v[10:11], v[10:11], v[194:195]
	v_pk_add_f32 v[12:13], v[12:13], v[196:197]
	v_pk_add_f32 v[10:11], v[10:11], v[198:199]
	v_pk_add_f32 v[12:13], v[12:13], v[200:201]
	v_pk_add_f32 v[10:11], v[10:11], v[202:203]
	v_pk_add_f32 v[12:13], v[12:13], v[204:205]
	v_pk_add_f32 v[10:11], v[10:11], v[206:207]
	v_pk_add_f32 v[12:13], v[12:13], v[208:209]
	v_pk_add_f32 v[10:11], v[10:11], v[226:227]
	v_pk_add_f32 v[12:13], v[12:13], v[228:229]
	v_pk_add_f32 v[10:11], v[10:11], v[230:231]
	v_pk_add_f32 v[12:13], v[12:13], v[232:233]
	v_pk_add_f32 v[10:11], v[10:11], v[234:235]
	v_pk_add_f32 v[12:13], v[12:13], v[236:237]
	global_store_dwordx4 v168, v[10:13], s[100:101] offset:2048
	global_load_dwordx4 v[186:189], v0, s[28:29] offset:1024 nt
	global_load_dwordx4 v[190:193], v0, s[98:99] offset:1024 nt
	s_add_u32 s6, s98, 0x100000
	s_addc_u32 s7, s99, 0
	global_load_dwordx4 v[194:197], v0, s[6:7] offset:1024 nt
	s_add_u32 s6, s98, 0x200000
	s_addc_u32 s7, s99, 0
	global_load_dwordx4 v[198:201], v0, s[6:7] offset:1024 nt
	s_add_u32 s6, s98, 0x300000
	s_addc_u32 s7, s99, 0
	global_load_dwordx4 v[202:205], v0, s[6:7] offset:1024 nt
	s_add_u32 s6, s98, 0x400000
	s_addc_u32 s7, s99, 0
	global_load_dwordx4 v[206:209], v0, s[6:7] offset:1024 nt
	s_add_u32 s6, s98, 0x500000
	s_addc_u32 s7, s99, 0
	global_load_dwordx4 v[226:229], v0, s[6:7] offset:1024 nt
	s_add_u32 s6, s98, 0x600000
	s_addc_u32 s7, s99, 0
	global_load_dwordx4 v[230:233], v0, s[6:7] offset:1024 nt
	s_add_u32 s6, s98, 0x700000
	s_addc_u32 s7, s99, 0
	global_load_dwordx4 v[234:237], v0, s[6:7] offset:1024 nt
	s_waitcnt vmcnt(20)
	v_pk_add_f32 v[14:15], v[82:83], v[86:87]
	v_pk_add_f32 v[16:17], v[84:85], v[88:89]
	v_pk_add_f32 v[14:15], v[14:15], v[90:91]
	v_pk_add_f32 v[16:17], v[16:17], v[92:93]
	v_pk_add_f32 v[14:15], v[14:15], v[94:95]
	v_pk_add_f32 v[16:17], v[16:17], v[96:97]
	v_pk_add_f32 v[14:15], v[14:15], v[98:99]
	v_pk_add_f32 v[16:17], v[16:17], v[100:101]
	v_pk_add_f32 v[14:15], v[14:15], v[102:103]
	v_pk_add_f32 v[16:17], v[16:17], v[104:105]
	v_pk_add_f32 v[14:15], v[14:15], v[128:129]
	v_pk_add_f32 v[16:17], v[16:17], v[130:131]
	v_pk_add_f32 v[14:15], v[14:15], v[132:133]
	v_pk_add_f32 v[16:17], v[16:17], v[134:135]
	v_pk_add_f32 v[14:15], v[14:15], v[136:137]
	v_pk_add_f32 v[16:17], v[16:17], v[138:139]
	global_store_dwordx4 v168, v[14:17], s[100:101] offset:3072
	global_load_dwordx4 v[82:85], v0, s[28:29] offset:2048 nt
	global_load_dwordx4 v[86:89], v0, s[98:99] offset:2048 nt
	s_add_u32 s6, s98, 0x100000
	s_addc_u32 s7, s99, 0
	global_load_dwordx4 v[90:93], v0, s[6:7] offset:2048 nt
	s_add_u32 s6, s98, 0x200000
	s_addc_u32 s7, s99, 0
	global_load_dwordx4 v[94:97], v0, s[6:7] offset:2048 nt
	s_add_u32 s6, s98, 0x300000
	s_addc_u32 s7, s99, 0
	global_load_dwordx4 v[98:101], v0, s[6:7] offset:2048 nt
	s_add_u32 s6, s98, 0x400000
	s_addc_u32 s7, s99, 0
	global_load_dwordx4 v[102:105], v0, s[6:7] offset:2048 nt
	s_add_u32 s6, s98, 0x500000
	s_addc_u32 s7, s99, 0
	global_load_dwordx4 v[128:131], v0, s[6:7] offset:2048 nt
	s_add_u32 s6, s98, 0x600000
	s_addc_u32 s7, s99, 0
	global_load_dwordx4 v[132:135], v0, s[6:7] offset:2048 nt
	s_add_u32 s6, s98, 0x700000
	s_addc_u32 s7, s99, 0
	global_load_dwordx4 v[136:139], v0, s[6:7] offset:2048 nt
	s_waitcnt vmcnt(20)
	v_pk_add_f32 v[18:19], v[140:141], v[144:145]
	v_pk_add_f32 v[20:21], v[142:143], v[146:147]
	v_pk_add_f32 v[18:19], v[18:19], v[148:149]
	v_pk_add_f32 v[20:21], v[20:21], v[150:151]
	v_pk_add_f32 v[18:19], v[18:19], v[152:153]
	v_pk_add_f32 v[20:21], v[20:21], v[154:155]
	v_pk_add_f32 v[18:19], v[18:19], v[156:157]
	v_pk_add_f32 v[20:21], v[20:21], v[158:159]
	v_pk_add_f32 v[18:19], v[18:19], v[160:161]
	v_pk_add_f32 v[20:21], v[20:21], v[162:163]
	v_pk_add_f32 v[18:19], v[18:19], v[164:165]
	v_pk_add_f32 v[20:21], v[20:21], v[166:167]
	v_pk_add_f32 v[18:19], v[18:19], v[178:179]
	v_pk_add_f32 v[20:21], v[20:21], v[180:181]
	v_pk_add_f32 v[18:19], v[18:19], v[182:183]
	v_pk_add_f32 v[20:21], v[20:21], v[184:185]
	global_store_dwordx4 v0, v[18:21], s[100:101]
	global_load_dwordx4 v[140:143], v0, s[28:29] offset:3072 nt
	global_load_dwordx4 v[144:147], v0, s[98:99] offset:3072 nt
	s_add_u32 s6, s98, 0x100000
	s_addc_u32 s7, s99, 0
	global_load_dwordx4 v[148:151], v0, s[6:7] offset:3072 nt
	s_add_u32 s6, s98, 0x200000
	s_addc_u32 s7, s99, 0
	global_load_dwordx4 v[152:155], v0, s[6:7] offset:3072 nt
	s_add_u32 s6, s98, 0x300000
	s_addc_u32 s7, s99, 0
	global_load_dwordx4 v[156:159], v0, s[6:7] offset:3072 nt
	s_add_u32 s6, s98, 0x400000
	s_addc_u32 s7, s99, 0
	global_load_dwordx4 v[160:163], v0, s[6:7] offset:3072 nt
	s_add_u32 s6, s98, 0x500000
	s_addc_u32 s7, s99, 0
	global_load_dwordx4 v[164:167], v0, s[6:7] offset:3072 nt
	s_add_u32 s6, s98, 0x600000
	s_addc_u32 s7, s99, 0
	global_load_dwordx4 v[178:181], v0, s[6:7] offset:3072 nt
	s_add_u32 s6, s98, 0x700000
	s_addc_u32 s7, s99, 0
	global_load_dwordx4 v[182:185], v0, s[6:7] offset:3072 nt
	s_waitcnt vmcnt(20)
; __device__ __forceinline__ unsigned cvt_pk_bf16(float lo, float hi) { unsigned r; asm volatile("v_cvt_pk_bf16_f32 %0, %1, %2" : "=v"(r) : "v"(lo), "v"(hi)); return r; }
; __device__ __forceinline__ void row_bf16_ss(const float* xrow, bf16_t* orow, float* ss, int lane) {
;     const f32x4* xr = (const f32x4*)xrow + lane; f32x4 v[8]; float s = 0.f;
; #pragma unroll
;     for (int j = 0; j < 8; ++j) { v[j] = xr[64 * j]; s += (v[j].x * v[j].x + v[j].y * v[j].y) + (v[j].z * v[j].z + v[j].w * v[j].w); }
;     s = wave_sum(s); u32x2* o8 = (u32x2*)orow + lane;
; #pragma unroll
;     for (int j = 0; j < 8; ++j) { u32x2 w; w.x = cvt_pk_bf16(v[j].x, v[j].y); w.y = cvt_pk_bf16(v[j].z, v[j].w); o8[64 * j] = w; }
;     if (lane == 0) *ss = s;
; }
; __device__ __forceinline__ void sample_assemble(const float* base, const float* XSP, int nsp, int s, float* xr, int lane) {
;     const f32x4* br = (const f32x4*)base + lane; f32x4* o = (f32x4*)xr + lane;
; #pragma unroll
;     for (int j = 0; j < 8; ++j) { f32x4 v = br[64 * j];
;         for (int sp = 0; sp < nsp; ++sp) v += *((const f32x4*)(XSP + ((size_t)sp * NS + s) * DM) + lane + 64 * j);
;         o[64 * j] = v; }
; }
	v_pk_add_f32 v[22:23], v[186:187], v[190:191]
	v_pk_add_f32 v[24:25], v[188:189], v[192:193]
	v_pk_add_f32 v[22:23], v[22:23], v[194:195]
	v_pk_add_f32 v[24:25], v[24:25], v[196:197]
	v_pk_add_f32 v[22:23], v[22:23], v[198:199]
	v_pk_add_f32 v[24:25], v[24:25], v[200:201]
	v_pk_add_f32 v[22:23], v[22:23], v[202:203]
	v_pk_add_f32 v[24:25], v[24:25], v[204:205]
	v_pk_add_f32 v[22:23], v[22:23], v[206:207]
	v_pk_add_f32 v[24:25], v[24:25], v[208:209]
	v_pk_add_f32 v[22:23], v[22:23], v[226:227]
	v_pk_add_f32 v[24:25], v[24:25], v[228:229]
	v_pk_add_f32 v[22:23], v[22:23], v[230:231]
	v_pk_add_f32 v[24:25], v[24:25], v[232:233]
	v_pk_add_f32 v[22:23], v[22:23], v[234:235]
	v_pk_add_f32 v[24:25], v[24:25], v[236:237]
	global_store_dwordx4 v0, v[22:25], s[100:101] offset:1024
	s_waitcnt vmcnt(11)
	v_pk_add_f32 v[26:27], v[82:83], v[86:87]
	v_pk_add_f32 v[28:29], v[84:85], v[88:89]
	v_pk_add_f32 v[26:27], v[26:27], v[90:91]
	v_pk_add_f32 v[28:29], v[28:29], v[92:93]
	v_pk_add_f32 v[26:27], v[26:27], v[94:95]
	v_pk_add_f32 v[28:29], v[28:29], v[96:97]
	v_pk_add_f32 v[26:27], v[26:27], v[98:99]
	v_pk_add_f32 v[28:29], v[28:29], v[100:101]
	v_pk_add_f32 v[26:27], v[26:27], v[102:103]
	v_pk_add_f32 v[28:29], v[28:29], v[104:105]
	v_pk_add_f32 v[26:27], v[26:27], v[128:129]
	v_pk_add_f32 v[28:29], v[28:29], v[130:131]
	v_pk_add_f32 v[26:27], v[26:27], v[132:133]
	v_pk_add_f32 v[28:29], v[28:29], v[134:135]
	v_pk_add_f32 v[26:27], v[26:27], v[136:137]
	v_pk_add_f32 v[28:29], v[28:29], v[138:139]
	global_store_dwordx4 v0, v[26:29], s[100:101] offset:2048
	s_waitcnt vmcnt(2)
	v_pk_add_f32 v[78:79], v[140:141], v[144:145]
	v_pk_add_f32 v[80:81], v[142:143], v[146:147]
	v_pk_add_f32 v[78:79], v[78:79], v[148:149]
	v_pk_add_f32 v[80:81], v[80:81], v[150:151]
	v_pk_add_f32 v[78:79], v[78:79], v[152:153]
	v_pk_add_f32 v[80:81], v[80:81], v[154:155]
	v_pk_add_f32 v[78:79], v[78:79], v[156:157]
	v_pk_add_f32 v[80:81], v[80:81], v[158:159]
	v_pk_add_f32 v[78:79], v[78:79], v[160:161]
	v_pk_add_f32 v[80:81], v[80:81], v[162:163]
	v_pk_add_f32 v[78:79], v[78:79], v[164:165]
	v_pk_add_f32 v[80:81], v[80:81], v[166:167]
	v_pk_add_f32 v[78:79], v[78:79], v[178:179]
	v_pk_add_f32 v[80:81], v[80:81], v[180:181]
	v_pk_add_f32 v[78:79], v[78:79], v[182:183]
	v_pk_add_f32 v[80:81], v[80:81], v[184:185]
	global_store_dwordx4 v0, v[78:81], s[100:101] offset:3072
	v_mul_f32_e32 v44, v3, v3
	v_mul_f32_e32 v30, v5, v5
	v_fmac_f32_e32 v44, v2, v2
	v_fmac_f32_e32 v30, v4, v4
	v_add_f32_e32 v44, v44, v30
	v_mul_f32_e32 v1, v7, v7
	v_mul_f32_e32 v30, v9, v9
	v_fmac_f32_e32 v1, v6, v6
	v_fmac_f32_e32 v30, v8, v8
	v_add_f32_e32 v1, v1, v30
	v_add_f32_e32 v44, v44, v1
	v_mul_f32_e32 v1, v11, v11
	v_mul_f32_e32 v30, v13, v13
	v_fmac_f32_e32 v1, v10, v10
	v_fmac_f32_e32 v30, v12, v12
	v_add_f32_e32 v1, v1, v30
	v_add_f32_e32 v44, v44, v1
	v_mul_f32_e32 v1, v15, v15
	v_mul_f32_e32 v30, v17, v17
	v_fmac_f32_e32 v1, v14, v14
	v_fmac_f32_e32 v30, v16, v16
	v_add_f32_e32 v1, v1, v30
	v_add_f32_e32 v44, v44, v1
	v_mul_f32_e32 v1, v19, v19
	v_mul_f32_e32 v30, v21, v21
	v_fmac_f32_e32 v1, v18, v18
	v_fmac_f32_e32 v30, v20, v20
	v_add_f32_e32 v1, v1, v30
	v_add_f32_e32 v44, v44, v1
	v_mul_f32_e32 v1, v23, v23
	v_mul_f32_e32 v30, v25, v25
	v_fmac_f32_e32 v1, v22, v22
	v_fmac_f32_e32 v30, v24, v24
	v_add_f32_e32 v1, v1, v30
	v_add_f32_e32 v44, v44, v1
	v_mul_f32_e32 v1, v27, v27
	v_mul_f32_e32 v30, v29, v29
	v_fmac_f32_e32 v1, v26, v26
	v_fmac_f32_e32 v30, v28, v28
	v_add_f32_e32 v1, v1, v30
	v_add_f32_e32 v44, v44, v1
	v_mul_f32_e32 v1, v79, v79
	v_mul_f32_e32 v30, v81, v81
	v_fmac_f32_e32 v1, v78, v78
	v_fmac_f32_e32 v30, v80, v80
	v_add_f32_e32 v1, v1, v30
	v_add_f32_e32 v44, v44, v1
	v_lshrrev_b32_e32 v47, 1, v168
	v_readfirstlane_b32 s6, v36
	v_readfirstlane_b32 s7, v37
	s_lshl_b64 s[98:99], s[26:27], 12
	s_add_u32 s6, s6, s98
	s_addc_u32 s7, s7, s99
	v_cvt_pk_bf16_f32 v106, v2, v3
	v_cvt_pk_bf16_f32 v107, v4, v5
	global_store_dwordx2 v47, v[106:107], s[6:7]
	v_cvt_pk_bf16_f32 v238, v6, v7
	v_cvt_pk_bf16_f32 v239, v8, v9
	global_store_dwordx2 v47, v[238:239], s[6:7] offset:512
	v_cvt_pk_bf16_f32 v240, v10, v11
	v_cvt_pk_bf16_f32 v241, v12, v13
	global_store_dwordx2 v47, v[240:241], s[6:7] offset:1024
	v_cvt_pk_bf16_f32 v242, v14, v15
	v_cvt_pk_bf16_f32 v243, v16, v17
	global_store_dwordx2 v47, v[242:243], s[6:7] offset:1536
	v_cvt_pk_bf16_f32 v248, v18, v19
	v_cvt_pk_bf16_f32 v249, v20, v21
	global_store_dwordx2 v47, v[248:249], s[6:7] offset:2048
	v_cvt_pk_bf16_f32 v250, v22, v23
	v_cvt_pk_bf16_f32 v251, v24, v25
	global_store_dwordx2 v47, v[250:251], s[6:7] offset:2560
	v_cvt_pk_bf16_f32 v252, v26, v27
	v_cvt_pk_bf16_f32 v253, v28, v29
	global_store_dwordx2 v47, v[252:253], s[6:7] offset:3072
	v_cvt_pk_bf16_f32 v254, v78, v79
	v_cvt_pk_bf16_f32 v255, v80, v81
	global_store_dwordx2 v47, v[254:255], s[6:7] offset:3584
	ds_bpermute_b32 v45, v38, v44
	s_waitcnt lgkmcnt(0)
	v_add_f32_e32 v44, v44, v45
	ds_bpermute_b32 v45, v39, v44
	s_waitcnt lgkmcnt(0)
	v_add_f32_e32 v44, v44, v45
	ds_bpermute_b32 v45, v40, v44
	s_waitcnt lgkmcnt(0)
	v_add_f32_e32 v44, v44, v45
	ds_bpermute_b32 v45, v41, v44
	s_waitcnt lgkmcnt(0)
	v_add_f32_e32 v44, v44, v45
	ds_bpermute_b32 v45, v42, v44
	s_waitcnt lgkmcnt(0)
	v_add_f32_e32 v44, v44, v45
	ds_bpermute_b32 v45, v43, v44
	s_and_saveexec_b64 s[6:7], s[40:41]
	s_cbranch_execz .LBB0_716
	s_lshl_b64 s[8:9], s[26:27], 2
	s_add_u32 s8, s10, s8
	s_waitcnt lgkmcnt(0)
	v_add_f32_e32 v0, v44, v45
	s_addc_u32 s9, s34, s9
	global_store_dword v169, v0, s[8:9]
	s_branch .LBB0_716

; __device__ __forceinline__ void sample_assemble(const float* base, const float* XSP, int nsp, int s, float* xr, int lane) {
;     const f32x4* br = (const f32x4*)base + lane; f32x4* o = (f32x4*)xr + lane;
; #pragma unroll
;     for (int j = 0; j < 8; ++j) { f32x4 v = br[64 * j];
;         for (int sp = 0; sp < nsp; ++sp) v += *((const f32x4*)(XSP + ((size_t)sp * NS + s) * DM) + lane + 64 * j);
;         o[64 * j] = v; }
; }
; __global__ void __launch_bounds__(NTHR, 2) fwd_kernel(Args a) {
;     ...
;               for (int m = MP + gw; m < MREAL; m += NGW) { sample_assemble(XR + (size_t)m * DM, XSP, 11, m - MP, XR + (size_t)m * DM, lane);
;                   row_bf16_ss(XR + (size_t)m * DM, XN + (size_t)m * DM, SSB + (size_t)2 * MPAD + m, lane); }
.LBB0_1019:
	s_waitcnt lgkmcnt(0)
	v_readfirstlane_b32 s98, v36
	v_readfirstlane_b32 s99, v37
	v_readfirstlane_b32 s100, v34
	v_readfirstlane_b32 s101, v35
	v_lshlrev_b32_e32 v39, 4, v211
	s_add_u32 s98, s98, s2
	s_addc_u32 s99, s99, s3
	s_add_u32 s98, s98, 0x216e4000
	s_addc_u32 s99, s99, 0
	s_add_u32 s100, s100, s2
	s_addc_u32 s101, s101, s3
	s_add_u32 s100, s100, 0xe700000
	s_addc_u32 s101, s101, 0
	v_add_u32_e32 v0, 0x1000, v39
	global_load_dwordx4 v[46:49], v39, s[100:101] nt
	global_load_dwordx4 v[50:53], v39, s[98:99] nt
	s_add_u32 s4, s98, 0x100000
	s_addc_u32 s5, s99, 0
	global_load_dwordx4 v[54:57], v39, s[4:5] nt
	s_add_u32 s4, s98, 0x200000
	s_addc_u32 s5, s99, 0
	global_load_dwordx4 v[58:61], v39, s[4:5] nt
	s_add_u32 s4, s98, 0x300000
	s_addc_u32 s5, s99, 0
	global_load_dwordx4 v[78:81], v39, s[4:5] nt
	s_add_u32 s4, s98, 0x400000
	s_addc_u32 s5, s99, 0
	global_load_dwordx4 v[82:85], v39, s[4:5] nt
	s_add_u32 s4, s98, 0x500000
	s_addc_u32 s5, s99, 0
	global_load_dwordx4 v[86:89], v39, s[4:5] nt
	s_add_u32 s4, s98, 0x600000
	s_addc_u32 s5, s99, 0
	global_load_dwordx4 v[90:93], v39, s[4:5] nt
	s_add_u32 s4, s98, 0x700000
	s_addc_u32 s5, s99, 0
	global_load_dwordx4 v[94:97], v39, s[4:5] nt
	s_add_u32 s4, s98, 0x800000
	s_addc_u32 s5, s99, 0
	global_load_dwordx4 v[98:101], v39, s[4:5] nt
	s_add_u32 s4, s98, 0x900000
	s_addc_u32 s5, s99, 0
	global_load_dwordx4 v[102:105], v39, s[4:5] nt
	s_add_u32 s4, s98, 0xa00000
	s_addc_u32 s5, s99, 0
	global_load_dwordx4 v[128:131], v39, s[4:5] nt
	global_load_dwordx4 v[132:135], v39, s[100:101] offset:1024 nt
	global_load_dwordx4 v[136:139], v39, s[98:99] offset:1024 nt
	s_add_u32 s4, s98, 0x100000
	s_addc_u32 s5, s99, 0
	global_load_dwordx4 v[140:143], v39, s[4:5] offset:1024 nt
	s_add_u32 s4, s98, 0x200000
	s_addc_u32 s5, s99, 0
	global_load_dwordx4 v[144:147], v39, s[4:5] offset:1024 nt
	s_add_u32 s4, s98, 0x300000
	s_addc_u32 s5, s99, 0
	global_load_dwordx4 v[148:151], v39, s[4:5] offset:1024 nt
	s_add_u32 s4, s98, 0x400000
	s_addc_u32 s5, s99, 0
	global_load_dwordx4 v[152:155], v39, s[4:5] offset:1024 nt
	s_add_u32 s4, s98, 0x500000
	s_addc_u32 s5, s99, 0
	global_load_dwordx4 v[156:159], v39, s[4:5] offset:1024 nt
	s_add_u32 s4, s98, 0x600000
	s_addc_u32 s5, s99, 0
	global_load_dwordx4 v[160:163], v39, s[4:5] offset:1024 nt
	s_add_u32 s4, s98, 0x700000
	s_addc_u32 s5, s99, 0
	global_load_dwordx4 v[164:167], v39, s[4:5] offset:1024 nt
	s_add_u32 s4, s98, 0x800000
	s_addc_u32 s5, s99, 0
	global_load_dwordx4 v[178:181], v39, s[4:5] offset:1024 nt
	s_add_u32 s4, s98, 0x900000
	s_addc_u32 s5, s99, 0
	global_load_dwordx4 v[182:185], v39, s[4:5] offset:1024 nt
	s_add_u32 s4, s98, 0xa00000
	s_addc_u32 s5, s99, 0
	global_load_dwordx4 v[186:189], v39, s[4:5] offset:1024 nt
	s_waitcnt vmcnt(12)
	v_pk_add_f32 v[2:3], v[46:47], v[50:51]
	v_pk_add_f32 v[4:5], v[48:49], v[52:53]
	v_pk_add_f32 v[2:3], v[2:3], v[54:55]
	v_pk_add_f32 v[4:5], v[4:5], v[56:57]
	v_pk_add_f32 v[2:3], v[2:3], v[58:59]
	v_pk_add_f32 v[4:5], v[4:5], v[60:61]
	v_pk_add_f32 v[2:3], v[2:3], v[78:79]
	v_pk_add_f32 v[4:5], v[4:5], v[80:81]
	v_pk_add_f32 v[2:3], v[2:3], v[82:83]
	v_pk_add_f32 v[4:5], v[4:5], v[84:85]
	v_pk_add_f32 v[2:3], v[2:3], v[86:87]
	v_pk_add_f32 v[4:5], v[4:5], v[88:89]
	v_pk_add_f32 v[2:3], v[2:3], v[90:91]
	v_pk_add_f32 v[4:5], v[4:5], v[92:93]
	v_pk_add_f32 v[2:3], v[2:3], v[94:95]
	v_pk_add_f32 v[4:5], v[4:5], v[96:97]
	v_pk_add_f32 v[2:3], v[2:3], v[98:99]
	v_pk_add_f32 v[4:5], v[4:5], v[100:101]
	v_pk_add_f32 v[2:3], v[2:3], v[102:103]
	v_pk_add_f32 v[4:5], v[4:5], v[104:105]
	v_pk_add_f32 v[2:3], v[2:3], v[128:129]
	v_pk_add_f32 v[4:5], v[4:5], v[130:131]
	global_store_dwordx4 v39, v[2:5], s[100:101]
	global_load_dwordx4 v[46:49], v39, s[100:101] offset:2048 nt
	global_load_dwordx4 v[50:53], v39, s[98:99] offset:2048 nt
	s_add_u32 s4, s98, 0x100000
	s_addc_u32 s5, s99, 0
	global_load_dwordx4 v[54:57], v39, s[4:5] offset:2048 nt
	s_add_u32 s4, s98, 0x200000
	s_addc_u32 s5, s99, 0
	global_load_dwordx4 v[58:61], v39, s[4:5] offset:2048 nt
	s_add_u32 s4, s98, 0x300000
	s_addc_u32 s5, s99, 0
	global_load_dwordx4 v[78:81], v39, s[4:5] offset:2048 nt
	s_add_u32 s4, s98, 0x400000
	s_addc_u32 s5, s99, 0
	global_load_dwordx4 v[82:85], v39, s[4:5] offset:2048 nt
	s_add_u32 s4, s98, 0x500000
	s_addc_u32 s5, s99, 0
	global_load_dwordx4 v[86:89], v39, s[4:5] offset:2048 nt
	s_add_u32 s4, s98, 0x600000
	s_addc_u32 s5, s99, 0
	global_load_dwordx4 v[90:93], v39, s[4:5] offset:2048 nt
	s_add_u32 s4, s98, 0x700000
	s_addc_u32 s5, s99, 0
	global_load_dwordx4 v[94:97], v39, s[4:5] offset:2048 nt
	s_add_u32 s4, s98, 0x800000
	s_addc_u32 s5, s99, 0
	global_load_dwordx4 v[98:101], v39, s[4:5] offset:2048 nt
	s_add_u32 s4, s98, 0x900000
	s_addc_u32 s5, s99, 0
	global_load_dwordx4 v[102:105], v39, s[4:5] offset:2048 nt
	s_add_u32 s4, s98, 0xa00000
	s_addc_u32 s5, s99, 0
	global_load_dwordx4 v[128:131], v39, s[4:5] offset:2048 nt
	s_waitcnt vmcnt(13)
; __device__ __forceinline__ void sample_assemble(const float* base, const float* XSP, int nsp, int s, float* xr, int lane) {
;     const f32x4* br = (const f32x4*)base + lane; f32x4* o = (f32x4*)xr + lane;
; #pragma unroll
;     for (int j = 0; j < 8; ++j) { f32x4 v = br[64 * j];
;         for (int sp = 0; sp < nsp; ++sp) v += *((const f32x4*)(XSP + ((size_t)sp * NS + s) * DM) + lane + 64 * j);
;         o[64 * j] = v; }
; }
	v_pk_add_f32 v[6:7], v[132:133], v[136:137]
	v_pk_add_f32 v[8:9], v[134:135], v[138:139]
	v_pk_add_f32 v[6:7], v[6:7], v[140:141]
	v_pk_add_f32 v[8:9], v[8:9], v[142:143]
	v_pk_add_f32 v[6:7], v[6:7], v[144:145]
	v_pk_add_f32 v[8:9], v[8:9], v[146:147]
	v_pk_add_f32 v[6:7], v[6:7], v[148:149]
	v_pk_add_f32 v[8:9], v[8:9], v[150:151]
	v_pk_add_f32 v[6:7], v[6:7], v[152:153]
	v_pk_add_f32 v[8:9], v[8:9], v[154:155]
	v_pk_add_f32 v[6:7], v[6:7], v[156:157]
	v_pk_add_f32 v[8:9], v[8:9], v[158:159]
	v_pk_add_f32 v[6:7], v[6:7], v[160:161]
	v_pk_add_f32 v[8:9], v[8:9], v[162:163]
	v_pk_add_f32 v[6:7], v[6:7], v[164:165]
	v_pk_add_f32 v[8:9], v[8:9], v[166:167]
	v_pk_add_f32 v[6:7], v[6:7], v[178:179]
	v_pk_add_f32 v[8:9], v[8:9], v[180:181]
	v_pk_add_f32 v[6:7], v[6:7], v[182:183]
	v_pk_add_f32 v[8:9], v[8:9], v[184:185]
	v_pk_add_f32 v[6:7], v[6:7], v[186:187]
	v_pk_add_f32 v[8:9], v[8:9], v[188:189]
	global_store_dwordx4 v39, v[6:9], s[100:101] offset:1024
	global_load_dwordx4 v[132:135], v39, s[100:101] offset:3072 nt
	global_load_dwordx4 v[136:139], v39, s[98:99] offset:3072 nt
	s_add_u32 s4, s98, 0x100000
	s_addc_u32 s5, s99, 0
	global_load_dwordx4 v[140:143], v39, s[4:5] offset:3072 nt
	s_add_u32 s4, s98, 0x200000
	s_addc_u32 s5, s99, 0
	global_load_dwordx4 v[144:147], v39, s[4:5] offset:3072 nt
	s_add_u32 s4, s98, 0x300000
	s_addc_u32 s5, s99, 0
	global_load_dwordx4 v[148:151], v39, s[4:5] offset:3072 nt
	s_add_u32 s4, s98, 0x400000
	s_addc_u32 s5, s99, 0
	global_load_dwordx4 v[152:155], v39, s[4:5] offset:3072 nt
	s_add_u32 s4, s98, 0x500000
	s_addc_u32 s5, s99, 0
	global_load_dwordx4 v[156:159], v39, s[4:5] offset:3072 nt
	s_add_u32 s4, s98, 0x600000
	s_addc_u32 s5, s99, 0
	global_load_dwordx4 v[160:163], v39, s[4:5] offset:3072 nt
	s_add_u32 s4, s98, 0x700000
	s_addc_u32 s5, s99, 0
	global_load_dwordx4 v[164:167], v39, s[4:5] offset:3072 nt
	s_add_u32 s4, s98, 0x800000
	s_addc_u32 s5, s99, 0
	global_load_dwordx4 v[178:181], v39, s[4:5] offset:3072 nt
	s_add_u32 s4, s98, 0x900000
	s_addc_u32 s5, s99, 0
	global_load_dwordx4 v[182:185], v39, s[4:5] offset:3072 nt
	s_add_u32 s4, s98, 0xa00000
	s_addc_u32 s5, s99, 0
	global_load_dwordx4 v[186:189], v39, s[4:5] offset:3072 nt
	s_waitcnt vmcnt(13)
	v_pk_add_f32 v[10:11], v[46:47], v[50:51]
	v_pk_add_f32 v[12:13], v[48:49], v[52:53]
	v_pk_add_f32 v[10:11], v[10:11], v[54:55]
	v_pk_add_f32 v[12:13], v[12:13], v[56:57]
	v_pk_add_f32 v[10:11], v[10:11], v[58:59]
	v_pk_add_f32 v[12:13], v[12:13], v[60:61]
	v_pk_add_f32 v[10:11], v[10:11], v[78:79]
	v_pk_add_f32 v[12:13], v[12:13], v[80:81]
	v_pk_add_f32 v[10:11], v[10:11], v[82:83]
	v_pk_add_f32 v[12:13], v[12:13], v[84:85]
	v_pk_add_f32 v[10:11], v[10:11], v[86:87]
	v_pk_add_f32 v[12:13], v[12:13], v[88:89]
	v_pk_add_f32 v[10:11], v[10:11], v[90:91]
	v_pk_add_f32 v[12:13], v[12:13], v[92:93]
	v_pk_add_f32 v[10:11], v[10:11], v[94:95]
	v_pk_add_f32 v[12:13], v[12:13], v[96:97]
	v_pk_add_f32 v[10:11], v[10:11], v[98:99]
	v_pk_add_f32 v[12:13], v[12:13], v[100:101]
	v_pk_add_f32 v[10:11], v[10:11], v[102:103]
	v_pk_add_f32 v[12:13], v[12:13], v[104:105]
	v_pk_add_f32 v[10:11], v[10:11], v[128:129]
	v_pk_add_f32 v[12:13], v[12:13], v[130:131]
	global_store_dwordx4 v39, v[10:13], s[100:101] offset:2048
	global_load_dwordx4 v[46:49], v0, s[100:101] nt
	global_load_dwordx4 v[50:53], v0, s[98:99] nt
	s_add_u32 s4, s98, 0x100000
	s_addc_u32 s5, s99, 0
	global_load_dwordx4 v[54:57], v0, s[4:5] nt
	s_add_u32 s4, s98, 0x200000
	s_addc_u32 s5, s99, 0
	global_load_dwordx4 v[58:61], v0, s[4:5] nt
	s_add_u32 s4, s98, 0x300000
	s_addc_u32 s5, s99, 0
	global_load_dwordx4 v[78:81], v0, s[4:5] nt
	s_add_u32 s4, s98, 0x400000
	s_addc_u32 s5, s99, 0
	global_load_dwordx4 v[82:85], v0, s[4:5] nt
	s_add_u32 s4, s98, 0x500000
	s_addc_u32 s5, s99, 0
	global_load_dwordx4 v[86:89], v0, s[4:5] nt
	s_add_u32 s4, s98, 0x600000
	s_addc_u32 s5, s99, 0
	global_load_dwordx4 v[90:93], v0, s[4:5] nt
	s_add_u32 s4, s98, 0x700000
	s_addc_u32 s5, s99, 0
	global_load_dwordx4 v[94:97], v0, s[4:5] nt
	s_add_u32 s4, s98, 0x800000
	s_addc_u32 s5, s99, 0
	global_load_dwordx4 v[98:101], v0, s[4:5] nt
	s_add_u32 s4, s98, 0x900000
	s_addc_u32 s5, s99, 0
	global_load_dwordx4 v[102:105], v0, s[4:5] nt
	s_add_u32 s4, s98, 0xa00000
	s_addc_u32 s5, s99, 0
	global_load_dwordx4 v[128:131], v0, s[4:5] nt
	s_waitcnt vmcnt(13)
	v_pk_add_f32 v[14:15], v[132:133], v[136:137]
	v_pk_add_f32 v[16:17], v[134:135], v[138:139]
	v_pk_add_f32 v[14:15], v[14:15], v[140:141]
	v_pk_add_f32 v[16:17], v[16:17], v[142:143]
	v_pk_add_f32 v[14:15], v[14:15], v[144:145]
	v_pk_add_f32 v[16:17], v[16:17], v[146:147]
	v_pk_add_f32 v[14:15], v[14:15], v[148:149]
	v_pk_add_f32 v[16:17], v[16:17], v[150:151]
	v_pk_add_f32 v[14:15], v[14:15], v[152:153]
	v_pk_add_f32 v[16:17], v[16:17], v[154:155]
	v_pk_add_f32 v[14:15], v[14:15], v[156:157]
	v_pk_add_f32 v[16:17], v[16:17], v[158:159]
	v_pk_add_f32 v[14:15], v[14:15], v[160:161]
	v_pk_add_f32 v[16:17], v[16:17], v[162:163]
	v_pk_add_f32 v[14:15], v[14:15], v[164:165]
	v_pk_add_f32 v[16:17], v[16:17], v[166:167]
	v_pk_add_f32 v[14:15], v[14:15], v[178:179]
	v_pk_add_f32 v[16:17], v[16:17], v[180:181]
	v_pk_add_f32 v[14:15], v[14:15], v[182:183]
	v_pk_add_f32 v[16:17], v[16:17], v[184:185]
	v_pk_add_f32 v[14:15], v[14:15], v[186:187]
	v_pk_add_f32 v[16:17], v[16:17], v[188:189]
	global_store_dwordx4 v39, v[14:17], s[100:101] offset:3072
	global_load_dwordx4 v[132:135], v0, s[100:101] offset:1024 nt
	global_load_dwordx4 v[136:139], v0, s[98:99] offset:1024 nt
	s_add_u32 s4, s98, 0x100000
	s_addc_u32 s5, s99, 0
	global_load_dwordx4 v[140:143], v0, s[4:5] offset:1024 nt
	s_add_u32 s4, s98, 0x200000
	s_addc_u32 s5, s99, 0
	global_load_dwordx4 v[144:147], v0, s[4:5] offset:1024 nt
	s_add_u32 s4, s98, 0x300000
	s_addc_u32 s5, s99, 0
	global_load_dwordx4 v[148:151], v0, s[4:5] offset:1024 nt
	s_add_u32 s4, s98, 0x400000
	s_addc_u32 s5, s99, 0
	global_load_dwordx4 v[152:155], v0, s[4:5] offset:1024 nt
	s_add_u32 s4, s98, 0x500000
	s_addc_u32 s5, s99, 0
	global_load_dwordx4 v[156:159], v0, s[4:5] offset:1024 nt
	s_add_u32 s4, s98, 0x600000
	s_addc_u32 s5, s99, 0
	global_load_dwordx4 v[160:163], v0, s[4:5] offset:1024 nt
	s_add_u32 s4, s98, 0x700000
	s_addc_u32 s5, s99, 0
	global_load_dwordx4 v[164:167], v0, s[4:5] offset:1024 nt
	s_add_u32 s4, s98, 0x800000
	s_addc_u32 s5, s99, 0
	global_load_dwordx4 v[178:181], v0, s[4:5] offset:1024 nt
	s_add_u32 s4, s98, 0x900000
	s_addc_u32 s5, s99, 0
	global_load_dwordx4 v[182:185], v0, s[4:5] offset:1024 nt
	s_add_u32 s4, s98, 0xa00000
	s_addc_u32 s5, s99, 0
	global_load_dwordx4 v[186:189], v0, s[4:5] offset:1024 nt
	s_waitcnt vmcnt(13)
; __device__ __forceinline__ void sample_assemble(const float* base, const float* XSP, int nsp, int s, float* xr, int lane) {
;     const f32x4* br = (const f32x4*)base + lane; f32x4* o = (f32x4*)xr + lane;
; #pragma unroll
;     for (int j = 0; j < 8; ++j) { f32x4 v = br[64 * j];
;         for (int sp = 0; sp < nsp; ++sp) v += *((const f32x4*)(XSP + ((size_t)sp * NS + s) * DM) + lane + 64 * j);
;         o[64 * j] = v; }
; }
	v_pk_add_f32 v[18:19], v[46:47], v[50:51]
	v_pk_add_f32 v[20:21], v[48:49], v[52:53]
	v_pk_add_f32 v[18:19], v[18:19], v[54:55]
	v_pk_add_f32 v[20:21], v[20:21], v[56:57]
	v_pk_add_f32 v[18:19], v[18:19], v[58:59]
	v_pk_add_f32 v[20:21], v[20:21], v[60:61]
	v_pk_add_f32 v[18:19], v[18:19], v[78:79]
	v_pk_add_f32 v[20:21], v[20:21], v[80:81]
	v_pk_add_f32 v[18:19], v[18:19], v[82:83]
	v_pk_add_f32 v[20:21], v[20:21], v[84:85]
	v_pk_add_f32 v[18:19], v[18:19], v[86:87]
	v_pk_add_f32 v[20:21], v[20:21], v[88:89]
	v_pk_add_f32 v[18:19], v[18:19], v[90:91]
	v_pk_add_f32 v[20:21], v[20:21], v[92:93]
	v_pk_add_f32 v[18:19], v[18:19], v[94:95]
	v_pk_add_f32 v[20:21], v[20:21], v[96:97]
	v_pk_add_f32 v[18:19], v[18:19], v[98:99]
	v_pk_add_f32 v[20:21], v[20:21], v[100:101]
	v_pk_add_f32 v[18:19], v[18:19], v[102:103]
	v_pk_add_f32 v[20:21], v[20:21], v[104:105]
	v_pk_add_f32 v[18:19], v[18:19], v[128:129]
	v_pk_add_f32 v[20:21], v[20:21], v[130:131]
	global_store_dwordx4 v0, v[18:21], s[100:101]
	global_load_dwordx4 v[46:49], v0, s[100:101] offset:2048 nt
	global_load_dwordx4 v[50:53], v0, s[98:99] offset:2048 nt
	s_add_u32 s4, s98, 0x100000
	s_addc_u32 s5, s99, 0
	global_load_dwordx4 v[54:57], v0, s[4:5] offset:2048 nt
	s_add_u32 s4, s98, 0x200000
	s_addc_u32 s5, s99, 0
	global_load_dwordx4 v[58:61], v0, s[4:5] offset:2048 nt
	s_add_u32 s4, s98, 0x300000
	s_addc_u32 s5, s99, 0
	global_load_dwordx4 v[78:81], v0, s[4:5] offset:2048 nt
	s_add_u32 s4, s98, 0x400000
	s_addc_u32 s5, s99, 0
	global_load_dwordx4 v[82:85], v0, s[4:5] offset:2048 nt
	s_add_u32 s4, s98, 0x500000
	s_addc_u32 s5, s99, 0
	global_load_dwordx4 v[86:89], v0, s[4:5] offset:2048 nt
	s_add_u32 s4, s98, 0x600000
	s_addc_u32 s5, s99, 0
	global_load_dwordx4 v[90:93], v0, s[4:5] offset:2048 nt
	s_add_u32 s4, s98, 0x700000
	s_addc_u32 s5, s99, 0
	global_load_dwordx4 v[94:97], v0, s[4:5] offset:2048 nt
	s_add_u32 s4, s98, 0x800000
	s_addc_u32 s5, s99, 0
	global_load_dwordx4 v[98:101], v0, s[4:5] offset:2048 nt
	s_add_u32 s4, s98, 0x900000
	s_addc_u32 s5, s99, 0
	global_load_dwordx4 v[102:105], v0, s[4:5] offset:2048 nt
	s_add_u32 s4, s98, 0xa00000
	s_addc_u32 s5, s99, 0
	global_load_dwordx4 v[128:131], v0, s[4:5] offset:2048 nt
	s_waitcnt vmcnt(13)
	v_pk_add_f32 v[22:23], v[132:133], v[136:137]
	v_pk_add_f32 v[24:25], v[134:135], v[138:139]
	v_pk_add_f32 v[22:23], v[22:23], v[140:141]
	v_pk_add_f32 v[24:25], v[24:25], v[142:143]
	v_pk_add_f32 v[22:23], v[22:23], v[144:145]
	v_pk_add_f32 v[24:25], v[24:25], v[146:147]
	v_pk_add_f32 v[22:23], v[22:23], v[148:149]
	v_pk_add_f32 v[24:25], v[24:25], v[150:151]
	v_pk_add_f32 v[22:23], v[22:23], v[152:153]
	v_pk_add_f32 v[24:25], v[24:25], v[154:155]
	v_pk_add_f32 v[22:23], v[22:23], v[156:157]
	v_pk_add_f32 v[24:25], v[24:25], v[158:159]
	v_pk_add_f32 v[22:23], v[22:23], v[160:161]
	v_pk_add_f32 v[24:25], v[24:25], v[162:163]
	v_pk_add_f32 v[22:23], v[22:23], v[164:165]
	v_pk_add_f32 v[24:25], v[24:25], v[166:167]
	v_pk_add_f32 v[22:23], v[22:23], v[178:179]
	v_pk_add_f32 v[24:25], v[24:25], v[180:181]
	v_pk_add_f32 v[22:23], v[22:23], v[182:183]
	v_pk_add_f32 v[24:25], v[24:25], v[184:185]
	v_pk_add_f32 v[22:23], v[22:23], v[186:187]
	v_pk_add_f32 v[24:25], v[24:25], v[188:189]
	global_store_dwordx4 v0, v[22:25], s[100:101] offset:1024
	global_load_dwordx4 v[132:135], v0, s[100:101] offset:3072 nt
	global_load_dwordx4 v[136:139], v0, s[98:99] offset:3072 nt
	s_add_u32 s4, s98, 0x100000
	s_addc_u32 s5, s99, 0
	global_load_dwordx4 v[140:143], v0, s[4:5] offset:3072 nt
	s_add_u32 s4, s98, 0x200000
	s_addc_u32 s5, s99, 0
	global_load_dwordx4 v[144:147], v0, s[4:5] offset:3072 nt
	s_add_u32 s4, s98, 0x300000
	s_addc_u32 s5, s99, 0
	global_load_dwordx4 v[148:151], v0, s[4:5] offset:3072 nt
	s_add_u32 s4, s98, 0x400000
	s_addc_u32 s5, s99, 0
	global_load_dwordx4 v[152:155], v0, s[4:5] offset:3072 nt
	s_add_u32 s4, s98, 0x500000
	s_addc_u32 s5, s99, 0
	global_load_dwordx4 v[156:159], v0, s[4:5] offset:3072 nt
	s_add_u32 s4, s98, 0x600000
	s_addc_u32 s5, s99, 0
	global_load_dwordx4 v[160:163], v0, s[4:5] offset:3072 nt
	s_add_u32 s4, s98, 0x700000
	s_addc_u32 s5, s99, 0
	global_load_dwordx4 v[164:167], v0, s[4:5] offset:3072 nt
	s_add_u32 s4, s98, 0x800000
	s_addc_u32 s5, s99, 0
	global_load_dwordx4 v[178:181], v0, s[4:5] offset:3072 nt
	s_add_u32 s4, s98, 0x900000
	s_addc_u32 s5, s99, 0
	global_load_dwordx4 v[182:185], v0, s[4:5] offset:3072 nt
	s_add_u32 s4, s98, 0xa00000
	s_addc_u32 s5, s99, 0
	global_load_dwordx4 v[186:189], v0, s[4:5] offset:3072 nt
	s_waitcnt vmcnt(13)
; __device__ __forceinline__ unsigned cvt_pk_bf16(float lo, float hi) { unsigned r; asm volatile("v_cvt_pk_bf16_f32 %0, %1, %2" : "=v"(r) : "v"(lo), "v"(hi)); return r; }
; __device__ __forceinline__ void row_bf16_ss(const float* xrow, bf16_t* orow, float* ss, int lane) {
;     const f32x4* xr = (const f32x4*)xrow + lane; f32x4 v[8]; float s = 0.f;
; #pragma unroll
;     for (int j = 0; j < 8; ++j) { v[j] = xr[64 * j]; s += (v[j].x * v[j].x + v[j].y * v[j].y) + (v[j].z * v[j].z + v[j].w * v[j].w); }
;     s = wave_sum(s); u32x2* o8 = (u32x2*)orow + lane;
; #pragma unroll
;     for (int j = 0; j < 8; ++j) { u32x2 w; w.x = cvt_pk_bf16(v[j].x, v[j].y); w.y = cvt_pk_bf16(v[j].z, v[j].w); o8[64 * j] = w; }
;     if (lane == 0) *ss = s;
; }
; __device__ __forceinline__ void sample_assemble(const float* base, const float* XSP, int nsp, int s, float* xr, int lane) {
;     const f32x4* br = (const f32x4*)base + lane; f32x4* o = (f32x4*)xr + lane;
; #pragma unroll
;     for (int j = 0; j < 8; ++j) { f32x4 v = br[64 * j];
;         for (int sp = 0; sp < nsp; ++sp) v += *((const f32x4*)(XSP + ((size_t)sp * NS + s) * DM) + lane + 64 * j);
;         o[64 * j] = v; }
; }
	v_pk_add_f32 v[26:27], v[46:47], v[50:51]
	v_pk_add_f32 v[28:29], v[48:49], v[52:53]
	v_pk_add_f32 v[26:27], v[26:27], v[54:55]
	v_pk_add_f32 v[28:29], v[28:29], v[56:57]
	v_pk_add_f32 v[26:27], v[26:27], v[58:59]
	v_pk_add_f32 v[28:29], v[28:29], v[60:61]
	v_pk_add_f32 v[26:27], v[26:27], v[78:79]
	v_pk_add_f32 v[28:29], v[28:29], v[80:81]
	v_pk_add_f32 v[26:27], v[26:27], v[82:83]
	v_pk_add_f32 v[28:29], v[28:29], v[84:85]
	v_pk_add_f32 v[26:27], v[26:27], v[86:87]
	v_pk_add_f32 v[28:29], v[28:29], v[88:89]
	v_pk_add_f32 v[26:27], v[26:27], v[90:91]
	v_pk_add_f32 v[28:29], v[28:29], v[92:93]
	v_pk_add_f32 v[26:27], v[26:27], v[94:95]
	v_pk_add_f32 v[28:29], v[28:29], v[96:97]
	v_pk_add_f32 v[26:27], v[26:27], v[98:99]
	v_pk_add_f32 v[28:29], v[28:29], v[100:101]
	v_pk_add_f32 v[26:27], v[26:27], v[102:103]
	v_pk_add_f32 v[28:29], v[28:29], v[104:105]
	v_pk_add_f32 v[26:27], v[26:27], v[128:129]
	v_pk_add_f32 v[28:29], v[28:29], v[130:131]
	global_store_dwordx4 v0, v[26:29], s[100:101] offset:2048
	s_waitcnt vmcnt(1)
	v_pk_add_f32 v[42:43], v[132:133], v[136:137]
	v_pk_add_f32 v[44:45], v[134:135], v[138:139]
	v_pk_add_f32 v[42:43], v[42:43], v[140:141]
	v_pk_add_f32 v[44:45], v[44:45], v[142:143]
	v_pk_add_f32 v[42:43], v[42:43], v[144:145]
	v_pk_add_f32 v[44:45], v[44:45], v[146:147]
	v_pk_add_f32 v[42:43], v[42:43], v[148:149]
	v_pk_add_f32 v[44:45], v[44:45], v[150:151]
	v_pk_add_f32 v[42:43], v[42:43], v[152:153]
	v_pk_add_f32 v[44:45], v[44:45], v[154:155]
	v_pk_add_f32 v[42:43], v[42:43], v[156:157]
	v_pk_add_f32 v[44:45], v[44:45], v[158:159]
	v_pk_add_f32 v[42:43], v[42:43], v[160:161]
	v_pk_add_f32 v[44:45], v[44:45], v[162:163]
	v_pk_add_f32 v[42:43], v[42:43], v[164:165]
	v_pk_add_f32 v[44:45], v[44:45], v[166:167]
	v_pk_add_f32 v[42:43], v[42:43], v[178:179]
	v_pk_add_f32 v[44:45], v[44:45], v[180:181]
	v_pk_add_f32 v[42:43], v[42:43], v[182:183]
	v_pk_add_f32 v[44:45], v[44:45], v[184:185]
	v_pk_add_f32 v[42:43], v[42:43], v[186:187]
	v_pk_add_f32 v[44:45], v[44:45], v[188:189]
	global_store_dwordx4 v0, v[42:45], s[100:101] offset:3072
	v_mul_f32_e32 v40, v3, v3
	v_mul_f32_e32 v30, v5, v5
	v_fmac_f32_e32 v40, v2, v2
	v_fmac_f32_e32 v30, v4, v4
	v_add_f32_e32 v40, v40, v30
	v_mul_f32_e32 v1, v7, v7
	v_mul_f32_e32 v30, v9, v9
	v_fmac_f32_e32 v1, v6, v6
	v_fmac_f32_e32 v30, v8, v8
	v_add_f32_e32 v1, v1, v30
	v_add_f32_e32 v40, v40, v1
	v_mul_f32_e32 v1, v11, v11
	v_mul_f32_e32 v30, v13, v13
	v_fmac_f32_e32 v1, v10, v10
	v_fmac_f32_e32 v30, v12, v12
	v_add_f32_e32 v1, v1, v30
	v_add_f32_e32 v40, v40, v1
	v_mul_f32_e32 v1, v15, v15
	v_mul_f32_e32 v30, v17, v17
	v_fmac_f32_e32 v1, v14, v14
	v_fmac_f32_e32 v30, v16, v16
	v_add_f32_e32 v1, v1, v30
	v_add_f32_e32 v40, v40, v1
	v_mul_f32_e32 v1, v19, v19
	v_mul_f32_e32 v30, v21, v21
	v_fmac_f32_e32 v1, v18, v18
	v_fmac_f32_e32 v30, v20, v20
	v_add_f32_e32 v1, v1, v30
	v_add_f32_e32 v40, v40, v1
	v_mul_f32_e32 v1, v23, v23
	v_mul_f32_e32 v30, v25, v25
	v_fmac_f32_e32 v1, v22, v22
	v_fmac_f32_e32 v30, v24, v24
	v_add_f32_e32 v1, v1, v30
	v_add_f32_e32 v40, v40, v1
	v_mul_f32_e32 v1, v27, v27
	v_mul_f32_e32 v30, v29, v29
	v_fmac_f32_e32 v1, v26, v26
	v_fmac_f32_e32 v30, v28, v28
	v_add_f32_e32 v1, v1, v30
	v_add_f32_e32 v40, v40, v1
	v_mul_f32_e32 v1, v43, v43
	v_mul_f32_e32 v30, v45, v45
	v_fmac_f32_e32 v1, v42, v42
	v_fmac_f32_e32 v30, v44, v44
	v_add_f32_e32 v1, v1, v30
	v_add_f32_e32 v40, v40, v1
	v_lshlrev_b32_e32 v38, 3, v211
	v_readfirstlane_b32 s4, v32
	v_readfirstlane_b32 s5, v33
	s_add_u32 s4, s4, s2
	s_addc_u32 s5, s5, s3
	s_add_u32 s4, s4, 0xc600000
	s_addc_u32 s5, s5, 0
	v_cvt_pk_bf16_f32 v106, v2, v3
	v_cvt_pk_bf16_f32 v107, v4, v5
	global_store_dwordx2 v38, v[106:107], s[4:5]
	v_cvt_pk_bf16_f32 v190, v6, v7
	v_cvt_pk_bf16_f32 v191, v8, v9
	global_store_dwordx2 v38, v[190:191], s[4:5] offset:512
	v_cvt_pk_bf16_f32 v192, v10, v11
	v_cvt_pk_bf16_f32 v193, v12, v13
	global_store_dwordx2 v38, v[192:193], s[4:5] offset:1024
	v_cvt_pk_bf16_f32 v194, v14, v15
	v_cvt_pk_bf16_f32 v195, v16, v17
	global_store_dwordx2 v38, v[194:195], s[4:5] offset:1536
	v_cvt_pk_bf16_f32 v196, v18, v19
	v_cvt_pk_bf16_f32 v197, v20, v21
	global_store_dwordx2 v38, v[196:197], s[4:5] offset:2048
	v_cvt_pk_bf16_f32 v198, v22, v23
	v_cvt_pk_bf16_f32 v199, v24, v25
	global_store_dwordx2 v38, v[198:199], s[4:5] offset:2560
	v_cvt_pk_bf16_f32 v200, v26, v27
	v_cvt_pk_bf16_f32 v201, v28, v29
	global_store_dwordx2 v38, v[200:201], s[4:5] offset:3072
	v_cvt_pk_bf16_f32 v202, v42, v43
	v_cvt_pk_bf16_f32 v203, v44, v45
	global_store_dwordx2 v38, v[202:203], s[4:5] offset:3584
	ds_bpermute_b32 v41, v62, v40
	s_waitcnt lgkmcnt(0)
	v_add_f32_e32 v40, v40, v41
	ds_bpermute_b32 v41, v63, v40
	s_waitcnt lgkmcnt(0)
	v_add_f32_e32 v40, v40, v41
	ds_bpermute_b32 v41, v64, v40
	s_waitcnt lgkmcnt(0)
	v_add_f32_e32 v40, v40, v41
	ds_bpermute_b32 v41, v65, v40
	s_waitcnt lgkmcnt(0)
	v_add_f32_e32 v40, v40, v41
	ds_bpermute_b32 v41, v66, v40
	s_waitcnt lgkmcnt(0)
	v_add_f32_e32 v40, v40, v41
	ds_bpermute_b32 v41, v67, v40
	s_and_saveexec_b64 s[4:5], s[40:41]
	s_cbranch_execz .LBB0_1018
	s_add_u32 s8, s2, s6
	s_waitcnt lgkmcnt(0)
	v_add_f32_e32 v0, v40, v41
	s_addc_u32 s9, s3, s7
	global_store_dword v169, v0, s[8:9]
	s_branch .LBB0_1018

; __device__ __forceinline__ float bf_lo(unsigned w) { return __uint_as_float(w << 16); }
; __device__ __forceinline__ float bf_hi(unsigned w) { return __uint_as_float(w & 0xffff0000u); }
; __global__ void __launch_bounds__(NTHR, 2) fwd_kernel(Args a) {
;     ...
;     for (int m = gw; m < MREAL; m += NGW) {
;         if (m >= MP) { sample_assemble(XR + (size_t)m * DM, XSP, 11, m - MP, XR + (size_t)m * DM, lane); rms_row_f32(XR + (size_t)m * DM, final_norm_g, out + O_YS + (size_t)(m - MP) * DM, lane); }
;         else { const u32x2* xr = (const u32x2*)(XN + (size_t)m * DM) + lane; f32x4 v[8]; float sq = 0.f;
; #pragma unroll
;             for (int j = 0; j < 8; ++j) { const u32x2 w = xr[64 * j]; v[j] = (f32x4){bf_lo(w.x), bf_hi(w.x), bf_lo(w.y), bf_hi(w.y)}; sq += (v[j].x * v[j].x + v[j].y * v[j].y) + (v[j].z * v[j].z + v[j].w * v[j].w); }
.Lfin_prompt_loop:
	s_mov_b32 s20, s3
	s_add_i32 s21, s20, s96
	s_add_i32 s22, s21, s96
	s_add_i32 s23, s22, s96
	s_cmp_lt_u32 s21, 0x2000
	s_cselect_b32 s25, 1, 0
	s_cselect_b32 s21, s21, s3
	s_cmp_lt_u32 s22, 0x2000
	s_cselect_b32 s26, 1, 0
	s_cselect_b32 s22, s22, s3
	s_cmp_lt_u32 s23, 0x2000
	s_cselect_b32 s27, 1, 0
	s_cselect_b32 s23, s23, s3
	s_lshl_b32 s16, s20, 12
	s_add_u32 s16, s10, s16
	s_addc_u32 s17, s11, 0
	global_load_dwordx2 v[48:49], v1, s[16:17] nt
	global_load_dwordx2 v[50:51], v1, s[16:17] offset:512 nt
	global_load_dwordx2 v[52:53], v1, s[16:17] offset:1024 nt
	global_load_dwordx2 v[54:55], v1, s[16:17] offset:1536 nt
	global_load_dwordx2 v[56:57], v1, s[16:17] offset:2048 nt
	global_load_dwordx2 v[58:59], v1, s[16:17] offset:2560 nt
	global_load_dwordx2 v[60:61], v1, s[16:17] offset:3072 nt
	global_load_dwordx2 v[62:63], v1, s[16:17] offset:3584 nt
	s_lshl_b32 s16, s21, 12
	s_add_u32 s16, s10, s16
	s_addc_u32 s17, s11, 0
	global_load_dwordx2 v[64:65], v1, s[16:17] nt
	global_load_dwordx2 v[66:67], v1, s[16:17] offset:512 nt
	global_load_dwordx2 v[68:69], v1, s[16:17] offset:1024 nt
	global_load_dwordx2 v[70:71], v1, s[16:17] offset:1536 nt
	global_load_dwordx2 v[72:73], v1, s[16:17] offset:2048 nt
	global_load_dwordx2 v[74:75], v1, s[16:17] offset:2560 nt
	global_load_dwordx2 v[76:77], v1, s[16:17] offset:3072 nt
	global_load_dwordx2 v[78:79], v1, s[16:17] offset:3584 nt
	s_lshl_b32 s16, s22, 12
	s_add_u32 s16, s10, s16
	s_addc_u32 s17, s11, 0
	global_load_dwordx2 v[80:81], v1, s[16:17] nt
	global_load_dwordx2 v[82:83], v1, s[16:17] offset:512 nt
	global_load_dwordx2 v[84:85], v1, s[16:17] offset:1024 nt
	global_load_dwordx2 v[86:87], v1, s[16:17] offset:1536 nt
	global_load_dwordx2 v[88:89], v1, s[16:17] offset:2048 nt
	global_load_dwordx2 v[90:91], v1, s[16:17] offset:2560 nt
	global_load_dwordx2 v[92:93], v1, s[16:17] offset:3072 nt
	global_load_dwordx2 v[94:95], v1, s[16:17] offset:3584 nt
	s_lshl_b32 s16, s23, 12
	s_add_u32 s16, s10, s16
	s_addc_u32 s17, s11, 0
	global_load_dwordx2 v[96:97], v1, s[16:17] nt
	global_load_dwordx2 v[98:99], v1, s[16:17] offset:512 nt
	global_load_dwordx2 v[100:101], v1, s[16:17] offset:1024 nt
	global_load_dwordx2 v[102:103], v1, s[16:17] offset:1536 nt
	global_load_dwordx2 v[104:105], v1, s[16:17] offset:2048 nt
	global_load_dwordx2 v[106:107], v1, s[16:17] offset:2560 nt
	global_load_dwordx2 v[108:109], v1, s[16:17] offset:3072 nt
	global_load_dwordx2 v[110:111], v1, s[16:17] offset:3584 nt
	s_waitcnt vmcnt(24)
	v_lshlrev_b32_e32 v112, 16, v48
	v_and_b32_e32 v113, 0xffff0000, v48
	v_lshlrev_b32_e32 v114, 16, v49
	v_and_b32_e32 v115, 0xffff0000, v49
	v_mul_f32_e32 v10, v113, v113
	v_mul_f32_e32 v247, v115, v115
	v_fmac_f32_e32 v10, v112, v112
	v_fmac_f32_e32 v247, v114, v114
	v_add_f32_e32 v10, v10, v247
	v_lshlrev_b32_e32 v116, 16, v50
	v_and_b32_e32 v117, 0xffff0000, v50
	v_lshlrev_b32_e32 v118, 16, v51
	v_and_b32_e32 v119, 0xffff0000, v51
	v_mul_f32_e32 v245, v117, v117
	v_mul_f32_e32 v247, v119, v119
	v_fmac_f32_e32 v245, v116, v116
	v_fmac_f32_e32 v247, v118, v118
	v_add_f32_e32 v245, v245, v247
	v_add_f32_e32 v10, v10, v245
	v_lshlrev_b32_e32 v120, 16, v52
	v_and_b32_e32 v121, 0xffff0000, v52
	v_lshlrev_b32_e32 v122, 16, v53
	v_and_b32_e32 v123, 0xffff0000, v53
	v_mul_f32_e32 v245, v121, v121
	v_mul_f32_e32 v247, v123, v123
	v_fmac_f32_e32 v245, v120, v120
	v_fmac_f32_e32 v247, v122, v122
	v_add_f32_e32 v245, v245, v247
	v_add_f32_e32 v10, v10, v245
	v_lshlrev_b32_e32 v124, 16, v54
	v_and_b32_e32 v125, 0xffff0000, v54
	v_lshlrev_b32_e32 v126, 16, v55
	v_and_b32_e32 v127, 0xffff0000, v55
	v_mul_f32_e32 v245, v125, v125
	v_mul_f32_e32 v247, v127, v127
	v_fmac_f32_e32 v245, v124, v124
	v_fmac_f32_e32 v247, v126, v126
	v_add_f32_e32 v245, v245, v247
	v_add_f32_e32 v10, v10, v245
	v_lshlrev_b32_e32 v128, 16, v56
	v_and_b32_e32 v129, 0xffff0000, v56
	v_lshlrev_b32_e32 v130, 16, v57
	v_and_b32_e32 v131, 0xffff0000, v57
	v_mul_f32_e32 v245, v129, v129
	v_mul_f32_e32 v247, v131, v131
	v_fmac_f32_e32 v245, v128, v128
	v_fmac_f32_e32 v247, v130, v130
	v_add_f32_e32 v245, v245, v247
	v_add_f32_e32 v10, v10, v245
	v_lshlrev_b32_e32 v132, 16, v58
	v_and_b32_e32 v133, 0xffff0000, v58
	v_lshlrev_b32_e32 v134, 16, v59
	v_and_b32_e32 v135, 0xffff0000, v59
	v_mul_f32_e32 v245, v133, v133
	v_mul_f32_e32 v247, v135, v135
	v_fmac_f32_e32 v245, v132, v132
	v_fmac_f32_e32 v247, v134, v134
	v_add_f32_e32 v245, v245, v247
	v_add_f32_e32 v10, v10, v245
	v_lshlrev_b32_e32 v136, 16, v60
	v_and_b32_e32 v137, 0xffff0000, v60
	v_lshlrev_b32_e32 v138, 16, v61
	v_and_b32_e32 v139, 0xffff0000, v61
	v_mul_f32_e32 v245, v137, v137
	v_mul_f32_e32 v247, v139, v139
	v_fmac_f32_e32 v245, v136, v136
	v_fmac_f32_e32 v247, v138, v138
	v_add_f32_e32 v245, v245, v247
	v_add_f32_e32 v10, v10, v245
	v_lshlrev_b32_e32 v140, 16, v62
	v_and_b32_e32 v141, 0xffff0000, v62
	v_lshlrev_b32_e32 v142, 16, v63
	v_and_b32_e32 v143, 0xffff0000, v63
	v_mul_f32_e32 v245, v141, v141
	v_mul_f32_e32 v247, v143, v143
	v_fmac_f32_e32 v245, v140, v140
	v_fmac_f32_e32 v247, v142, v142
	v_add_f32_e32 v245, v245, v247
	v_add_f32_e32 v10, v10, v245
	s_waitcnt vmcnt(16)
; __device__ __forceinline__ float bf_lo(unsigned w) { return __uint_as_float(w << 16); }
; __device__ __forceinline__ float bf_hi(unsigned w) { return __uint_as_float(w & 0xffff0000u); }
; __global__ void __launch_bounds__(NTHR, 2) fwd_kernel(Args a) {
;     ...
;         else { const u32x2* xr = (const u32x2*)(XN + (size_t)m * DM) + lane; f32x4 v[8]; float sq = 0.f;
; #pragma unroll
;             for (int j = 0; j < 8; ++j) { const u32x2 w = xr[64 * j]; v[j] = (f32x4){bf_lo(w.x), bf_hi(w.x), bf_lo(w.y), bf_hi(w.y)}; sq += (v[j].x * v[j].x + v[j].y * v[j].y) + (v[j].z * v[j].z + v[j].w * v[j].w); }
	v_lshlrev_b32_e32 v144, 16, v64
	v_and_b32_e32 v145, 0xffff0000, v64
	v_lshlrev_b32_e32 v146, 16, v65
	v_and_b32_e32 v147, 0xffff0000, v65
	v_mul_f32_e32 v12, v145, v145
	v_mul_f32_e32 v247, v147, v147
	v_fmac_f32_e32 v12, v144, v144
	v_fmac_f32_e32 v247, v146, v146
	v_add_f32_e32 v12, v12, v247
	v_lshlrev_b32_e32 v148, 16, v66
	v_and_b32_e32 v149, 0xffff0000, v66
	v_lshlrev_b32_e32 v150, 16, v67
	v_and_b32_e32 v151, 0xffff0000, v67
	v_mul_f32_e32 v245, v149, v149
	v_mul_f32_e32 v247, v151, v151
	v_fmac_f32_e32 v245, v148, v148
	v_fmac_f32_e32 v247, v150, v150
	v_add_f32_e32 v245, v245, v247
	v_add_f32_e32 v12, v12, v245
	v_lshlrev_b32_e32 v152, 16, v68
	v_and_b32_e32 v153, 0xffff0000, v68
	v_lshlrev_b32_e32 v154, 16, v69
	v_and_b32_e32 v155, 0xffff0000, v69
	v_mul_f32_e32 v245, v153, v153
	v_mul_f32_e32 v247, v155, v155
	v_fmac_f32_e32 v245, v152, v152
	v_fmac_f32_e32 v247, v154, v154
	v_add_f32_e32 v245, v245, v247
	v_add_f32_e32 v12, v12, v245
	v_lshlrev_b32_e32 v156, 16, v70
	v_and_b32_e32 v157, 0xffff0000, v70
	v_lshlrev_b32_e32 v158, 16, v71
	v_and_b32_e32 v159, 0xffff0000, v71
	v_mul_f32_e32 v245, v157, v157
	v_mul_f32_e32 v247, v159, v159
	v_fmac_f32_e32 v245, v156, v156
	v_fmac_f32_e32 v247, v158, v158
	v_add_f32_e32 v245, v245, v247
	v_add_f32_e32 v12, v12, v245
	v_lshlrev_b32_e32 v160, 16, v72
	v_and_b32_e32 v161, 0xffff0000, v72
	v_lshlrev_b32_e32 v162, 16, v73
	v_and_b32_e32 v163, 0xffff0000, v73
	v_mul_f32_e32 v245, v161, v161
	v_mul_f32_e32 v247, v163, v163
	v_fmac_f32_e32 v245, v160, v160
	v_fmac_f32_e32 v247, v162, v162
	v_add_f32_e32 v245, v245, v247
	v_add_f32_e32 v12, v12, v245
	v_lshlrev_b32_e32 v164, 16, v74
	v_and_b32_e32 v165, 0xffff0000, v74
	v_lshlrev_b32_e32 v166, 16, v75
	v_and_b32_e32 v167, 0xffff0000, v75
	v_mul_f32_e32 v245, v165, v165
	v_mul_f32_e32 v247, v167, v167
	v_fmac_f32_e32 v245, v164, v164
	v_fmac_f32_e32 v247, v166, v166
	v_add_f32_e32 v245, v245, v247
	v_add_f32_e32 v12, v12, v245
	v_lshlrev_b32_e32 v168, 16, v76
	v_and_b32_e32 v169, 0xffff0000, v76
	v_lshlrev_b32_e32 v170, 16, v77
	v_and_b32_e32 v171, 0xffff0000, v77
	v_mul_f32_e32 v245, v169, v169
	v_mul_f32_e32 v247, v171, v171
	v_fmac_f32_e32 v245, v168, v168
	v_fmac_f32_e32 v247, v170, v170
	v_add_f32_e32 v245, v245, v247
	v_add_f32_e32 v12, v12, v245
	v_lshlrev_b32_e32 v172, 16, v78
	v_and_b32_e32 v173, 0xffff0000, v78
	v_lshlrev_b32_e32 v174, 16, v79
	v_and_b32_e32 v175, 0xffff0000, v79
	v_mul_f32_e32 v245, v173, v173
	v_mul_f32_e32 v247, v175, v175
	v_fmac_f32_e32 v245, v172, v172
	v_fmac_f32_e32 v247, v174, v174
	v_add_f32_e32 v245, v245, v247
	v_add_f32_e32 v12, v12, v245
	s_waitcnt vmcnt(8)
	v_lshlrev_b32_e32 v176, 16, v80
	v_and_b32_e32 v177, 0xffff0000, v80
	v_lshlrev_b32_e32 v178, 16, v81
	v_and_b32_e32 v179, 0xffff0000, v81
	v_mul_f32_e32 v14, v177, v177
	v_mul_f32_e32 v247, v179, v179
	v_fmac_f32_e32 v14, v176, v176
	v_fmac_f32_e32 v247, v178, v178
	v_add_f32_e32 v14, v14, v247
	v_lshlrev_b32_e32 v180, 16, v82
	v_and_b32_e32 v181, 0xffff0000, v82
	v_lshlrev_b32_e32 v182, 16, v83
	v_and_b32_e32 v183, 0xffff0000, v83
	v_mul_f32_e32 v245, v181, v181
	v_mul_f32_e32 v247, v183, v183
	v_fmac_f32_e32 v245, v180, v180
	v_fmac_f32_e32 v247, v182, v182
	v_add_f32_e32 v245, v245, v247
	v_add_f32_e32 v14, v14, v245
	v_lshlrev_b32_e32 v184, 16, v84
	v_and_b32_e32 v185, 0xffff0000, v84
	v_lshlrev_b32_e32 v186, 16, v85
	v_and_b32_e32 v187, 0xffff0000, v85
	v_mul_f32_e32 v245, v185, v185
	v_mul_f32_e32 v247, v187, v187
	v_fmac_f32_e32 v245, v184, v184
	v_fmac_f32_e32 v247, v186, v186
	v_add_f32_e32 v245, v245, v247
	v_add_f32_e32 v14, v14, v245
	v_lshlrev_b32_e32 v188, 16, v86
	v_and_b32_e32 v189, 0xffff0000, v86
	v_lshlrev_b32_e32 v190, 16, v87
	v_and_b32_e32 v191, 0xffff0000, v87
	v_mul_f32_e32 v245, v189, v189
	v_mul_f32_e32 v247, v191, v191
	v_fmac_f32_e32 v245, v188, v188
	v_fmac_f32_e32 v247, v190, v190
	v_add_f32_e32 v245, v245, v247
	v_add_f32_e32 v14, v14, v245
	v_lshlrev_b32_e32 v192, 16, v88
	v_and_b32_e32 v193, 0xffff0000, v88
	v_lshlrev_b32_e32 v194, 16, v89
	v_and_b32_e32 v195, 0xffff0000, v89
	v_mul_f32_e32 v245, v193, v193
	v_mul_f32_e32 v247, v195, v195
	v_fmac_f32_e32 v245, v192, v192
	v_fmac_f32_e32 v247, v194, v194
	v_add_f32_e32 v245, v245, v247
	v_add_f32_e32 v14, v14, v245
	v_lshlrev_b32_e32 v196, 16, v90
	v_and_b32_e32 v197, 0xffff0000, v90
	v_lshlrev_b32_e32 v198, 16, v91
	v_and_b32_e32 v199, 0xffff0000, v91
	v_mul_f32_e32 v245, v197, v197
	v_mul_f32_e32 v247, v199, v199
	v_fmac_f32_e32 v245, v196, v196
	v_fmac_f32_e32 v247, v198, v198
	v_add_f32_e32 v245, v245, v247
	v_add_f32_e32 v14, v14, v245
	v_lshlrev_b32_e32 v200, 16, v92
	v_and_b32_e32 v201, 0xffff0000, v92
	v_lshlrev_b32_e32 v202, 16, v93
	v_and_b32_e32 v203, 0xffff0000, v93
	v_mul_f32_e32 v245, v201, v201
	v_mul_f32_e32 v247, v203, v203
	v_fmac_f32_e32 v245, v200, v200
	v_fmac_f32_e32 v247, v202, v202
	v_add_f32_e32 v245, v245, v247
	v_add_f32_e32 v14, v14, v245
	v_lshlrev_b32_e32 v204, 16, v94
	v_and_b32_e32 v205, 0xffff0000, v94
	v_lshlrev_b32_e32 v206, 16, v95
	v_and_b32_e32 v207, 0xffff0000, v95
	v_mul_f32_e32 v245, v205, v205
	v_mul_f32_e32 v247, v207, v207
	v_fmac_f32_e32 v245, v204, v204
	v_fmac_f32_e32 v247, v206, v206
	v_add_f32_e32 v245, v245, v247
	v_add_f32_e32 v14, v14, v245
	s_waitcnt vmcnt(0)
; __device__ __forceinline__ float bf_lo(unsigned w) { return __uint_as_float(w << 16); }
; __device__ __forceinline__ float bf_hi(unsigned w) { return __uint_as_float(w & 0xffff0000u); }
; __device__ __forceinline__ float wave_sum(float v) {
; #pragma unroll
;     for (int o = 1; o < 64; o <<= 1) v += __shfl_xor(v, o);
;     return v;
; }
; __global__ void __launch_bounds__(NTHR, 2) fwd_kernel(Args a) {
;     ...
;             for (int j = 0; j < 8; ++j) { const u32x2 w = xr[64 * j]; v[j] = (f32x4){bf_lo(w.x), bf_hi(w.x), bf_lo(w.y), bf_hi(w.y)}; sq += (v[j].x * v[j].x + v[j].y * v[j].y) + (v[j].z * v[j].z + v[j].w * v[j].w); }
;             const float rstd = rsqrtf(wave_sum(sq) * (1.f / DM) + EPS); const f32x4* gr = (const f32x4*)final_norm_g + lane; f32x4* o = (f32x4*)(out + O_YP + (size_t)m * DM) + lane;
	v_lshlrev_b32_e32 v208, 16, v96
	v_and_b32_e32 v209, 0xffff0000, v96
	v_lshlrev_b32_e32 v210, 16, v97
	v_and_b32_e32 v211, 0xffff0000, v97
	v_mul_f32_e32 v240, v209, v209
	v_mul_f32_e32 v247, v211, v211
	v_fmac_f32_e32 v240, v208, v208
	v_fmac_f32_e32 v247, v210, v210
	v_add_f32_e32 v240, v240, v247
	v_lshlrev_b32_e32 v212, 16, v98
	v_and_b32_e32 v213, 0xffff0000, v98
	v_lshlrev_b32_e32 v214, 16, v99
	v_and_b32_e32 v215, 0xffff0000, v99
	v_mul_f32_e32 v245, v213, v213
	v_mul_f32_e32 v247, v215, v215
	v_fmac_f32_e32 v245, v212, v212
	v_fmac_f32_e32 v247, v214, v214
	v_add_f32_e32 v245, v245, v247
	v_add_f32_e32 v240, v240, v245
	v_lshlrev_b32_e32 v216, 16, v100
	v_and_b32_e32 v217, 0xffff0000, v100
	v_lshlrev_b32_e32 v218, 16, v101
	v_and_b32_e32 v219, 0xffff0000, v101
	v_mul_f32_e32 v245, v217, v217
	v_mul_f32_e32 v247, v219, v219
	v_fmac_f32_e32 v245, v216, v216
	v_fmac_f32_e32 v247, v218, v218
	v_add_f32_e32 v245, v245, v247
	v_add_f32_e32 v240, v240, v245
	v_lshlrev_b32_e32 v220, 16, v102
	v_and_b32_e32 v221, 0xffff0000, v102
	v_lshlrev_b32_e32 v222, 16, v103
	v_and_b32_e32 v223, 0xffff0000, v103
	v_mul_f32_e32 v245, v221, v221
	v_mul_f32_e32 v247, v223, v223
	v_fmac_f32_e32 v245, v220, v220
	v_fmac_f32_e32 v247, v222, v222
	v_add_f32_e32 v245, v245, v247
	v_add_f32_e32 v240, v240, v245
	v_lshlrev_b32_e32 v224, 16, v104
	v_and_b32_e32 v225, 0xffff0000, v104
	v_lshlrev_b32_e32 v226, 16, v105
	v_and_b32_e32 v227, 0xffff0000, v105
	v_mul_f32_e32 v245, v225, v225
	v_mul_f32_e32 v247, v227, v227
	v_fmac_f32_e32 v245, v224, v224
	v_fmac_f32_e32 v247, v226, v226
	v_add_f32_e32 v245, v245, v247
	v_add_f32_e32 v240, v240, v245
	v_lshlrev_b32_e32 v228, 16, v106
	v_and_b32_e32 v229, 0xffff0000, v106
	v_lshlrev_b32_e32 v230, 16, v107
	v_and_b32_e32 v231, 0xffff0000, v107
	v_mul_f32_e32 v245, v229, v229
	v_mul_f32_e32 v247, v231, v231
	v_fmac_f32_e32 v245, v228, v228
	v_fmac_f32_e32 v247, v230, v230
	v_add_f32_e32 v245, v245, v247
	v_add_f32_e32 v240, v240, v245
	v_lshlrev_b32_e32 v232, 16, v108
	v_and_b32_e32 v233, 0xffff0000, v108
	v_lshlrev_b32_e32 v234, 16, v109
	v_and_b32_e32 v235, 0xffff0000, v109
	v_mul_f32_e32 v245, v233, v233
	v_mul_f32_e32 v247, v235, v235
	v_fmac_f32_e32 v245, v232, v232
	v_fmac_f32_e32 v247, v234, v234
	v_add_f32_e32 v245, v245, v247
	v_add_f32_e32 v240, v240, v245
	v_lshlrev_b32_e32 v236, 16, v110
	v_and_b32_e32 v237, 0xffff0000, v110
	v_lshlrev_b32_e32 v238, 16, v111
	v_and_b32_e32 v239, 0xffff0000, v111
	v_mul_f32_e32 v245, v237, v237
	v_mul_f32_e32 v247, v239, v239
	v_fmac_f32_e32 v245, v236, v236
	v_fmac_f32_e32 v247, v238, v238
	v_add_f32_e32 v245, v245, v247
	v_add_f32_e32 v240, v240, v245
	ds_bpermute_b32 v241, v3, v10
	ds_bpermute_b32 v242, v3, v12
	ds_bpermute_b32 v243, v3, v14
	ds_bpermute_b32 v244, v3, v240
	s_waitcnt lgkmcnt(0)
	v_add_f32_e32 v10, v10, v241
	v_add_f32_e32 v12, v12, v242
	v_add_f32_e32 v14, v14, v243
	v_add_f32_e32 v240, v240, v244
	ds_bpermute_b32 v241, v4, v10
	ds_bpermute_b32 v242, v4, v12
	ds_bpermute_b32 v243, v4, v14
	ds_bpermute_b32 v244, v4, v240
	s_waitcnt lgkmcnt(0)
	v_add_f32_e32 v10, v10, v241
	v_add_f32_e32 v12, v12, v242
	v_add_f32_e32 v14, v14, v243
	v_add_f32_e32 v240, v240, v244
	ds_bpermute_b32 v241, v5, v10
	ds_bpermute_b32 v242, v5, v12
	ds_bpermute_b32 v243, v5, v14
	ds_bpermute_b32 v244, v5, v240
	s_waitcnt lgkmcnt(0)
	v_add_f32_e32 v10, v10, v241
	v_add_f32_e32 v12, v12, v242
	v_add_f32_e32 v14, v14, v243
	v_add_f32_e32 v240, v240, v244
	ds_bpermute_b32 v241, v6, v10
	ds_bpermute_b32 v242, v6, v12
	ds_bpermute_b32 v243, v6, v14
	ds_bpermute_b32 v244, v6, v240
	s_waitcnt lgkmcnt(0)
	v_add_f32_e32 v10, v10, v241
	v_add_f32_e32 v12, v12, v242
	v_add_f32_e32 v14, v14, v243
	v_add_f32_e32 v240, v240, v244
	ds_bpermute_b32 v241, v7, v10
	ds_bpermute_b32 v242, v7, v12
	ds_bpermute_b32 v243, v7, v14
	ds_bpermute_b32 v244, v7, v240
	s_waitcnt lgkmcnt(0)
	v_add_f32_e32 v10, v10, v241
	v_add_f32_e32 v12, v12, v242
	v_add_f32_e32 v14, v14, v243
	v_add_f32_e32 v240, v240, v244
	ds_bpermute_b32 v241, v8, v10
	ds_bpermute_b32 v242, v8, v12
	ds_bpermute_b32 v243, v8, v14
	ds_bpermute_b32 v244, v8, v240
	s_waitcnt lgkmcnt(0)
	v_add_f32_e32 v10, v10, v241
	v_add_f32_e32 v12, v12, v242
	v_add_f32_e32 v14, v14, v243
	v_add_f32_e32 v240, v240, v244
	v_fmamk_f32 v10, v10, 0x3a000000, v9
	v_mul_f32_e32 v245, 0x4b800000, v10
	v_cmp_gt_f32_e32 vcc, s12, v10
	s_nop 1
	v_cndmask_b32_e32 v10, v10, v245, vcc
	v_rsq_f32_e32 v10, v10
	s_nop 0
	v_mul_f32_e32 v245, 0x45800000, v10
	v_cndmask_b32_e32 v10, v10, v245, vcc
	v_fmamk_f32 v12, v12, 0x3a000000, v9
	v_mul_f32_e32 v245, 0x4b800000, v12
	v_cmp_gt_f32_e32 vcc, s12, v12
	s_nop 1
	v_cndmask_b32_e32 v12, v12, v245, vcc
	v_rsq_f32_e32 v12, v12
	s_nop 0
	v_mul_f32_e32 v245, 0x45800000, v12
	v_cndmask_b32_e32 v12, v12, v245, vcc
	v_fmamk_f32 v14, v14, 0x3a000000, v9
	v_mul_f32_e32 v245, 0x4b800000, v14
	v_cmp_gt_f32_e32 vcc, s12, v14
	s_nop 1
	v_cndmask_b32_e32 v14, v14, v245, vcc
	v_rsq_f32_e32 v14, v14
	s_nop 0
	v_mul_f32_e32 v245, 0x45800000, v14
	v_cndmask_b32_e32 v14, v14, v245, vcc
	v_fmamk_f32 v240, v240, 0x3a000000, v9
	v_mul_f32_e32 v245, 0x4b800000, v240
	v_cmp_gt_f32_e32 vcc, s12, v240
	s_nop 1
	v_cndmask_b32_e32 v240, v240, v245, vcc
	v_rsq_f32_e32 v240, v240
	s_nop 0
	v_mul_f32_e32 v245, 0x45800000, v240
	v_cndmask_b32_e32 v240, v240, v245, vcc
	s_waitcnt vmcnt(0)
; __global__ void __launch_bounds__(NTHR, 2) fwd_kernel(Args a) {
;     ...
;             const float rstd = rsqrtf(wave_sum(sq) * (1.f / DM) + EPS); const f32x4* gr = (const f32x4*)final_norm_g + lane; f32x4* o = (f32x4*)(out + O_YP + (size_t)m * DM) + lane;
; #pragma unroll
;             for (int j = 0; j < 8; ++j) o[64 * j] = v[j] * rstd * gr[64 * j]; } }
	s_lshl_b32 s16, s20, 13
	s_add_u32 s16, s6, s16
	s_addc_u32 s17, s7, 0
	v_pk_mul_f32 v[112:113], v[10:11], v[112:113] op_sel_hi:[0,1]
	v_pk_mul_f32 v[114:115], v[10:11], v[114:115] op_sel_hi:[0,1]
	v_pk_mul_f32 v[112:113], v[112:113], v[16:17]
	v_pk_mul_f32 v[114:115], v[114:115], v[18:19]
	global_store_dwordx4 v0, v[112:115], s[16:17] nt
	v_pk_mul_f32 v[116:117], v[10:11], v[116:117] op_sel_hi:[0,1]
	v_pk_mul_f32 v[118:119], v[10:11], v[118:119] op_sel_hi:[0,1]
	v_pk_mul_f32 v[116:117], v[116:117], v[20:21]
	v_pk_mul_f32 v[118:119], v[118:119], v[22:23]
	global_store_dwordx4 v0, v[116:119], s[16:17] offset:1024 nt
	v_pk_mul_f32 v[120:121], v[10:11], v[120:121] op_sel_hi:[0,1]
	v_pk_mul_f32 v[122:123], v[10:11], v[122:123] op_sel_hi:[0,1]
	v_pk_mul_f32 v[120:121], v[120:121], v[24:25]
	v_pk_mul_f32 v[122:123], v[122:123], v[26:27]
	global_store_dwordx4 v0, v[120:123], s[16:17] offset:2048 nt
	v_pk_mul_f32 v[124:125], v[10:11], v[124:125] op_sel_hi:[0,1]
	v_pk_mul_f32 v[126:127], v[10:11], v[126:127] op_sel_hi:[0,1]
	v_pk_mul_f32 v[124:125], v[124:125], v[28:29]
	v_pk_mul_f32 v[126:127], v[126:127], v[30:31]
	global_store_dwordx4 v0, v[124:127], s[16:17] offset:3072 nt
	v_pk_mul_f32 v[128:129], v[10:11], v[128:129] op_sel_hi:[0,1]
	v_pk_mul_f32 v[130:131], v[10:11], v[130:131] op_sel_hi:[0,1]
	v_pk_mul_f32 v[128:129], v[128:129], v[32:33]
	v_pk_mul_f32 v[130:131], v[130:131], v[34:35]
	global_store_dwordx4 v2, v[128:131], s[16:17] nt
	v_pk_mul_f32 v[132:133], v[10:11], v[132:133] op_sel_hi:[0,1]
	v_pk_mul_f32 v[134:135], v[10:11], v[134:135] op_sel_hi:[0,1]
	v_pk_mul_f32 v[132:133], v[132:133], v[36:37]
	v_pk_mul_f32 v[134:135], v[134:135], v[38:39]
	global_store_dwordx4 v2, v[132:135], s[16:17] offset:1024 nt
	v_pk_mul_f32 v[136:137], v[10:11], v[136:137] op_sel_hi:[0,1]
	v_pk_mul_f32 v[138:139], v[10:11], v[138:139] op_sel_hi:[0,1]
	v_pk_mul_f32 v[136:137], v[136:137], v[40:41]
	v_pk_mul_f32 v[138:139], v[138:139], v[42:43]
	global_store_dwordx4 v2, v[136:139], s[16:17] offset:2048 nt
	v_pk_mul_f32 v[140:141], v[10:11], v[140:141] op_sel_hi:[0,1]
	v_pk_mul_f32 v[142:143], v[10:11], v[142:143] op_sel_hi:[0,1]
	v_pk_mul_f32 v[140:141], v[140:141], v[44:45]
	v_pk_mul_f32 v[142:143], v[142:143], v[46:47]
	global_store_dwordx4 v2, v[140:143], s[16:17] offset:3072 nt
	s_cmp_eq_u32 s25, 0
	s_cbranch_scc1 .Lfin_skip_1
	s_lshl_b32 s16, s21, 13
	s_add_u32 s16, s6, s16
	s_addc_u32 s17, s7, 0
	v_pk_mul_f32 v[144:145], v[12:13], v[144:145] op_sel_hi:[0,1]
	v_pk_mul_f32 v[146:147], v[12:13], v[146:147] op_sel_hi:[0,1]
	v_pk_mul_f32 v[144:145], v[144:145], v[16:17]
	v_pk_mul_f32 v[146:147], v[146:147], v[18:19]
	global_store_dwordx4 v0, v[144:147], s[16:17] nt
	v_pk_mul_f32 v[148:149], v[12:13], v[148:149] op_sel_hi:[0,1]
	v_pk_mul_f32 v[150:151], v[12:13], v[150:151] op_sel_hi:[0,1]
	v_pk_mul_f32 v[148:149], v[148:149], v[20:21]
	v_pk_mul_f32 v[150:151], v[150:151], v[22:23]
	global_store_dwordx4 v0, v[148:151], s[16:17] offset:1024 nt
	v_pk_mul_f32 v[152:153], v[12:13], v[152:153] op_sel_hi:[0,1]
	v_pk_mul_f32 v[154:155], v[12:13], v[154:155] op_sel_hi:[0,1]
	v_pk_mul_f32 v[152:153], v[152:153], v[24:25]
	v_pk_mul_f32 v[154:155], v[154:155], v[26:27]
	global_store_dwordx4 v0, v[152:155], s[16:17] offset:2048 nt
	v_pk_mul_f32 v[156:157], v[12:13], v[156:157] op_sel_hi:[0,1]
	v_pk_mul_f32 v[158:159], v[12:13], v[158:159] op_sel_hi:[0,1]
	v_pk_mul_f32 v[156:157], v[156:157], v[28:29]
	v_pk_mul_f32 v[158:159], v[158:159], v[30:31]
	global_store_dwordx4 v0, v[156:159], s[16:17] offset:3072 nt
	v_pk_mul_f32 v[160:161], v[12:13], v[160:161] op_sel_hi:[0,1]
	v_pk_mul_f32 v[162:163], v[12:13], v[162:163] op_sel_hi:[0,1]
	v_pk_mul_f32 v[160:161], v[160:161], v[32:33]
	v_pk_mul_f32 v[162:163], v[162:163], v[34:35]
	global_store_dwordx4 v2, v[160:163], s[16:17] nt
	v_pk_mul_f32 v[164:165], v[12:13], v[164:165] op_sel_hi:[0,1]
	v_pk_mul_f32 v[166:167], v[12:13], v[166:167] op_sel_hi:[0,1]
	v_pk_mul_f32 v[164:165], v[164:165], v[36:37]
	v_pk_mul_f32 v[166:167], v[166:167], v[38:39]
	global_store_dwordx4 v2, v[164:167], s[16:17] offset:1024 nt
	v_pk_mul_f32 v[168:169], v[12:13], v[168:169] op_sel_hi:[0,1]
	v_pk_mul_f32 v[170:171], v[12:13], v[170:171] op_sel_hi:[0,1]
	v_pk_mul_f32 v[168:169], v[168:169], v[40:41]
	v_pk_mul_f32 v[170:171], v[170:171], v[42:43]
	global_store_dwordx4 v2, v[168:171], s[16:17] offset:2048 nt
	v_pk_mul_f32 v[172:173], v[12:13], v[172:173] op_sel_hi:[0,1]
	v_pk_mul_f32 v[174:175], v[12:13], v[174:175] op_sel_hi:[0,1]
	v_pk_mul_f32 v[172:173], v[172:173], v[44:45]
	v_pk_mul_f32 v[174:175], v[174:175], v[46:47]
	global_store_dwordx4 v2, v[172:175], s[16:17] offset:3072 nt
; __global__ void __launch_bounds__(NTHR, 2) fwd_kernel(Args a) {
;     ...
;             const float rstd = rsqrtf(wave_sum(sq) * (1.f / DM) + EPS); const f32x4* gr = (const f32x4*)final_norm_g + lane; f32x4* o = (f32x4*)(out + O_YP + (size_t)m * DM) + lane;
; #pragma unroll
;             for (int j = 0; j < 8; ++j) o[64 * j] = v[j] * rstd * gr[64 * j]; } }
.Lfin_skip_1:
	s_cmp_eq_u32 s26, 0
	s_cbranch_scc1 .Lfin_skip_2
	s_lshl_b32 s16, s22, 13
	s_add_u32 s16, s6, s16
	s_addc_u32 s17, s7, 0
	v_pk_mul_f32 v[176:177], v[14:15], v[176:177] op_sel_hi:[0,1]
	v_pk_mul_f32 v[178:179], v[14:15], v[178:179] op_sel_hi:[0,1]
	v_pk_mul_f32 v[176:177], v[176:177], v[16:17]
	v_pk_mul_f32 v[178:179], v[178:179], v[18:19]
	global_store_dwordx4 v0, v[176:179], s[16:17] nt
	v_pk_mul_f32 v[180:181], v[14:15], v[180:181] op_sel_hi:[0,1]
	v_pk_mul_f32 v[182:183], v[14:15], v[182:183] op_sel_hi:[0,1]
	v_pk_mul_f32 v[180:181], v[180:181], v[20:21]
	v_pk_mul_f32 v[182:183], v[182:183], v[22:23]
	global_store_dwordx4 v0, v[180:183], s[16:17] offset:1024 nt
	v_pk_mul_f32 v[184:185], v[14:15], v[184:185] op_sel_hi:[0,1]
	v_pk_mul_f32 v[186:187], v[14:15], v[186:187] op_sel_hi:[0,1]
	v_pk_mul_f32 v[184:185], v[184:185], v[24:25]
	v_pk_mul_f32 v[186:187], v[186:187], v[26:27]
	global_store_dwordx4 v0, v[184:187], s[16:17] offset:2048 nt
	v_pk_mul_f32 v[188:189], v[14:15], v[188:189] op_sel_hi:[0,1]
	v_pk_mul_f32 v[190:191], v[14:15], v[190:191] op_sel_hi:[0,1]
	v_pk_mul_f32 v[188:189], v[188:189], v[28:29]
	v_pk_mul_f32 v[190:191], v[190:191], v[30:31]
	global_store_dwordx4 v0, v[188:191], s[16:17] offset:3072 nt
	v_pk_mul_f32 v[192:193], v[14:15], v[192:193] op_sel_hi:[0,1]
	v_pk_mul_f32 v[194:195], v[14:15], v[194:195] op_sel_hi:[0,1]
	v_pk_mul_f32 v[192:193], v[192:193], v[32:33]
	v_pk_mul_f32 v[194:195], v[194:195], v[34:35]
	global_store_dwordx4 v2, v[192:195], s[16:17] nt
	v_pk_mul_f32 v[196:197], v[14:15], v[196:197] op_sel_hi:[0,1]
	v_pk_mul_f32 v[198:199], v[14:15], v[198:199] op_sel_hi:[0,1]
	v_pk_mul_f32 v[196:197], v[196:197], v[36:37]
	v_pk_mul_f32 v[198:199], v[198:199], v[38:39]
	global_store_dwordx4 v2, v[196:199], s[16:17] offset:1024 nt
	v_pk_mul_f32 v[200:201], v[14:15], v[200:201] op_sel_hi:[0,1]
	v_pk_mul_f32 v[202:203], v[14:15], v[202:203] op_sel_hi:[0,1]
	v_pk_mul_f32 v[200:201], v[200:201], v[40:41]
	v_pk_mul_f32 v[202:203], v[202:203], v[42:43]
	global_store_dwordx4 v2, v[200:203], s[16:17] offset:2048 nt
	v_pk_mul_f32 v[204:205], v[14:15], v[204:205] op_sel_hi:[0,1]
	v_pk_mul_f32 v[206:207], v[14:15], v[206:207] op_sel_hi:[0,1]
	v_pk_mul_f32 v[204:205], v[204:205], v[44:45]
	v_pk_mul_f32 v[206:207], v[206:207], v[46:47]
	global_store_dwordx4 v2, v[204:207], s[16:17] offset:3072 nt
.Lfin_skip_2:
	s_cmp_eq_u32 s27, 0
	s_cbranch_scc1 .Lfin_skip_3
	s_lshl_b32 s16, s23, 13
	s_add_u32 s16, s6, s16
	s_addc_u32 s17, s7, 0
	v_pk_mul_f32 v[208:209], v[240:241], v[208:209] op_sel_hi:[0,1]
	v_pk_mul_f32 v[210:211], v[240:241], v[210:211] op_sel_hi:[0,1]
	v_pk_mul_f32 v[208:209], v[208:209], v[16:17]
	v_pk_mul_f32 v[210:211], v[210:211], v[18:19]
	global_store_dwordx4 v0, v[208:211], s[16:17] nt
	v_pk_mul_f32 v[212:213], v[240:241], v[212:213] op_sel_hi:[0,1]
	v_pk_mul_f32 v[214:215], v[240:241], v[214:215] op_sel_hi:[0,1]
	v_pk_mul_f32 v[212:213], v[212:213], v[20:21]
	v_pk_mul_f32 v[214:215], v[214:215], v[22:23]
	global_store_dwordx4 v0, v[212:215], s[16:17] offset:1024 nt
	v_pk_mul_f32 v[216:217], v[240:241], v[216:217] op_sel_hi:[0,1]
	v_pk_mul_f32 v[218:219], v[240:241], v[218:219] op_sel_hi:[0,1]
	v_pk_mul_f32 v[216:217], v[216:217], v[24:25]
	v_pk_mul_f32 v[218:219], v[218:219], v[26:27]
	global_store_dwordx4 v0, v[216:219], s[16:17] offset:2048 nt
	v_pk_mul_f32 v[220:221], v[240:241], v[220:221] op_sel_hi:[0,1]
	v_pk_mul_f32 v[222:223], v[240:241], v[222:223] op_sel_hi:[0,1]
	v_pk_mul_f32 v[220:221], v[220:221], v[28:29]
	v_pk_mul_f32 v[222:223], v[222:223], v[30:31]
	global_store_dwordx4 v0, v[220:223], s[16:17] offset:3072 nt
	v_pk_mul_f32 v[224:225], v[240:241], v[224:225] op_sel_hi:[0,1]
	v_pk_mul_f32 v[226:227], v[240:241], v[226:227] op_sel_hi:[0,1]
	v_pk_mul_f32 v[224:225], v[224:225], v[32:33]
	v_pk_mul_f32 v[226:227], v[226:227], v[34:35]
	global_store_dwordx4 v2, v[224:227], s[16:17] nt
	v_pk_mul_f32 v[228:229], v[240:241], v[228:229] op_sel_hi:[0,1]
	v_pk_mul_f32 v[230:231], v[240:241], v[230:231] op_sel_hi:[0,1]
	v_pk_mul_f32 v[228:229], v[228:229], v[36:37]
	v_pk_mul_f32 v[230:231], v[230:231], v[38:39]
	global_store_dwordx4 v2, v[228:231], s[16:17] offset:1024 nt
	v_pk_mul_f32 v[232:233], v[240:241], v[232:233] op_sel_hi:[0,1]
	v_pk_mul_f32 v[234:235], v[240:241], v[234:235] op_sel_hi:[0,1]
	v_pk_mul_f32 v[232:233], v[232:233], v[40:41]
	v_pk_mul_f32 v[234:235], v[234:235], v[42:43]
	global_store_dwordx4 v2, v[232:235], s[16:17] offset:2048 nt
	v_pk_mul_f32 v[236:237], v[240:241], v[236:237] op_sel_hi:[0,1]
	v_pk_mul_f32 v[238:239], v[240:241], v[238:239] op_sel_hi:[0,1]
	v_pk_mul_f32 v[236:237], v[236:237], v[44:45]
	v_pk_mul_f32 v[238:239], v[238:239], v[46:47]
	global_store_dwordx4 v2, v[236:239], s[16:17] offset:3072 nt

; __device__ __forceinline__ void sample_assemble(const float* base, const float* XSP, int nsp, int s, float* xr, int lane) {
;     const f32x4* br = (const f32x4*)base + lane; f32x4* o = (f32x4*)xr + lane;
; #pragma unroll
;     for (int j = 0; j < 8; ++j) { f32x4 v = br[64 * j];
;         for (int sp = 0; sp < nsp; ++sp) v += *((const f32x4*)(XSP + ((size_t)sp * NS + s) * DM) + lane + 64 * j);
;         o[64 * j] = v; }
; }
; __global__ void __launch_bounds__(NTHR, 2) fwd_kernel(Args a) {
;     ...
;         if (m >= MP) { sample_assemble(XR + (size_t)m * DM, XSP, 11, m - MP, XR + (size_t)m * DM, lane); rms_row_f32(XR + (size_t)m * DM, final_norm_g, out + O_YS + (size_t)(m - MP) * DM, lane); }
.Lfin_sample_loop:
	s_lshl_b32 s16, s14, 13
	s_add_u32 s18, s8, 0x216e4000
	s_addc_u32 s19, s9, 0
	s_add_u32 s18, s18, s16
	s_addc_u32 s19, s19, 0
	s_add_u32 s20, s8, 0x12700000
	s_addc_u32 s21, s9, 0
	s_add_u32 s20, s20, s16
	s_addc_u32 s21, s21, 0
	v_add_u32_e32 v48, 0x1000, v0
	global_load_dwordx4 v[82:85], v0, s[20:21] nt
	global_load_dwordx4 v[86:89], v0, s[18:19] nt
	s_add_u32 s22, s18, 0x100000
	s_addc_u32 s23, s19, 0
	global_load_dwordx4 v[90:93], v0, s[22:23] nt
	s_add_u32 s22, s18, 0x200000
	s_addc_u32 s23, s19, 0
	global_load_dwordx4 v[94:97], v0, s[22:23] nt
	s_add_u32 s22, s18, 0x300000
	s_addc_u32 s23, s19, 0
	global_load_dwordx4 v[98:101], v0, s[22:23] nt
	s_add_u32 s22, s18, 0x400000
	s_addc_u32 s23, s19, 0
	global_load_dwordx4 v[102:105], v0, s[22:23] nt
	s_add_u32 s22, s18, 0x500000
	s_addc_u32 s23, s19, 0
	global_load_dwordx4 v[106:109], v0, s[22:23] nt
	s_add_u32 s22, s18, 0x600000
	s_addc_u32 s23, s19, 0
	global_load_dwordx4 v[110:113], v0, s[22:23] nt
	s_add_u32 s22, s18, 0x700000
	s_addc_u32 s23, s19, 0
	global_load_dwordx4 v[114:117], v0, s[22:23] nt
	s_add_u32 s22, s18, 0x800000
	s_addc_u32 s23, s19, 0
	global_load_dwordx4 v[118:121], v0, s[22:23] nt
	s_add_u32 s22, s18, 0x900000
	s_addc_u32 s23, s19, 0
	global_load_dwordx4 v[122:125], v0, s[22:23] nt
	s_add_u32 s22, s18, 0xa00000
	s_addc_u32 s23, s19, 0
	global_load_dwordx4 v[126:129], v0, s[22:23] nt
	global_load_dwordx4 v[130:133], v0, s[20:21] offset:1024 nt
	global_load_dwordx4 v[134:137], v0, s[18:19] offset:1024 nt
	s_add_u32 s22, s18, 0x100000
	s_addc_u32 s23, s19, 0
	global_load_dwordx4 v[138:141], v0, s[22:23] offset:1024 nt
	s_add_u32 s22, s18, 0x200000
	s_addc_u32 s23, s19, 0
	global_load_dwordx4 v[142:145], v0, s[22:23] offset:1024 nt
	s_add_u32 s22, s18, 0x300000
	s_addc_u32 s23, s19, 0
	global_load_dwordx4 v[146:149], v0, s[22:23] offset:1024 nt
	s_add_u32 s22, s18, 0x400000
	s_addc_u32 s23, s19, 0
	global_load_dwordx4 v[150:153], v0, s[22:23] offset:1024 nt
	s_add_u32 s22, s18, 0x500000
	s_addc_u32 s23, s19, 0
	global_load_dwordx4 v[154:157], v0, s[22:23] offset:1024 nt
	s_add_u32 s22, s18, 0x600000
	s_addc_u32 s23, s19, 0
	global_load_dwordx4 v[158:161], v0, s[22:23] offset:1024 nt
	s_add_u32 s22, s18, 0x700000
	s_addc_u32 s23, s19, 0
	global_load_dwordx4 v[162:165], v0, s[22:23] offset:1024 nt
	s_add_u32 s22, s18, 0x800000
	s_addc_u32 s23, s19, 0
	global_load_dwordx4 v[166:169], v0, s[22:23] offset:1024 nt
	s_add_u32 s22, s18, 0x900000
	s_addc_u32 s23, s19, 0
	global_load_dwordx4 v[170:173], v0, s[22:23] offset:1024 nt
	s_add_u32 s22, s18, 0xa00000
	s_addc_u32 s23, s19, 0
	global_load_dwordx4 v[174:177], v0, s[22:23] offset:1024 nt
	global_load_dwordx4 v[178:181], v0, s[20:21] offset:2048 nt
	global_load_dwordx4 v[182:185], v0, s[18:19] offset:2048 nt
	s_add_u32 s22, s18, 0x100000
	s_addc_u32 s23, s19, 0
	global_load_dwordx4 v[186:189], v0, s[22:23] offset:2048 nt
	s_add_u32 s22, s18, 0x200000
	s_addc_u32 s23, s19, 0
	global_load_dwordx4 v[190:193], v0, s[22:23] offset:2048 nt
	s_add_u32 s22, s18, 0x300000
	s_addc_u32 s23, s19, 0
	global_load_dwordx4 v[194:197], v0, s[22:23] offset:2048 nt
	s_add_u32 s22, s18, 0x400000
	s_addc_u32 s23, s19, 0
	global_load_dwordx4 v[198:201], v0, s[22:23] offset:2048 nt
	s_add_u32 s22, s18, 0x500000
	s_addc_u32 s23, s19, 0
	global_load_dwordx4 v[202:205], v0, s[22:23] offset:2048 nt
	s_add_u32 s22, s18, 0x600000
	s_addc_u32 s23, s19, 0
	global_load_dwordx4 v[206:209], v0, s[22:23] offset:2048 nt
	s_add_u32 s22, s18, 0x700000
	s_addc_u32 s23, s19, 0
	global_load_dwordx4 v[210:213], v0, s[22:23] offset:2048 nt
	s_add_u32 s22, s18, 0x800000
	s_addc_u32 s23, s19, 0
	global_load_dwordx4 v[214:217], v0, s[22:23] offset:2048 nt
	s_add_u32 s22, s18, 0x900000
	s_addc_u32 s23, s19, 0
	global_load_dwordx4 v[218:221], v0, s[22:23] offset:2048 nt
	s_add_u32 s22, s18, 0xa00000
	s_addc_u32 s23, s19, 0
	global_load_dwordx4 v[222:225], v0, s[22:23] offset:2048 nt
	s_waitcnt vmcnt(24)
	v_pk_add_f32 v[50:51], v[82:83], v[86:87]
	v_pk_add_f32 v[52:53], v[84:85], v[88:89]
	v_pk_add_f32 v[50:51], v[50:51], v[90:91]
	v_pk_add_f32 v[52:53], v[52:53], v[92:93]
	v_pk_add_f32 v[50:51], v[50:51], v[94:95]
	v_pk_add_f32 v[52:53], v[52:53], v[96:97]
	v_pk_add_f32 v[50:51], v[50:51], v[98:99]
	v_pk_add_f32 v[52:53], v[52:53], v[100:101]
	v_pk_add_f32 v[50:51], v[50:51], v[102:103]
	v_pk_add_f32 v[52:53], v[52:53], v[104:105]
	v_pk_add_f32 v[50:51], v[50:51], v[106:107]
	v_pk_add_f32 v[52:53], v[52:53], v[108:109]
	v_pk_add_f32 v[50:51], v[50:51], v[110:111]
	v_pk_add_f32 v[52:53], v[52:53], v[112:113]
	v_pk_add_f32 v[50:51], v[50:51], v[114:115]
	v_pk_add_f32 v[52:53], v[52:53], v[116:117]
	v_pk_add_f32 v[50:51], v[50:51], v[118:119]
	v_pk_add_f32 v[52:53], v[52:53], v[120:121]
	v_pk_add_f32 v[50:51], v[50:51], v[122:123]
	v_pk_add_f32 v[52:53], v[52:53], v[124:125]
	v_pk_add_f32 v[50:51], v[50:51], v[126:127]
	v_pk_add_f32 v[52:53], v[52:53], v[128:129]
	global_store_dwordx4 v0, v[50:53], s[20:21] nt
	global_load_dwordx4 v[82:85], v0, s[20:21] offset:3072 nt
	global_load_dwordx4 v[86:89], v0, s[18:19] offset:3072 nt
	s_add_u32 s22, s18, 0x100000
	s_addc_u32 s23, s19, 0
	global_load_dwordx4 v[90:93], v0, s[22:23] offset:3072 nt
	s_add_u32 s22, s18, 0x200000
	s_addc_u32 s23, s19, 0
	global_load_dwordx4 v[94:97], v0, s[22:23] offset:3072 nt
	s_add_u32 s22, s18, 0x300000
	s_addc_u32 s23, s19, 0
	global_load_dwordx4 v[98:101], v0, s[22:23] offset:3072 nt
	s_add_u32 s22, s18, 0x400000
	s_addc_u32 s23, s19, 0
	global_load_dwordx4 v[102:105], v0, s[22:23] offset:3072 nt
	s_add_u32 s22, s18, 0x500000
	s_addc_u32 s23, s19, 0
	global_load_dwordx4 v[106:109], v0, s[22:23] offset:3072 nt
	s_add_u32 s22, s18, 0x600000
	s_addc_u32 s23, s19, 0
	global_load_dwordx4 v[110:113], v0, s[22:23] offset:3072 nt
	s_add_u32 s22, s18, 0x700000
	s_addc_u32 s23, s19, 0
	global_load_dwordx4 v[114:117], v0, s[22:23] offset:3072 nt
	s_add_u32 s22, s18, 0x800000
	s_addc_u32 s23, s19, 0
	global_load_dwordx4 v[118:121], v0, s[22:23] offset:3072 nt
	s_add_u32 s22, s18, 0x900000
	s_addc_u32 s23, s19, 0
	global_load_dwordx4 v[122:125], v0, s[22:23] offset:3072 nt
	s_add_u32 s22, s18, 0xa00000
	s_addc_u32 s23, s19, 0
	global_load_dwordx4 v[126:129], v0, s[22:23] offset:3072 nt
	s_waitcnt vmcnt(25)
; __device__ __forceinline__ void sample_assemble(const float* base, const float* XSP, int nsp, int s, float* xr, int lane) {
;     const f32x4* br = (const f32x4*)base + lane; f32x4* o = (f32x4*)xr + lane;
; #pragma unroll
;     for (int j = 0; j < 8; ++j) { f32x4 v = br[64 * j];
;         for (int sp = 0; sp < nsp; ++sp) v += *((const f32x4*)(XSP + ((size_t)sp * NS + s) * DM) + lane + 64 * j);
;         o[64 * j] = v; }
; }
	v_pk_add_f32 v[54:55], v[130:131], v[134:135]
	v_pk_add_f32 v[56:57], v[132:133], v[136:137]
	v_pk_add_f32 v[54:55], v[54:55], v[138:139]
	v_pk_add_f32 v[56:57], v[56:57], v[140:141]
	v_pk_add_f32 v[54:55], v[54:55], v[142:143]
	v_pk_add_f32 v[56:57], v[56:57], v[144:145]
	v_pk_add_f32 v[54:55], v[54:55], v[146:147]
	v_pk_add_f32 v[56:57], v[56:57], v[148:149]
	v_pk_add_f32 v[54:55], v[54:55], v[150:151]
	v_pk_add_f32 v[56:57], v[56:57], v[152:153]
	v_pk_add_f32 v[54:55], v[54:55], v[154:155]
	v_pk_add_f32 v[56:57], v[56:57], v[156:157]
	v_pk_add_f32 v[54:55], v[54:55], v[158:159]
	v_pk_add_f32 v[56:57], v[56:57], v[160:161]
	v_pk_add_f32 v[54:55], v[54:55], v[162:163]
	v_pk_add_f32 v[56:57], v[56:57], v[164:165]
	v_pk_add_f32 v[54:55], v[54:55], v[166:167]
	v_pk_add_f32 v[56:57], v[56:57], v[168:169]
	v_pk_add_f32 v[54:55], v[54:55], v[170:171]
	v_pk_add_f32 v[56:57], v[56:57], v[172:173]
	v_pk_add_f32 v[54:55], v[54:55], v[174:175]
	v_pk_add_f32 v[56:57], v[56:57], v[176:177]
	global_store_dwordx4 v0, v[54:57], s[20:21] offset:1024 nt
	global_load_dwordx4 v[130:133], v48, s[20:21] nt
	global_load_dwordx4 v[134:137], v48, s[18:19] nt
	s_add_u32 s22, s18, 0x100000
	s_addc_u32 s23, s19, 0
	global_load_dwordx4 v[138:141], v48, s[22:23] nt
	s_add_u32 s22, s18, 0x200000
	s_addc_u32 s23, s19, 0
	global_load_dwordx4 v[142:145], v48, s[22:23] nt
	s_add_u32 s22, s18, 0x300000
	s_addc_u32 s23, s19, 0
	global_load_dwordx4 v[146:149], v48, s[22:23] nt
	s_add_u32 s22, s18, 0x400000
	s_addc_u32 s23, s19, 0
	global_load_dwordx4 v[150:153], v48, s[22:23] nt
	s_add_u32 s22, s18, 0x500000
	s_addc_u32 s23, s19, 0
	global_load_dwordx4 v[154:157], v48, s[22:23] nt
	s_add_u32 s22, s18, 0x600000
	s_addc_u32 s23, s19, 0
	global_load_dwordx4 v[158:161], v48, s[22:23] nt
	s_add_u32 s22, s18, 0x700000
	s_addc_u32 s23, s19, 0
	global_load_dwordx4 v[162:165], v48, s[22:23] nt
	s_add_u32 s22, s18, 0x800000
	s_addc_u32 s23, s19, 0
	global_load_dwordx4 v[166:169], v48, s[22:23] nt
	s_add_u32 s22, s18, 0x900000
	s_addc_u32 s23, s19, 0
	global_load_dwordx4 v[170:173], v48, s[22:23] nt
	s_add_u32 s22, s18, 0xa00000
	s_addc_u32 s23, s19, 0
	global_load_dwordx4 v[174:177], v48, s[22:23] nt
	s_waitcnt vmcnt(26)
	v_pk_add_f32 v[58:59], v[178:179], v[182:183]
	v_pk_add_f32 v[60:61], v[180:181], v[184:185]
	v_pk_add_f32 v[58:59], v[58:59], v[186:187]
	v_pk_add_f32 v[60:61], v[60:61], v[188:189]
	v_pk_add_f32 v[58:59], v[58:59], v[190:191]
	v_pk_add_f32 v[60:61], v[60:61], v[192:193]
	v_pk_add_f32 v[58:59], v[58:59], v[194:195]
	v_pk_add_f32 v[60:61], v[60:61], v[196:197]
	v_pk_add_f32 v[58:59], v[58:59], v[198:199]
	v_pk_add_f32 v[60:61], v[60:61], v[200:201]
	v_pk_add_f32 v[58:59], v[58:59], v[202:203]
	v_pk_add_f32 v[60:61], v[60:61], v[204:205]
	v_pk_add_f32 v[58:59], v[58:59], v[206:207]
	v_pk_add_f32 v[60:61], v[60:61], v[208:209]
	v_pk_add_f32 v[58:59], v[58:59], v[210:211]
	v_pk_add_f32 v[60:61], v[60:61], v[212:213]
	v_pk_add_f32 v[58:59], v[58:59], v[214:215]
	v_pk_add_f32 v[60:61], v[60:61], v[216:217]
	v_pk_add_f32 v[58:59], v[58:59], v[218:219]
	v_pk_add_f32 v[60:61], v[60:61], v[220:221]
	v_pk_add_f32 v[58:59], v[58:59], v[222:223]
	v_pk_add_f32 v[60:61], v[60:61], v[224:225]
	global_store_dwordx4 v0, v[58:61], s[20:21] offset:2048 nt
	global_load_dwordx4 v[178:181], v48, s[20:21] offset:1024 nt
	global_load_dwordx4 v[182:185], v48, s[18:19] offset:1024 nt
	s_add_u32 s22, s18, 0x100000
	s_addc_u32 s23, s19, 0
	global_load_dwordx4 v[186:189], v48, s[22:23] offset:1024 nt
	s_add_u32 s22, s18, 0x200000
	s_addc_u32 s23, s19, 0
	global_load_dwordx4 v[190:193], v48, s[22:23] offset:1024 nt
	s_add_u32 s22, s18, 0x300000
	s_addc_u32 s23, s19, 0
	global_load_dwordx4 v[194:197], v48, s[22:23] offset:1024 nt
	s_add_u32 s22, s18, 0x400000
	s_addc_u32 s23, s19, 0
	global_load_dwordx4 v[198:201], v48, s[22:23] offset:1024 nt
	s_add_u32 s22, s18, 0x500000
	s_addc_u32 s23, s19, 0
	global_load_dwordx4 v[202:205], v48, s[22:23] offset:1024 nt
	s_add_u32 s22, s18, 0x600000
	s_addc_u32 s23, s19, 0
	global_load_dwordx4 v[206:209], v48, s[22:23] offset:1024 nt
	s_add_u32 s22, s18, 0x700000
	s_addc_u32 s23, s19, 0
	global_load_dwordx4 v[210:213], v48, s[22:23] offset:1024 nt
	s_add_u32 s22, s18, 0x800000
	s_addc_u32 s23, s19, 0
	global_load_dwordx4 v[214:217], v48, s[22:23] offset:1024 nt
	s_add_u32 s22, s18, 0x900000
	s_addc_u32 s23, s19, 0
	global_load_dwordx4 v[218:221], v48, s[22:23] offset:1024 nt
	s_add_u32 s22, s18, 0xa00000
	s_addc_u32 s23, s19, 0
	global_load_dwordx4 v[222:225], v48, s[22:23] offset:1024 nt
	s_waitcnt vmcnt(26)
; __device__ __forceinline__ void sample_assemble(const float* base, const float* XSP, int nsp, int s, float* xr, int lane) {
;     const f32x4* br = (const f32x4*)base + lane; f32x4* o = (f32x4*)xr + lane;
; #pragma unroll
;     for (int j = 0; j < 8; ++j) { f32x4 v = br[64 * j];
;         for (int sp = 0; sp < nsp; ++sp) v += *((const f32x4*)(XSP + ((size_t)sp * NS + s) * DM) + lane + 64 * j);
;         o[64 * j] = v; }
; }
	v_pk_add_f32 v[62:63], v[82:83], v[86:87]
	v_pk_add_f32 v[64:65], v[84:85], v[88:89]
	v_pk_add_f32 v[62:63], v[62:63], v[90:91]
	v_pk_add_f32 v[64:65], v[64:65], v[92:93]
	v_pk_add_f32 v[62:63], v[62:63], v[94:95]
	v_pk_add_f32 v[64:65], v[64:65], v[96:97]
	v_pk_add_f32 v[62:63], v[62:63], v[98:99]
	v_pk_add_f32 v[64:65], v[64:65], v[100:101]
	v_pk_add_f32 v[62:63], v[62:63], v[102:103]
	v_pk_add_f32 v[64:65], v[64:65], v[104:105]
	v_pk_add_f32 v[62:63], v[62:63], v[106:107]
	v_pk_add_f32 v[64:65], v[64:65], v[108:109]
	v_pk_add_f32 v[62:63], v[62:63], v[110:111]
	v_pk_add_f32 v[64:65], v[64:65], v[112:113]
	v_pk_add_f32 v[62:63], v[62:63], v[114:115]
	v_pk_add_f32 v[64:65], v[64:65], v[116:117]
	v_pk_add_f32 v[62:63], v[62:63], v[118:119]
	v_pk_add_f32 v[64:65], v[64:65], v[120:121]
	v_pk_add_f32 v[62:63], v[62:63], v[122:123]
	v_pk_add_f32 v[64:65], v[64:65], v[124:125]
	v_pk_add_f32 v[62:63], v[62:63], v[126:127]
	v_pk_add_f32 v[64:65], v[64:65], v[128:129]
	global_store_dwordx4 v0, v[62:65], s[20:21] offset:3072 nt
	global_load_dwordx4 v[82:85], v48, s[20:21] offset:2048 nt
	global_load_dwordx4 v[86:89], v48, s[18:19] offset:2048 nt
	s_add_u32 s22, s18, 0x100000
	s_addc_u32 s23, s19, 0
	global_load_dwordx4 v[90:93], v48, s[22:23] offset:2048 nt
	s_add_u32 s22, s18, 0x200000
	s_addc_u32 s23, s19, 0
	global_load_dwordx4 v[94:97], v48, s[22:23] offset:2048 nt
	s_add_u32 s22, s18, 0x300000
	s_addc_u32 s23, s19, 0
	global_load_dwordx4 v[98:101], v48, s[22:23] offset:2048 nt
	s_add_u32 s22, s18, 0x400000
	s_addc_u32 s23, s19, 0
	global_load_dwordx4 v[102:105], v48, s[22:23] offset:2048 nt
	s_add_u32 s22, s18, 0x500000
	s_addc_u32 s23, s19, 0
	global_load_dwordx4 v[106:109], v48, s[22:23] offset:2048 nt
	s_add_u32 s22, s18, 0x600000
	s_addc_u32 s23, s19, 0
	global_load_dwordx4 v[110:113], v48, s[22:23] offset:2048 nt
	s_add_u32 s22, s18, 0x700000
	s_addc_u32 s23, s19, 0
	global_load_dwordx4 v[114:117], v48, s[22:23] offset:2048 nt
	s_add_u32 s22, s18, 0x800000
	s_addc_u32 s23, s19, 0
	global_load_dwordx4 v[118:121], v48, s[22:23] offset:2048 nt
	s_add_u32 s22, s18, 0x900000
	s_addc_u32 s23, s19, 0
	global_load_dwordx4 v[122:125], v48, s[22:23] offset:2048 nt
	s_add_u32 s22, s18, 0xa00000
	s_addc_u32 s23, s19, 0
	global_load_dwordx4 v[126:129], v48, s[22:23] offset:2048 nt
	s_waitcnt vmcnt(26)
	v_pk_add_f32 v[66:67], v[130:131], v[134:135]
	v_pk_add_f32 v[68:69], v[132:133], v[136:137]
	v_pk_add_f32 v[66:67], v[66:67], v[138:139]
	v_pk_add_f32 v[68:69], v[68:69], v[140:141]
	v_pk_add_f32 v[66:67], v[66:67], v[142:143]
	v_pk_add_f32 v[68:69], v[68:69], v[144:145]
	v_pk_add_f32 v[66:67], v[66:67], v[146:147]
	v_pk_add_f32 v[68:69], v[68:69], v[148:149]
	v_pk_add_f32 v[66:67], v[66:67], v[150:151]
	v_pk_add_f32 v[68:69], v[68:69], v[152:153]
	v_pk_add_f32 v[66:67], v[66:67], v[154:155]
	v_pk_add_f32 v[68:69], v[68:69], v[156:157]
	v_pk_add_f32 v[66:67], v[66:67], v[158:159]
	v_pk_add_f32 v[68:69], v[68:69], v[160:161]
	v_pk_add_f32 v[66:67], v[66:67], v[162:163]
	v_pk_add_f32 v[68:69], v[68:69], v[164:165]
	v_pk_add_f32 v[66:67], v[66:67], v[166:167]
	v_pk_add_f32 v[68:69], v[68:69], v[168:169]
	v_pk_add_f32 v[66:67], v[66:67], v[170:171]
	v_pk_add_f32 v[68:69], v[68:69], v[172:173]
	v_pk_add_f32 v[66:67], v[66:67], v[174:175]
	v_pk_add_f32 v[68:69], v[68:69], v[176:177]
	global_store_dwordx4 v48, v[66:69], s[20:21] nt
	global_load_dwordx4 v[130:133], v48, s[20:21] offset:3072 nt
	global_load_dwordx4 v[134:137], v48, s[18:19] offset:3072 nt
	s_add_u32 s22, s18, 0x100000
	s_addc_u32 s23, s19, 0
	global_load_dwordx4 v[138:141], v48, s[22:23] offset:3072 nt
	s_add_u32 s22, s18, 0x200000
	s_addc_u32 s23, s19, 0
	global_load_dwordx4 v[142:145], v48, s[22:23] offset:3072 nt
	s_add_u32 s22, s18, 0x300000
	s_addc_u32 s23, s19, 0
	global_load_dwordx4 v[146:149], v48, s[22:23] offset:3072 nt
	s_add_u32 s22, s18, 0x400000
	s_addc_u32 s23, s19, 0
	global_load_dwordx4 v[150:153], v48, s[22:23] offset:3072 nt
	s_add_u32 s22, s18, 0x500000
	s_addc_u32 s23, s19, 0
	global_load_dwordx4 v[154:157], v48, s[22:23] offset:3072 nt
	s_add_u32 s22, s18, 0x600000
	s_addc_u32 s23, s19, 0
	global_load_dwordx4 v[158:161], v48, s[22:23] offset:3072 nt
	s_add_u32 s22, s18, 0x700000
	s_addc_u32 s23, s19, 0
	global_load_dwordx4 v[162:165], v48, s[22:23] offset:3072 nt
	s_add_u32 s22, s18, 0x800000
	s_addc_u32 s23, s19, 0
	global_load_dwordx4 v[166:169], v48, s[22:23] offset:3072 nt
	s_add_u32 s22, s18, 0x900000
	s_addc_u32 s23, s19, 0
	global_load_dwordx4 v[170:173], v48, s[22:23] offset:3072 nt
	s_add_u32 s22, s18, 0xa00000
	s_addc_u32 s23, s19, 0
	global_load_dwordx4 v[174:177], v48, s[22:23] offset:3072 nt
	s_waitcnt vmcnt(26)
	v_pk_add_f32 v[70:71], v[178:179], v[182:183]
	v_pk_add_f32 v[72:73], v[180:181], v[184:185]
	v_pk_add_f32 v[70:71], v[70:71], v[186:187]
	v_pk_add_f32 v[72:73], v[72:73], v[188:189]
	v_pk_add_f32 v[70:71], v[70:71], v[190:191]
	v_pk_add_f32 v[72:73], v[72:73], v[192:193]
	v_pk_add_f32 v[70:71], v[70:71], v[194:195]
	v_pk_add_f32 v[72:73], v[72:73], v[196:197]
	v_pk_add_f32 v[70:71], v[70:71], v[198:199]
	v_pk_add_f32 v[72:73], v[72:73], v[200:201]
	v_pk_add_f32 v[70:71], v[70:71], v[202:203]
	v_pk_add_f32 v[72:73], v[72:73], v[204:205]
	v_pk_add_f32 v[70:71], v[70:71], v[206:207]
	v_pk_add_f32 v[72:73], v[72:73], v[208:209]
	v_pk_add_f32 v[70:71], v[70:71], v[210:211]
	v_pk_add_f32 v[72:73], v[72:73], v[212:213]
	v_pk_add_f32 v[70:71], v[70:71], v[214:215]
	v_pk_add_f32 v[72:73], v[72:73], v[216:217]
	v_pk_add_f32 v[70:71], v[70:71], v[218:219]
	v_pk_add_f32 v[72:73], v[72:73], v[220:221]
	v_pk_add_f32 v[70:71], v[70:71], v[222:223]
	v_pk_add_f32 v[72:73], v[72:73], v[224:225]
	global_store_dwordx4 v48, v[70:73], s[20:21] offset:1024 nt
	s_waitcnt vmcnt(14)
; __device__ __forceinline__ void rms_row_f32(const float* xrow, const float* g, float* orow, int lane) {
;     const f32x4* xr = (const f32x4*)xrow + lane; f32x4 v[8]; float s = 0.f;
; #pragma unroll
;     for (int j = 0; j < 8; ++j) { v[j] = xr[64 * j]; s += (v[j].x * v[j].x + v[j].y * v[j].y) + (v[j].z * v[j].z + v[j].w * v[j].w); }
;     const float rstd = rsqrtf(wave_sum(s) * (1.f / DM) + EPS);
;     const f32x4* gr = (const f32x4*)g + lane; f32x4* o = (f32x4*)orow + lane;
; #pragma unroll
;     for (int j = 0; j < 8; ++j) { const f32x4 gg = gr[64 * j]; o[64 * j] = v[j] * rstd * gg; }
; }
; __device__ __forceinline__ void sample_assemble(const float* base, const float* XSP, int nsp, int s, float* xr, int lane) {
;     const f32x4* br = (const f32x4*)base + lane; f32x4* o = (f32x4*)xr + lane;
; #pragma unroll
;     for (int j = 0; j < 8; ++j) { f32x4 v = br[64 * j];
;         for (int sp = 0; sp < nsp; ++sp) v += *((const f32x4*)(XSP + ((size_t)sp * NS + s) * DM) + lane + 64 * j);
;         o[64 * j] = v; }
; }
	v_pk_add_f32 v[74:75], v[82:83], v[86:87]
	v_pk_add_f32 v[76:77], v[84:85], v[88:89]
	v_pk_add_f32 v[74:75], v[74:75], v[90:91]
	v_pk_add_f32 v[76:77], v[76:77], v[92:93]
	v_pk_add_f32 v[74:75], v[74:75], v[94:95]
	v_pk_add_f32 v[76:77], v[76:77], v[96:97]
	v_pk_add_f32 v[74:75], v[74:75], v[98:99]
	v_pk_add_f32 v[76:77], v[76:77], v[100:101]
	v_pk_add_f32 v[74:75], v[74:75], v[102:103]
	v_pk_add_f32 v[76:77], v[76:77], v[104:105]
	v_pk_add_f32 v[74:75], v[74:75], v[106:107]
	v_pk_add_f32 v[76:77], v[76:77], v[108:109]
	v_pk_add_f32 v[74:75], v[74:75], v[110:111]
	v_pk_add_f32 v[76:77], v[76:77], v[112:113]
	v_pk_add_f32 v[74:75], v[74:75], v[114:115]
	v_pk_add_f32 v[76:77], v[76:77], v[116:117]
	v_pk_add_f32 v[74:75], v[74:75], v[118:119]
	v_pk_add_f32 v[76:77], v[76:77], v[120:121]
	v_pk_add_f32 v[74:75], v[74:75], v[122:123]
	v_pk_add_f32 v[76:77], v[76:77], v[124:125]
	v_pk_add_f32 v[74:75], v[74:75], v[126:127]
	v_pk_add_f32 v[76:77], v[76:77], v[128:129]
	global_store_dwordx4 v48, v[74:77], s[20:21] offset:2048 nt
	s_waitcnt vmcnt(2)
	v_pk_add_f32 v[78:79], v[130:131], v[134:135]
	v_pk_add_f32 v[80:81], v[132:133], v[136:137]
	v_pk_add_f32 v[78:79], v[78:79], v[138:139]
	v_pk_add_f32 v[80:81], v[80:81], v[140:141]
	v_pk_add_f32 v[78:79], v[78:79], v[142:143]
	v_pk_add_f32 v[80:81], v[80:81], v[144:145]
	v_pk_add_f32 v[78:79], v[78:79], v[146:147]
	v_pk_add_f32 v[80:81], v[80:81], v[148:149]
	v_pk_add_f32 v[78:79], v[78:79], v[150:151]
	v_pk_add_f32 v[80:81], v[80:81], v[152:153]
	v_pk_add_f32 v[78:79], v[78:79], v[154:155]
	v_pk_add_f32 v[80:81], v[80:81], v[156:157]
	v_pk_add_f32 v[78:79], v[78:79], v[158:159]
	v_pk_add_f32 v[80:81], v[80:81], v[160:161]
	v_pk_add_f32 v[78:79], v[78:79], v[162:163]
	v_pk_add_f32 v[80:81], v[80:81], v[164:165]
	v_pk_add_f32 v[78:79], v[78:79], v[166:167]
	v_pk_add_f32 v[80:81], v[80:81], v[168:169]
	v_pk_add_f32 v[78:79], v[78:79], v[170:171]
	v_pk_add_f32 v[80:81], v[80:81], v[172:173]
	v_pk_add_f32 v[78:79], v[78:79], v[174:175]
	v_pk_add_f32 v[80:81], v[80:81], v[176:177]
	global_store_dwordx4 v48, v[78:81], s[20:21] offset:3072 nt
	v_mul_f32_e32 v226, v51, v51
	v_mul_f32_e32 v228, v53, v53
	v_fmac_f32_e32 v226, v50, v50
	v_fmac_f32_e32 v228, v52, v52
	v_add_f32_e32 v226, v226, v228
	v_mul_f32_e32 v49, v55, v55
	v_mul_f32_e32 v228, v57, v57
	v_fmac_f32_e32 v49, v54, v54
	v_fmac_f32_e32 v228, v56, v56
	v_add_f32_e32 v49, v49, v228
	v_add_f32_e32 v226, v226, v49
	v_mul_f32_e32 v49, v59, v59
	v_mul_f32_e32 v228, v61, v61
	v_fmac_f32_e32 v49, v58, v58
	v_fmac_f32_e32 v228, v60, v60
	v_add_f32_e32 v49, v49, v228
	v_add_f32_e32 v226, v226, v49
	v_mul_f32_e32 v49, v63, v63
	v_mul_f32_e32 v228, v65, v65
	v_fmac_f32_e32 v49, v62, v62
	v_fmac_f32_e32 v228, v64, v64
	v_add_f32_e32 v49, v49, v228
	v_add_f32_e32 v226, v226, v49
	v_mul_f32_e32 v49, v67, v67
	v_mul_f32_e32 v228, v69, v69
	v_fmac_f32_e32 v49, v66, v66
	v_fmac_f32_e32 v228, v68, v68
	v_add_f32_e32 v49, v49, v228
	v_add_f32_e32 v226, v226, v49
	v_mul_f32_e32 v49, v71, v71
	v_mul_f32_e32 v228, v73, v73
	v_fmac_f32_e32 v49, v70, v70
	v_fmac_f32_e32 v228, v72, v72
	v_add_f32_e32 v49, v49, v228
	v_add_f32_e32 v226, v226, v49
	v_mul_f32_e32 v49, v75, v75
	v_mul_f32_e32 v228, v77, v77
	v_fmac_f32_e32 v49, v74, v74
	v_fmac_f32_e32 v228, v76, v76
	v_add_f32_e32 v49, v49, v228
	v_add_f32_e32 v226, v226, v49
	v_mul_f32_e32 v49, v79, v79
	v_mul_f32_e32 v228, v81, v81
	v_fmac_f32_e32 v49, v78, v78
	v_fmac_f32_e32 v228, v80, v80
	v_add_f32_e32 v49, v49, v228
	v_add_f32_e32 v226, v226, v49
	ds_bpermute_b32 v229, v3, v226
	s_waitcnt lgkmcnt(0)
	v_add_f32_e32 v226, v226, v229
	ds_bpermute_b32 v229, v4, v226
	s_waitcnt lgkmcnt(0)
	v_add_f32_e32 v226, v226, v229
	ds_bpermute_b32 v229, v5, v226
	s_waitcnt lgkmcnt(0)
	v_add_f32_e32 v226, v226, v229
	ds_bpermute_b32 v229, v6, v226
	s_waitcnt lgkmcnt(0)
	v_add_f32_e32 v226, v226, v229
	ds_bpermute_b32 v229, v7, v226
	s_waitcnt lgkmcnt(0)
	v_add_f32_e32 v226, v226, v229
	ds_bpermute_b32 v229, v8, v226
	s_waitcnt lgkmcnt(0)
	v_add_f32_e32 v226, v226, v229
	v_fmamk_f32 v226, v226, 0x3a000000, v9
	v_mul_f32_e32 v49, 0x4b800000, v226
	v_cmp_gt_f32_e32 vcc, s12, v226
	s_nop 1
	v_cndmask_b32_e32 v226, v226, v49, vcc
	v_rsq_f32_e32 v226, v226
	s_nop 0
	v_mul_f32_e32 v49, 0x45800000, v226
	v_cndmask_b32_e32 v226, v226, v49, vcc
	s_lshl_b32 s16, s14, 13
	s_add_u32 s16, s16, 0x4000000
	s_add_u32 s16, s6, s16
	s_addc_u32 s17, s7, 0
	v_pk_mul_f32 v[50:51], v[226:227], v[50:51] op_sel_hi:[0,1]
	v_pk_mul_f32 v[52:53], v[226:227], v[52:53] op_sel_hi:[0,1]
	v_pk_mul_f32 v[50:51], v[50:51], v[16:17]
	v_pk_mul_f32 v[52:53], v[52:53], v[18:19]
	global_store_dwordx4 v0, v[50:53], s[16:17] nt
	v_pk_mul_f32 v[54:55], v[226:227], v[54:55] op_sel_hi:[0,1]
	v_pk_mul_f32 v[56:57], v[226:227], v[56:57] op_sel_hi:[0,1]
	v_pk_mul_f32 v[54:55], v[54:55], v[20:21]
	v_pk_mul_f32 v[56:57], v[56:57], v[22:23]
	global_store_dwordx4 v0, v[54:57], s[16:17] offset:1024 nt
	v_pk_mul_f32 v[58:59], v[226:227], v[58:59] op_sel_hi:[0,1]
	v_pk_mul_f32 v[60:61], v[226:227], v[60:61] op_sel_hi:[0,1]
	v_pk_mul_f32 v[58:59], v[58:59], v[24:25]
	v_pk_mul_f32 v[60:61], v[60:61], v[26:27]
	global_store_dwordx4 v0, v[58:61], s[16:17] offset:2048 nt
	v_pk_mul_f32 v[62:63], v[226:227], v[62:63] op_sel_hi:[0,1]
	v_pk_mul_f32 v[64:65], v[226:227], v[64:65] op_sel_hi:[0,1]
	v_pk_mul_f32 v[62:63], v[62:63], v[28:29]
	v_pk_mul_f32 v[64:65], v[64:65], v[30:31]
	global_store_dwordx4 v0, v[62:65], s[16:17] offset:3072 nt
	v_pk_mul_f32 v[66:67], v[226:227], v[66:67] op_sel_hi:[0,1]
	v_pk_mul_f32 v[68:69], v[226:227], v[68:69] op_sel_hi:[0,1]
	v_pk_mul_f32 v[66:67], v[66:67], v[32:33]
	v_pk_mul_f32 v[68:69], v[68:69], v[34:35]
	global_store_dwordx4 v2, v[66:69], s[16:17] nt
	v_pk_mul_f32 v[70:71], v[226:227], v[70:71] op_sel_hi:[0,1]
	v_pk_mul_f32 v[72:73], v[226:227], v[72:73] op_sel_hi:[0,1]
	v_pk_mul_f32 v[70:71], v[70:71], v[36:37]
	v_pk_mul_f32 v[72:73], v[72:73], v[38:39]
	global_store_dwordx4 v2, v[70:73], s[16:17] offset:1024 nt
	v_pk_mul_f32 v[74:75], v[226:227], v[74:75] op_sel_hi:[0,1]
	v_pk_mul_f32 v[76:77], v[226:227], v[76:77] op_sel_hi:[0,1]
	v_pk_mul_f32 v[74:75], v[74:75], v[40:41]
	v_pk_mul_f32 v[76:77], v[76:77], v[42:43]
	global_store_dwordx4 v2, v[74:77], s[16:17] offset:2048 nt
	v_pk_mul_f32 v[78:79], v[226:227], v[78:79] op_sel_hi:[0,1]
	v_pk_mul_f32 v[80:81], v[226:227], v[80:81] op_sel_hi:[0,1]
	v_pk_mul_f32 v[78:79], v[78:79], v[44:45]
	v_pk_mul_f32 v[80:81], v[80:81], v[46:47]
	global_store_dwordx4 v2, v[78:81], s[16:17] offset:3072 nt
	s_add_i32 s14, s14, s96
	s_cmp_lt_u32 s14, 0x80
	s_cbranch_scc1 .Lfin_sample_loop
